# P1->P2 seam deferred behind b_unit: early flag after last tile K-loop (tiles<=6 retired) gates b_unit, full XCC wait moved before a_unit
# speedup vs baseline: 1.0064x; 1.0064x over previous
; #define PG8_STAGE(bufoff, gbase, voff) do { _Pragma("unroll") for (int _i = 0; _i < 2; ++_i) \
;         __builtin_amdgcn_global_load_lds((const GAS unsigned*)((const char*)(gbase) + (voff)[_i]), (LAS unsigned*)(lds + (bufoff) + ldsw + _i * 8192), 16, 0, 0); } while (0)
; #define PG8_LDA(dst, b, h) do { _Pragma("unroll") for (int m = 0; m < 4; ++m) _Pragma("unroll") for (int k = 0; k < 2; ++k) dst[m][k] = *(const LAS bf16x8*)(lds + PG8_SA(b, h) + aoff + m * 2048 + k * 1024); } while (0)
; #define PG8_LDB(dst, b, h) do { _Pragma("unroll") for (int n = 0; n < 2; ++n) _Pragma("unroll") for (int k = 0; k < 2; ++k) dst[n][k] = *(const LAS bf16x8*)(lds + PG8_SB(b, h) + boff + n * 2048 + k * 1024); } while (0)
; #define PG8_MMA(ai, bj, At, Bt) do { __builtin_amdgcn_s_setprio(1); _Pragma("unroll") for (int m = 0; m < 4; ++m) _Pragma("unroll") for (int n = 0; n < 2; ++n) _Pragma("unroll") for (int k = 0; k < 2; ++k) \
;         acc[ai][bj][m][n] = __builtin_amdgcn_mfma_f32_16x16x32_bf16(Bt[n][k], At[m][k], acc[ai][bj][m][n], 0, 0, 0); __builtin_amdgcn_s_setprio(0); } while (0)
; #define PG8_WAIT_L(n) asm volatile("s_waitcnt lgkmcnt(" #n ")" ::: "memory")
; #define PG8_BAR __builtin_amdgcn_s_barrier()
; #define PG8_SCHED __builtin_amdgcn_sched_barrier(0)
; template <class Prog, bool ALIGN_EPI, bool NHALF = false, bool PITCHED = false, bool SLACK = false>
; __device__ __forceinline__ void gemm_phase(LAS unsigned char* lds, const int pitch, Prog& P, const int wave_, unsigned long long& t_k, unsigned long long& t_e) {
;     ...
;             PG8_LDB(B0, 0, 0); PG8_LDB(B1, 0, 1); PG8_SCHED; PG8_LDA(At, 0, 0); if (!(SLACK && SLACK_PRE && fst)) PG8_STAGE(PG8_SA(1, 1), a1 + hstep, voffA);
;             PG8_WAIT_F; PG8_WAIT_L(0); PG8_BAR; PG8_MMA(0, 0, At, B0); PG8_MMA(0, 1, At, B1); PG8_BAR; PG8_SCHED;
;             PG8_LDA(At, 0, 1); PG8_STAGE(PG8_SB(0, 0), b2, voffB2); PG8_STAGE(PG8_SB(0, 1), b2 + hstep2, voffB2); PG8_STAGE(PG8_SA(0, 0), a2, voffA2);
;             PG8_WAIT_F; PG8_WAIT_L(0); PG8_BAR; PG8_MMA(1, 0, At, B0); PG8_MMA(1, 1, At, B1); PG8_BAR; PG8_SCHED;
.Lwf3:
	s_waitcnt lgkmcnt(0)
	s_barrier
	s_setprio 1
	s_waitcnt lgkmcnt(0)
	v_mfma_f32_16x16x32_bf16 v[60:63], v[132:135], v[174:177], v[60:63]
	v_mfma_f32_16x16x32_bf16 v[56:59], v[140:143], v[174:177], v[56:59]
	v_mfma_f32_16x16x32_bf16 v[44:47], v[132:135], v[182:185], v[44:47]
	v_mfma_f32_16x16x32_bf16 v[40:43], v[140:143], v[182:185], v[40:43]
	v_mfma_f32_16x16x32_bf16 v[28:31], v[132:135], v[196:199], v[28:31]
	v_mfma_f32_16x16x32_bf16 v[24:27], v[140:143], v[196:199], v[24:27]
	v_mfma_f32_16x16x32_bf16 v[12:15], v[132:135], v[204:207], v[12:15]
	v_mfma_f32_16x16x32_bf16 v[8:11], v[140:143], v[204:207], v[8:11]
	v_mfma_f32_16x16x32_bf16 v[60:63], v[136:139], v[178:181], v[60:63]
	v_mfma_f32_16x16x32_bf16 v[56:59], v[144:147], v[178:181], v[56:59]
	v_mfma_f32_16x16x32_bf16 v[44:47], v[136:139], v[186:189], v[44:47]
	v_mfma_f32_16x16x32_bf16 v[40:43], v[144:147], v[186:189], v[40:43]
	v_mfma_f32_16x16x32_bf16 v[28:31], v[136:139], v[200:203], v[28:31]
	v_mfma_f32_16x16x32_bf16 v[24:27], v[144:147], v[200:203], v[24:27]
	v_mfma_f32_16x16x32_bf16 v[12:15], v[136:139], v[208:211], v[12:15]
	v_mfma_f32_16x16x32_bf16 v[8:11], v[144:147], v[208:211], v[8:11]
	s_setprio 0
	s_setprio 1
	v_mfma_f32_16x16x32_bf16 v[52:55], v[148:151], v[174:177], v[52:55]
	v_mfma_f32_16x16x32_bf16 v[48:51], v[166:169], v[174:177], v[48:51]
	v_mfma_f32_16x16x32_bf16 v[36:39], v[148:151], v[182:185], v[36:39]
	v_mfma_f32_16x16x32_bf16 v[32:35], v[166:169], v[182:185], v[32:35]
	v_mfma_f32_16x16x32_bf16 v[20:23], v[148:151], v[196:199], v[20:23]
	v_mfma_f32_16x16x32_bf16 v[16:19], v[166:169], v[196:199], v[16:19]
	v_mfma_f32_16x16x32_bf16 v[4:7], v[148:151], v[204:207], v[4:7]
	v_mfma_f32_16x16x32_bf16 v[0:3], v[166:169], v[204:207], v[0:3]
	v_mfma_f32_16x16x32_bf16 v[52:55], v[162:165], v[178:181], v[52:55]
	v_mfma_f32_16x16x32_bf16 v[48:51], v[170:173], v[178:181], v[48:51]
	v_mfma_f32_16x16x32_bf16 v[36:39], v[162:165], v[186:189], v[36:39]
	v_mfma_f32_16x16x32_bf16 v[32:35], v[170:173], v[186:189], v[32:35]
	v_mfma_f32_16x16x32_bf16 v[20:23], v[162:165], v[200:203], v[20:23]
	v_mfma_f32_16x16x32_bf16 v[16:19], v[170:173], v[200:203], v[16:19]
	v_mfma_f32_16x16x32_bf16 v[4:7], v[162:165], v[208:211], v[4:7]
	v_mfma_f32_16x16x32_bf16 v[0:3], v[170:173], v[208:211], v[0:3]
	s_setprio 0
	s_barrier
	ds_read_b128 v[132:135], v130
	ds_read_b128 v[136:139], v130 offset:1024
	ds_read_b128 v[140:143], v130 offset:2048
	ds_read_b128 v[144:147], v130 offset:3072
	ds_read_b128 v[148:151], v131
	ds_read_b128 v[162:165], v131 offset:1024
	ds_read_b128 v[166:169], v131 offset:2048
	ds_read_b128 v[170:173], v131 offset:3072
	s_add_u32 s34, s50, 0x40000
	s_addc_u32 s35, s51, 0
	s_mov_b32 m0, s62
	v_lshl_add_u64 v[216:217], s[34:35], 0, v[152:153]
	ds_read_b128 v[174:177], v252 offset:32768
	ds_read_b128 v[178:181], v252 offset:33792
	ds_read_b128 v[182:185], v252 offset:34816
	ds_read_b128 v[186:189], v252 offset:35840
	ds_read_b128 v[196:199], v252 offset:36864
	ds_read_b128 v[200:203], v252 offset:37888
	ds_read_b128 v[204:207], v252 offset:38912
	ds_read_b128 v[208:211], v252 offset:39936
	global_load_lds_dwordx4 v[216:217], off
	v_lshl_add_u64 v[216:217], s[34:35], 0, v[154:155]
	s_mov_b32 m0, s63
	s_nop 0
	global_load_lds_dwordx4 v[216:217], off
	s_waitcnt vmcnt(8)
	s_waitcnt lgkmcnt(0)
	s_barrier
	s_setprio 1
	s_waitcnt lgkmcnt(0)
	v_mfma_f32_16x16x32_bf16 v[124:127], v[132:135], v[174:177], v[124:127]
	v_mfma_f32_16x16x32_bf16 v[120:123], v[140:143], v[174:177], v[120:123]
	v_mfma_f32_16x16x32_bf16 v[108:111], v[132:135], v[182:185], v[108:111]
	v_mfma_f32_16x16x32_bf16 v[104:107], v[140:143], v[182:185], v[104:107]
	v_mfma_f32_16x16x32_bf16 v[92:95], v[132:135], v[196:199], v[92:95]
	v_mfma_f32_16x16x32_bf16 v[88:91], v[140:143], v[196:199], v[88:91]
	v_mfma_f32_16x16x32_bf16 v[76:79], v[132:135], v[204:207], v[76:79]
	v_mfma_f32_16x16x32_bf16 v[72:75], v[140:143], v[204:207], v[72:75]
	v_mfma_f32_16x16x32_bf16 v[124:127], v[136:139], v[178:181], v[124:127]
	v_mfma_f32_16x16x32_bf16 v[120:123], v[144:147], v[178:181], v[120:123]
	v_mfma_f32_16x16x32_bf16 v[108:111], v[136:139], v[186:189], v[108:111]
	v_mfma_f32_16x16x32_bf16 v[104:107], v[144:147], v[186:189], v[104:107]
	v_mfma_f32_16x16x32_bf16 v[92:95], v[136:139], v[200:203], v[92:95]
	v_mfma_f32_16x16x32_bf16 v[88:91], v[144:147], v[200:203], v[88:91]
	v_mfma_f32_16x16x32_bf16 v[76:79], v[136:139], v[208:211], v[76:79]
	v_mfma_f32_16x16x32_bf16 v[72:75], v[144:147], v[208:211], v[72:75]
	s_setprio 0
	s_setprio 1
	v_mfma_f32_16x16x32_bf16 v[116:119], v[148:151], v[174:177], v[116:119]
	v_mfma_f32_16x16x32_bf16 v[112:115], v[166:169], v[174:177], v[112:115]
	v_mfma_f32_16x16x32_bf16 v[100:103], v[148:151], v[182:185], v[100:103]
	v_mfma_f32_16x16x32_bf16 v[96:99], v[166:169], v[182:185], v[96:99]
	v_mfma_f32_16x16x32_bf16 v[84:87], v[148:151], v[196:199], v[84:87]
	v_mfma_f32_16x16x32_bf16 v[80:83], v[166:169], v[196:199], v[80:83]
	v_mfma_f32_16x16x32_bf16 v[68:71], v[148:151], v[204:207], v[68:71]
	v_mfma_f32_16x16x32_bf16 v[64:67], v[166:169], v[204:207], v[64:67]
	v_mfma_f32_16x16x32_bf16 v[116:119], v[162:165], v[178:181], v[116:119]
	v_mfma_f32_16x16x32_bf16 v[112:115], v[170:173], v[178:181], v[112:115]
	v_mfma_f32_16x16x32_bf16 v[100:103], v[162:165], v[186:189], v[100:103]
	v_mfma_f32_16x16x32_bf16 v[96:99], v[170:173], v[186:189], v[96:99]
	v_mfma_f32_16x16x32_bf16 v[84:87], v[162:165], v[200:203], v[84:87]
	v_mfma_f32_16x16x32_bf16 v[80:83], v[170:173], v[200:203], v[80:83]
	v_mfma_f32_16x16x32_bf16 v[68:71], v[162:165], v[208:211], v[68:71]
	v_mfma_f32_16x16x32_bf16 v[64:67], v[170:173], v[208:211], v[64:67]
	s_setprio 0
	s_barrier
; #define PG8_STAGE(bufoff, gbase, voff) do { _Pragma("unroll") for (int _i = 0; _i < 2; ++_i) \
;         __builtin_amdgcn_global_load_lds((const GAS unsigned*)((const char*)(gbase) + (voff)[_i]), (LAS unsigned*)(lds + (bufoff) + ldsw + _i * 8192), 16, 0, 0); } while (0)
; #define PG8_LDA(dst, b, h) do { _Pragma("unroll") for (int m = 0; m < 4; ++m) _Pragma("unroll") for (int k = 0; k < 2; ++k) dst[m][k] = *(const LAS bf16x8*)(lds + PG8_SA(b, h) + aoff + m * 2048 + k * 1024); } while (0)
; #define PG8_LDB(dst, b, h) do { _Pragma("unroll") for (int n = 0; n < 2; ++n) _Pragma("unroll") for (int k = 0; k < 2; ++k) dst[n][k] = *(const LAS bf16x8*)(lds + PG8_SB(b, h) + boff + n * 2048 + k * 1024); } while (0)
; #define PG8_MMA(ai, bj, At, Bt) do { __builtin_amdgcn_s_setprio(1); _Pragma("unroll") for (int m = 0; m < 4; ++m) _Pragma("unroll") for (int n = 0; n < 2; ++n) _Pragma("unroll") for (int k = 0; k < 2; ++k) \
;         acc[ai][bj][m][n] = __builtin_amdgcn_mfma_f32_16x16x32_bf16(Bt[n][k], At[m][k], acc[ai][bj][m][n], 0, 0, 0); __builtin_amdgcn_s_setprio(0); } while (0)
; #define PG8_WAIT_V(n) asm volatile("s_waitcnt vmcnt(" #n ")" ::: "memory")
; #define PG8_WAIT_L(n) asm volatile("s_waitcnt lgkmcnt(" #n ")" ::: "memory")
; #define PG8_BAR __builtin_amdgcn_s_barrier()
; #define PG8_SCHED __builtin_amdgcn_sched_barrier(0)
; template <class Prog, bool ALIGN_EPI, bool NHALF = false, bool PITCHED = false, bool SLACK = false>
; __device__ __forceinline__ void gemm_phase(LAS unsigned char* lds, const int pitch, Prog& P, const int wave_, unsigned long long& t_k, unsigned long long& t_e) {
;     ...
;             PG8_LDB(B0, 1, 0); PG8_LDB(B1, 1, 1); PG8_SCHED; PG8_LDA(At, 1, 0); PG8_STAGE(PG8_SA(0, 1), a2 + hstep2, voffA2);
;             if (SLACK_PRE) PG8_WAIT_F; else PG8_WAIT_V(8); PG8_WAIT_L(0); PG8_BAR; PG8_MMA(0, 0, At, B0); PG8_MMA(0, 1, At, B1); PG8_BAR; PG8_SCHED;
;             PG8_LDA(At, 1, 1); PG8_STAGE(PG8_SB(1, 0), b3, voffB2); PG8_STAGE(PG8_SB(1, 1), b3 + hstep2, voffB2); PG8_STAGE(PG8_SA(1, 0), a3, voffA2);
;             PG8_WAIT_V(8); PG8_WAIT_L(0); PG8_BAR; PG8_MMA(1, 0, At, B0); PG8_MMA(1, 1, At, B1); PG8_BAR; PG8_SCHED;
;             }
;         }
;         if constexpr (SLACK) { if (SLACK_PRE && has_next) PG8_STAGE(PG8_SA(1, 1), nA + kstep + hstep, voffA); }
	s_mov_b32 m0, s16
	v_lshl_add_u64 v[190:191], v[190:191], 0, s[12:13]
	s_add_u32 s34, s48, 0x40080
	ds_read_b128 v[174:177], v252 offset:49152
	ds_read_b128 v[178:181], v252 offset:50176
	ds_read_b128 v[182:185], v252 offset:51200
	ds_read_b128 v[186:189], v252 offset:52224
	ds_read_b128 v[196:199], v252 offset:53248
	ds_read_b128 v[200:203], v252 offset:54272
	ds_read_b128 v[204:207], v252 offset:55296
	ds_read_b128 v[208:211], v252 offset:56320
	global_load_lds_dwordx4 v[190:191], off
	v_lshl_add_u64 v[190:191], v[194:195], 0, s[12:13]
	s_mov_b32 m0, s17
	s_addc_u32 s35, s49, 0
	global_load_lds_dwordx4 v[190:191], off
	v_lshl_add_u64 v[190:191], s[34:35], 0, v[192:193]
	s_mov_b32 m0, s18
	s_nop 0
	global_load_lds_dwordx4 v[190:191], off
	v_lshl_add_u64 v[190:191], s[34:35], 0, v[156:157]
	s_mov_b32 m0, s19
	s_nop 0
	global_load_lds_dwordx4 v[190:191], off
	v_lshl_add_u64 v[190:191], v[212:213], 0, s[12:13]
	s_mov_b32 m0, s81
	s_nop 0
	global_load_lds_dwordx4 v[190:191], off
	v_lshl_add_u64 v[190:191], v[214:215], 0, s[12:13]
	s_mov_b32 m0, s82
	s_nop 0
	global_load_lds_dwordx4 v[190:191], off
	s_waitcnt vmcnt(8)
	s_waitcnt lgkmcnt(0)
	s_barrier
	s_setprio 1
	s_waitcnt lgkmcnt(0)
	v_mfma_f32_16x16x32_bf16 v[60:63], v[132:135], v[174:177], v[60:63]
	v_mfma_f32_16x16x32_bf16 v[56:59], v[140:143], v[174:177], v[56:59]
	v_mfma_f32_16x16x32_bf16 v[44:47], v[132:135], v[182:185], v[44:47]
	v_mfma_f32_16x16x32_bf16 v[40:43], v[140:143], v[182:185], v[40:43]
	v_mfma_f32_16x16x32_bf16 v[28:31], v[132:135], v[196:199], v[28:31]
	v_mfma_f32_16x16x32_bf16 v[24:27], v[140:143], v[196:199], v[24:27]
	v_mfma_f32_16x16x32_bf16 v[12:15], v[132:135], v[204:207], v[12:15]
	v_mfma_f32_16x16x32_bf16 v[8:11], v[140:143], v[204:207], v[8:11]
	v_mfma_f32_16x16x32_bf16 v[60:63], v[136:139], v[178:181], v[60:63]
	v_mfma_f32_16x16x32_bf16 v[56:59], v[144:147], v[178:181], v[56:59]
	v_mfma_f32_16x16x32_bf16 v[44:47], v[136:139], v[186:189], v[44:47]
	v_mfma_f32_16x16x32_bf16 v[40:43], v[144:147], v[186:189], v[40:43]
	v_mfma_f32_16x16x32_bf16 v[28:31], v[136:139], v[200:203], v[28:31]
	v_mfma_f32_16x16x32_bf16 v[24:27], v[144:147], v[200:203], v[24:27]
	v_mfma_f32_16x16x32_bf16 v[12:15], v[136:139], v[208:211], v[12:15]
	v_mfma_f32_16x16x32_bf16 v[8:11], v[144:147], v[208:211], v[8:11]
	s_setprio 0
	s_setprio 1
	v_mfma_f32_16x16x32_bf16 v[52:55], v[148:151], v[174:177], v[52:55]
	v_mfma_f32_16x16x32_bf16 v[48:51], v[166:169], v[174:177], v[48:51]
	v_mfma_f32_16x16x32_bf16 v[36:39], v[148:151], v[182:185], v[36:39]
	v_mfma_f32_16x16x32_bf16 v[32:35], v[166:169], v[182:185], v[32:35]
	v_mfma_f32_16x16x32_bf16 v[20:23], v[148:151], v[196:199], v[20:23]
	v_mfma_f32_16x16x32_bf16 v[16:19], v[166:169], v[196:199], v[16:19]
	v_mfma_f32_16x16x32_bf16 v[4:7], v[148:151], v[204:207], v[4:7]
	v_mfma_f32_16x16x32_bf16 v[0:3], v[166:169], v[204:207], v[0:3]
	v_mfma_f32_16x16x32_bf16 v[52:55], v[162:165], v[178:181], v[52:55]
	v_mfma_f32_16x16x32_bf16 v[48:51], v[170:173], v[178:181], v[48:51]
	v_mfma_f32_16x16x32_bf16 v[36:39], v[162:165], v[186:189], v[36:39]
	v_mfma_f32_16x16x32_bf16 v[32:35], v[170:173], v[186:189], v[32:35]
	v_mfma_f32_16x16x32_bf16 v[20:23], v[162:165], v[200:203], v[20:23]
	v_mfma_f32_16x16x32_bf16 v[16:19], v[170:173], v[200:203], v[16:19]
	v_mfma_f32_16x16x32_bf16 v[4:7], v[162:165], v[208:211], v[4:7]
	v_mfma_f32_16x16x32_bf16 v[0:3], v[170:173], v[208:211], v[0:3]
	s_setprio 0
	s_barrier
	s_add_i32 s0, s0, 2
	s_add_u32 s24, s24, 0x100
	s_addc_u32 s25, s25, 0
	s_add_u32 s38, s38, 0x100
	s_addc_u32 s39, s39, 0
	s_cmp_gt_u32 s0, 13
	s_cbranch_scc0 .LBB0_200
	s_cmp_lg_u32 s92, 8
	s_cbranch_scc1 .Lsd_e_skip
	s_and_b64 vcc, exec, s[46:47]
	s_cbranch_vccnz .Lsd_e_skip
	s_lshl_b32 s0, s23, 1
	s_add_u32 s16, s26, 0x6400
	s_addc_u32 s17, s27, 0
	s_add_u32 s16, s16, s0
	s_addc_u32 s17, s17, 0
	v_readlane_b32 s0, v254, 49
	v_readlane_b32 s1, v254, 54
	s_lshr_b32 s0, s0, 3
	s_lshl_b32 s0, s0, 2
	s_add_i32 s1, s1, 1
	v_mov_b32_e32 v130, s0
	v_mov_b32_e32 v131, s1
	s_mov_b64 exec, 1
	global_store_dword v130, v131, s[16:17]
	s_mov_b64 exec, -1
.Lsd_e_skip:
	s_nop 0
	s_nop 0
	s_nop 0
	s_nop 0
	s_nop 0
	s_nop 0
	s_nop 0
	s_nop 0
	s_nop 0
	s_and_b64 vcc, exec, s[74:75]
	s_cbranch_vccz .LBB0_203
	s_barrier

; #define SEAM(k) do { if (IN(k) && IN((k) + 1)) { if (lmode) { xcdl_barrier(bar); if (PROBE_DBLBAR) xcdl_barrier(bar); } else { xcd_barrier(bar); if (PROBE_DBLBAR) xcd_barrier(bar); } } TS_END(k); TS_BEGIN((k) + 1); } while (0)
; #define REPS(bit) for (int rep = ((PROBE_MASK & (bit)) ? 0 : 1); rep < 2; ++rep)
; __global__ void __launch_bounds__(512, 2) mk_fwd(Args args) {
;     ...
;         SEAM(ph);
;         REPS(4) { if (IN(ph + 1)) {
;             SUBTS(20, if (PH_MASK & 8) b_unit(F, F.vcu, DRY));
.LBB0_447:
	s_and_b64 vcc, exec, s[0:1]
	s_cbranch_vccz .LBB0_467
	s_waitcnt vmcnt(0)
	s_and_b64 vcc, exec, s[46:47]
	s_waitcnt vmcnt(0)
	s_barrier
	s_cbranch_vccnz .LBB0_466
	v_mbcnt_lo_u32_b32 v0, -1, 0
	v_mbcnt_hi_u32_b32 v0, -1, v0
	s_nop 0
	v_cmp_eq_u32_e32 vcc, 0, v0
	s_and_saveexec_b64 s[2:3], vcc
	s_cbranch_execz .LBB0_465
	s_lshl_b32 s6, s23, 1
	s_add_u32 s0, s26, 0x6000
	s_addc_u32 s1, s27, 0
	s_add_u32 s0, s0, s6
	s_addc_u32 s1, s1, 0
	v_readlane_b32 s6, v254, 49
	s_add_i32 s7, s34, 1
	s_lshr_b32 s6, s6, 3
	s_lshl_b32 s6, s6, 2
	v_mov_b32_e32 v0, s6
	v_mov_b32_e32 v1, s7
	s_waitcnt vmcnt(0) lgkmcnt(0)
	global_store_dword v0, v1, s[0:1]
	s_mov_b64 s[28:29], exec
	s_mov_b32 exec_lo, -1
	s_mov_b32 exec_hi, 0
	v_mbcnt_lo_u32_b32 v2, -1, 0
	v_lshlrev_b32_e32 v2, 2, v2
	v_mov_b32_e32 v1, s7
	s_mov_b32 s8, 0
	s_add_u32 s0, s0, 0x400
	s_addc_u32 s1, s1, 0

; #define BU_LOAD(buf, ib) do { _Pragma("unroll") for (int h = 0; h < 2; ++h) { const int it = (2 * (ib) + h + k2) & 7, l = 16 * w + 2 * it + rp; \
;             _Pragma("unroll") for (int s2 = 0; s2 < 8; ++s2) c4[buf][h][s2] = *(const GAS u32x4*)(z0 + (size_t)l * 2048 + 256 * s2); } } while (0)
; __device__ __forceinline__ void b_unit(Frame& F, int u, bool dry) {
;     ...
;     {
;         const f32x2* TW = (const f32x2*)(ws_ + WS_TW) + k2 * 256 + 8 * sg; const f32x2* W8 = (const f32x2*)(ws_ + WS_W8);
;         f32x2 tw[8], w8[8];
; #pragma unroll
;         for (int j = 0; j < 8; ++j) { tw[j] = TW[j]; w8[j] = W8[(j * k2) & 7]; }
;         const bf16_t* z0 = (const bf16_t*)(ws_ + WS_ZT) + (size_t)(b * 512 + g * 128) * 2048 + 8 * sg;
;         u32x4 c4[2][2][8];
;     ...
;         BU_LOAD(0, 0);
;         BU_LOAD(1, 1); BU_RED(0, 0);
.LBB0_468:
	s_cmp_le_i32 s66, s16
	s_cselect_b64 s[0:1], -1, 0
	s_and_b64 s[4:5], s[0:1], s[4:5]
	s_andn2_b64 vcc, exec, s[4:5]
	s_cbranch_vccnz .LBB0_562
	s_mov_b64 s[2:3], s[82:83]
	v_readlane_b32 s0, v254, 23
	v_mbcnt_lo_u32_b32 v170, -1, 0
	v_mbcnt_hi_u32_b32 v170, -1, v170
	s_add_u32 s0, s2, s0
	v_and_b32_e32 v18, 31, v170
	s_addc_u32 s1, s3, 0
	v_lshlrev_b32_e32 v192, 6, v18
	v_lshl_add_u64 v[0:1], s[0:1], 0, v[192:193]
	s_mov_b64 s[0:1], 0x1dd0000
	v_lshl_add_u64 v[2:3], v[0:1], 0, s[0:1]
	s_mov_b32 s0, 0x1dd0000
	v_add_co_u32_e32 v0, vcc, s0, v0
	s_add_u32 s6, s2, 0x1dd4000
	s_nop 0
	v_addc_co_u32_e32 v1, vcc, 0, v1, vcc
	s_addc_u32 s7, s3, 0
	flat_load_dwordx4 v[8:11], v[0:1]
	v_mov_b32_e32 v0, s2
	s_mov_b32 s8, 0x1dd4000
	v_readlane_b32 s0, v254, 24
	v_add_co_u32_e32 v0, vcc, s8, v0
	v_mov_b32_e32 v1, s3
	s_add_u32 s0, s6, s0
	v_addc_co_u32_e32 v1, vcc, 0, v1, vcc
	s_addc_u32 s1, s7, 0
	flat_load_dwordx2 v[144:145], v[0:1]
	v_mov_b64_e32 v[0:1], s[0:1]
	v_readlane_b32 s0, v254, 25
	s_add_u32 s0, s6, s0
	s_addc_u32 s1, s7, 0
	flat_load_dwordx2 v[146:147], v[0:1]
	flat_load_dwordx4 v[12:15], v[2:3] offset:16
	v_mov_b64_e32 v[0:1], s[0:1]
	v_readlane_b32 s0, v254, 26
	s_add_u32 s0, s6, s0
	s_addc_u32 s1, s7, 0
	flat_load_dwordx2 v[148:149], v[0:1]
	v_mov_b64_e32 v[0:1], s[0:1]
	v_readlane_b32 s0, v254, 27
	s_add_u32 s0, s6, s0
	s_addc_u32 s1, s7, 0
	flat_load_dwordx2 v[150:151], v[0:1]
	flat_load_dwordx4 v[4:7], v[2:3] offset:32
	v_mov_b64_e32 v[0:1], s[0:1]
	v_readlane_b32 s0, v254, 28
	s_add_u32 s0, s6, s0
	s_addc_u32 s1, s7, 0
	flat_load_dwordx2 v[152:153], v[0:1]
	v_mov_b64_e32 v[0:1], s[0:1]
	v_readlane_b32 s0, v254, 29
	s_add_u32 s0, s6, s0
	s_addc_u32 s1, s7, 0
	v_mov_b64_e32 v[16:17], s[0:1]
	v_readlane_b32 s0, v254, 30
	s_add_u32 s0, s6, s0
	s_addc_u32 s1, s7, 0
	flat_load_dwordx2 v[154:155], v[0:1]
	s_nop 0
	flat_load_dwordx4 v[0:3], v[2:3] offset:48
	v_lshlrev_b32_e32 v192, 4, v18
	flat_load_dwordx2 v[156:157], v[16:17]
	v_mov_b64_e32 v[16:17], s[0:1]
	v_readlane_b32 s0, v253, 43
	v_readlane_b32 s1, v253, 44
	s_add_u32 s0, s2, s0
	s_addc_u32 s1, s3, s1
	flat_load_dwordx2 v[158:159], v[16:17]
	v_lshl_add_u64 v[16:17], s[0:1], 0, v[192:193]
	s_mov_b64 s[0:1], 0x8000000
	v_bfe_u32 v172, v170, 5, 1
	v_lshl_add_u64 v[162:163], v[16:17], 0, s[0:1]
	v_readlane_b32 s0, v253, 45
	v_mov_b32_e32 v139, v193
	v_readlane_b32 s1, v253, 46
	v_or_b32_e32 v138, s0, v172
	v_lshlrev_b64 v[16:17], 12, v[138:139]
	v_lshl_add_u64 v[16:17], v[162:163], 0, v[16:17]
	global_load_dwordx4 v[140:143], v[16:17], off sc1
	global_load_dwordx4 v[174:177], v[16:17], off offset:512 sc1
	global_load_dwordx4 v[72:75], v[16:17], off offset:1024 sc1
	global_load_dwordx4 v[104:107], v[16:17], off offset:1536 sc1
	global_load_dwordx4 v[112:115], v[16:17], off offset:2048 sc1
	global_load_dwordx4 v[116:119], v[16:17], off offset:2560 sc1
	global_load_dwordx4 v[120:123], v[16:17], off offset:3072 sc1
	global_load_dwordx4 v[124:127], v[16:17], off offset:3584 sc1
	v_or_b32_e32 v136, s1, v172
	v_mov_b32_e32 v137, v193
	v_lshlrev_b64 v[16:17], 12, v[136:137]
	v_lshl_add_u64 v[16:17], v[162:163], 0, v[16:17]
	global_load_dwordx4 v[108:111], v[16:17], off sc1
	global_load_dwordx4 v[76:79], v[16:17], off offset:512 sc1
	global_load_dwordx4 v[60:63], v[16:17], off offset:1024 sc1
	global_load_dwordx4 v[56:59], v[16:17], off offset:1536 sc1
	global_load_dwordx4 v[52:55], v[16:17], off offset:2048 sc1
	global_load_dwordx4 v[48:51], v[16:17], off offset:2560 sc1
	global_load_dwordx4 v[44:47], v[16:17], off offset:3072 sc1
	global_load_dwordx4 v[40:43], v[16:17], off offset:3584 sc1
	v_readlane_b32 s1, v253, 47
	v_mov_b32_e32 v167, v193
	v_mov_b32_e32 v165, v193
	v_or_b32_e32 v166, s1, v172
	v_lshlrev_b64 v[16:17], 12, v[166:167]
	v_lshl_add_u64 v[16:17], v[162:163], 0, v[16:17]
	global_load_dwordx4 v[132:135], v[16:17], off sc1
	global_load_dwordx4 v[128:131], v[16:17], off offset:512 sc1
	global_load_dwordx4 v[100:103], v[16:17], off offset:1024 sc1
	global_load_dwordx4 v[96:99], v[16:17], off offset:1536 sc1
	global_load_dwordx4 v[92:95], v[16:17], off offset:2048 sc1
	global_load_dwordx4 v[88:91], v[16:17], off offset:2560 sc1
	global_load_dwordx4 v[84:87], v[16:17], off offset:3072 sc1
	global_load_dwordx4 v[80:83], v[16:17], off offset:3584 sc1
	v_readlane_b32 s1, v253, 48
	s_movk_i32 s6, 0x410
	v_and_b32_e32 v171, 63, v170
	v_or_b32_e32 v164, s1, v172
	v_lshlrev_b64 v[16:17], 12, v[164:165]
	v_lshl_add_u64 v[16:17], v[162:163], 0, v[16:17]
	global_load_dwordx4 v[68:71], v[16:17], off sc1
	global_load_dwordx4 v[64:67], v[16:17], off offset:512 sc1
	global_load_dwordx4 v[36:39], v[16:17], off offset:1024 sc1
	global_load_dwordx4 v[32:35], v[16:17], off offset:1536 sc1
	global_load_dwordx4 v[28:31], v[16:17], off offset:2048 sc1
	global_load_dwordx4 v[24:27], v[16:17], off offset:2560 sc1
	global_load_dwordx4 v[20:23], v[16:17], off offset:3072 sc1
	s_nop 0
	global_load_dwordx4 v[16:19], v[16:17], off offset:3584 sc1
	s_mov_b32 s7, 0x1d90000
	s_mov_b64 s[28:29], s[82:83]
	s_waitcnt vmcnt(0)
	v_lshlrev_b32_e32 v160, 16, v140
	v_and_b32_e32 v161, 0xffff0000, v140
	v_lshlrev_b32_e32 v178, 16, v174
	v_and_b32_e32 v179, 0xffff0000, v174
	s_waitcnt lgkmcnt(0)
	v_pk_fma_f32 v[182:183], v[144:145], v[160:161], 0 op_sel_hi:[0,1,0]
	v_pk_fma_f32 v[160:161], v[144:145], v[160:161], 0 op_sel:[1,0,0] op_sel_hi:[1,1,0]
	v_pk_fma_f32 v[182:183], v[146:147], v[178:179], v[182:183] op_sel_hi:[0,1,1]
	v_pk_fma_f32 v[160:161], v[146:147], v[178:179], v[160:161] op_sel:[1,0,0]
	v_lshlrev_b32_e32 v178, 16, v72
	v_and_b32_e32 v179, 0xffff0000, v72
	v_pk_fma_f32 v[182:183], v[148:149], v[178:179], v[182:183] op_sel_hi:[0,1,1]
	v_pk_fma_f32 v[160:161], v[148:149], v[178:179], v[160:161] op_sel:[1,0,0]
	v_lshlrev_b32_e32 v178, 16, v104
	v_and_b32_e32 v179, 0xffff0000, v104
	v_pk_fma_f32 v[182:183], v[150:151], v[178:179], v[182:183] op_sel_hi:[0,1,1]
	v_pk_fma_f32 v[160:161], v[150:151], v[178:179], v[160:161] op_sel:[1,0,0]
	v_lshlrev_b32_e32 v178, 16, v112
	v_and_b32_e32 v179, 0xffff0000, v112
	v_pk_fma_f32 v[182:183], v[152:153], v[178:179], v[182:183] op_sel_hi:[0,1,1]
	v_pk_fma_f32 v[160:161], v[152:153], v[178:179], v[160:161] op_sel:[1,0,0]
	v_lshlrev_b32_e32 v178, 16, v116
	v_and_b32_e32 v179, 0xffff0000, v116
	v_pk_fma_f32 v[182:183], v[154:155], v[178:179], v[182:183] op_sel_hi:[0,1,1]
	v_pk_fma_f32 v[160:161], v[154:155], v[178:179], v[160:161] op_sel:[1,0,0]
	v_lshlrev_b32_e32 v178, 16, v120
	v_and_b32_e32 v179, 0xffff0000, v120
	v_pk_fma_f32 v[182:183], v[156:157], v[178:179], v[182:183] op_sel_hi:[0,1,1]
	v_pk_fma_f32 v[160:161], v[156:157], v[178:179], v[160:161] op_sel:[1,0,0]
	v_lshlrev_b32_e32 v178, 16, v124
	v_and_b32_e32 v179, 0xffff0000, v124
	v_pk_fma_f32 v[182:183], v[158:159], v[178:179], v[182:183] op_sel_hi:[0,1,1]
	v_pk_fma_f32 v[178:179], v[158:159], v[178:179], v[160:161] op_sel:[1,0,0]
	v_mov_b32_e32 v161, v10
	v_mov_b32_e32 v10, v9
	v_mov_b32_e32 v160, v8
	v_pk_mul_f32 v[8:9], v[10:11], v[178:179]
	v_lshlrev_b32_e32 v140, 16, v141
	v_and_b32_e32 v141, 0xffff0000, v141
	v_pk_fma_f32 v[184:185], v[160:161], v[182:183], v[8:9] neg_lo:[0,0,1] neg_hi:[0,0,1]
	v_pk_mul_f32 v[8:9], v[160:161], v[178:179]
	v_lshlrev_b32_e32 v174, 16, v175
	v_and_b32_e32 v175, 0xffff0000, v175
	v_pk_fma_f32 v[178:179], v[10:11], v[182:183], v[8:9]
	v_pk_fma_f32 v[8:9], v[144:145], v[140:141], 0 op_sel_hi:[0,1,0]
	v_pk_fma_f32 v[140:141], v[144:145], v[140:141], 0 op_sel:[1,0,0] op_sel_hi:[1,1,0]
	v_pk_fma_f32 v[8:9], v[146:147], v[174:175], v[8:9] op_sel_hi:[0,1,1]
	v_pk_fma_f32 v[140:141], v[146:147], v[174:175], v[140:141] op_sel:[1,0,0]
	v_lshlrev_b32_e32 v72, 16, v73
	v_and_b32_e32 v73, 0xffff0000, v73
	v_pk_fma_f32 v[8:9], v[148:149], v[72:73], v[8:9] op_sel_hi:[0,1,1]
	v_pk_fma_f32 v[72:73], v[148:149], v[72:73], v[140:141] op_sel:[1,0,0]
	v_lshlrev_b32_e32 v104, 16, v105
	v_and_b32_e32 v105, 0xffff0000, v105
	v_pk_fma_f32 v[8:9], v[150:151], v[104:105], v[8:9] op_sel_hi:[0,1,1]
	v_pk_fma_f32 v[72:73], v[150:151], v[104:105], v[72:73] op_sel:[1,0,0]
	v_lshlrev_b32_e32 v104, 16, v113
	v_and_b32_e32 v105, 0xffff0000, v113
	v_pk_fma_f32 v[8:9], v[152:153], v[104:105], v[8:9] op_sel_hi:[0,1,1]
	v_pk_fma_f32 v[72:73], v[152:153], v[104:105], v[72:73] op_sel:[1,0,0]
	v_lshlrev_b32_e32 v104, 16, v117
	v_and_b32_e32 v105, 0xffff0000, v117
	v_pk_fma_f32 v[8:9], v[154:155], v[104:105], v[8:9] op_sel_hi:[0,1,1]
	v_pk_fma_f32 v[72:73], v[154:155], v[104:105], v[72:73] op_sel:[1,0,0]
	v_lshlrev_b32_e32 v104, 16, v121
	v_and_b32_e32 v105, 0xffff0000, v121
	v_pk_fma_f32 v[8:9], v[156:157], v[104:105], v[8:9] op_sel_hi:[0,1,1]
	v_pk_fma_f32 v[72:73], v[156:157], v[104:105], v[72:73] op_sel:[1,0,0]
	v_lshlrev_b32_e32 v104, 16, v125
	v_and_b32_e32 v105, 0xffff0000, v125
	v_pk_fma_f32 v[112:113], v[158:159], v[104:105], v[8:9] op_sel_hi:[0,1,1]
	v_pk_fma_f32 v[72:73], v[158:159], v[104:105], v[72:73] op_sel:[1,0,0]
	v_mov_b32_e32 v9, v14
	v_mov_b32_e32 v14, v13
	v_mov_b32_e32 v8, v12
	v_pk_mul_f32 v[12:13], v[14:15], v[72:73]
	v_lshlrev_b32_e32 v168, 16, v142
	v_and_b32_e32 v169, 0xffff0000, v142
	v_pk_fma_f32 v[104:105], v[8:9], v[112:113], v[12:13] neg_lo:[0,0,1] neg_hi:[0,0,1]
	v_pk_mul_f32 v[12:13], v[8:9], v[72:73]
	v_lshlrev_b32_e32 v180, 16, v176
	v_and_b32_e32 v181, 0xffff0000, v176
	v_pk_fma_f32 v[112:113], v[14:15], v[112:113], v[12:13]
	v_pk_fma_f32 v[12:13], v[144:145], v[168:169], 0 op_sel_hi:[0,1,0]
	v_pk_fma_f32 v[72:73], v[144:145], v[168:169], 0 op_sel:[1,0,0] op_sel_hi:[1,1,0]
	v_pk_fma_f32 v[12:13], v[146:147], v[180:181], v[12:13] op_sel_hi:[0,1,1]
	v_pk_fma_f32 v[72:73], v[146:147], v[180:181], v[72:73] op_sel:[1,0,0]
	v_lshlrev_b32_e32 v116, 16, v74
	v_and_b32_e32 v117, 0xffff0000, v74
	v_pk_fma_f32 v[12:13], v[148:149], v[116:117], v[12:13] op_sel_hi:[0,1,1]
	v_pk_fma_f32 v[72:73], v[148:149], v[116:117], v[72:73] op_sel:[1,0,0]
	v_lshlrev_b32_e32 v116, 16, v106
	v_and_b32_e32 v117, 0xffff0000, v106
	v_pk_fma_f32 v[12:13], v[150:151], v[116:117], v[12:13] op_sel_hi:[0,1,1]
	v_pk_fma_f32 v[72:73], v[150:151], v[116:117], v[72:73] op_sel:[1,0,0]
	v_lshlrev_b32_e32 v116, 16, v114
	v_and_b32_e32 v117, 0xffff0000, v114
	v_pk_fma_f32 v[12:13], v[152:153], v[116:117], v[12:13] op_sel_hi:[0,1,1]
	v_pk_fma_f32 v[72:73], v[152:153], v[116:117], v[72:73] op_sel:[1,0,0]
	v_lshlrev_b32_e32 v116, 16, v118
	v_and_b32_e32 v117, 0xffff0000, v118
	v_pk_fma_f32 v[12:13], v[154:155], v[116:117], v[12:13] op_sel_hi:[0,1,1]
	v_pk_fma_f32 v[72:73], v[154:155], v[116:117], v[72:73] op_sel:[1,0,0]
	v_lshlrev_b32_e32 v116, 16, v122
	v_and_b32_e32 v117, 0xffff0000, v122
	v_pk_fma_f32 v[12:13], v[156:157], v[116:117], v[12:13] op_sel_hi:[0,1,1]
	v_pk_fma_f32 v[72:73], v[156:157], v[116:117], v[72:73] op_sel:[1,0,0]
	v_lshlrev_b32_e32 v116, 16, v126
	v_and_b32_e32 v117, 0xffff0000, v126
	v_pk_fma_f32 v[120:121], v[158:159], v[116:117], v[12:13] op_sel_hi:[0,1,1]
	v_pk_fma_f32 v[72:73], v[158:159], v[116:117], v[72:73] op_sel:[1,0,0]
	v_mov_b32_e32 v13, v6
	v_mov_b32_e32 v6, v5
	v_mov_b32_e32 v12, v4
	v_pk_mul_f32 v[4:5], v[6:7], v[72:73]
	v_lshlrev_b32_e32 v142, 16, v143
	v_and_b32_e32 v143, 0xffff0000, v143
	v_pk_fma_f32 v[116:117], v[12:13], v[120:121], v[4:5] neg_lo:[0,0,1] neg_hi:[0,0,1]
	v_pk_mul_f32 v[4:5], v[12:13], v[72:73]
	v_lshlrev_b32_e32 v176, 16, v177
	v_and_b32_e32 v177, 0xffff0000, v177
	v_pk_fma_f32 v[120:121], v[6:7], v[120:121], v[4:5]
	v_pk_fma_f32 v[4:5], v[144:145], v[142:143], 0 op_sel_hi:[0,1,0]
	v_pk_fma_f32 v[72:73], v[144:145], v[142:143], 0 op_sel:[1,0,0] op_sel_hi:[1,1,0]
	v_pk_fma_f32 v[4:5], v[146:147], v[176:177], v[4:5] op_sel_hi:[0,1,1]
	v_pk_fma_f32 v[72:73], v[146:147], v[176:177], v[72:73] op_sel:[1,0,0]
	v_lshlrev_b32_e32 v74, 16, v75
	v_and_b32_e32 v75, 0xffff0000, v75
	v_pk_fma_f32 v[4:5], v[148:149], v[74:75], v[4:5] op_sel_hi:[0,1,1]
	v_pk_fma_f32 v[72:73], v[148:149], v[74:75], v[72:73] op_sel:[1,0,0]
	v_lshlrev_b32_e32 v74, 16, v107
	v_and_b32_e32 v75, 0xffff0000, v107
	v_pk_fma_f32 v[4:5], v[150:151], v[74:75], v[4:5] op_sel_hi:[0,1,1]
	v_pk_fma_f32 v[72:73], v[150:151], v[74:75], v[72:73] op_sel:[1,0,0]
	v_lshlrev_b32_e32 v74, 16, v115
	v_and_b32_e32 v75, 0xffff0000, v115
	v_pk_fma_f32 v[4:5], v[152:153], v[74:75], v[4:5] op_sel_hi:[0,1,1]
	v_pk_fma_f32 v[72:73], v[152:153], v[74:75], v[72:73] op_sel:[1,0,0]
	v_lshlrev_b32_e32 v74, 16, v119
	v_and_b32_e32 v75, 0xffff0000, v119
	v_pk_fma_f32 v[4:5], v[154:155], v[74:75], v[4:5] op_sel_hi:[0,1,1]
	v_pk_fma_f32 v[72:73], v[154:155], v[74:75], v[72:73] op_sel:[1,0,0]
	v_lshlrev_b32_e32 v74, 16, v123
	v_and_b32_e32 v75, 0xffff0000, v123
	v_pk_fma_f32 v[4:5], v[156:157], v[74:75], v[4:5] op_sel_hi:[0,1,1]
	v_pk_fma_f32 v[72:73], v[156:157], v[74:75], v[72:73] op_sel:[1,0,0]
	v_lshlrev_b32_e32 v74, 16, v127
	v_and_b32_e32 v75, 0xffff0000, v127
	v_pk_fma_f32 v[106:107], v[158:159], v[74:75], v[4:5] op_sel_hi:[0,1,1]
	v_pk_fma_f32 v[72:73], v[158:159], v[74:75], v[72:73] op_sel:[1,0,0]
	v_mov_b32_e32 v5, v2
	v_mov_b32_e32 v2, v1
	v_mov_b32_e32 v4, v0
	v_pk_mul_f32 v[0:1], v[2:3], v[72:73]
	v_pk_mul_f32 v[72:73], v[4:5], v[72:73]
	v_pk_fma_f32 v[0:1], v[4:5], v[106:107], v[0:1] neg_lo:[0,0,1] neg_hi:[0,0,1]
	v_pk_fma_f32 v[106:107], v[2:3], v[106:107], v[72:73]
	v_cvt_pk_bf16_f32 v75, v0, v1
	v_mul_lo_u32 v0, v138, s6
	v_cvt_pk_bf16_f32 v72, v184, v185
	v_cvt_pk_bf16_f32 v73, v104, v105
	v_cvt_pk_bf16_f32 v74, v116, v117
	v_add3_u32 v0, 0, v0, v192
	ds_write_b128 v0, v[72:75]
	v_cvt_pk_bf16_f32 v72, v178, v179
	v_cvt_pk_bf16_f32 v73, v112, v113
	v_cvt_pk_bf16_f32 v74, v120, v121
	v_cvt_pk_bf16_f32 v75, v106, v107
	ds_write_b128 v0, v[72:75] offset:512
	v_lshlrev_b32_e32 v0, 16, v108
	v_and_b32_e32 v1, 0xffff0000, v108
	v_lshlrev_b32_e32 v74, 16, v110
	v_and_b32_e32 v75, 0xffff0000, v110
	v_lshlrev_b32_e32 v104, 16, v111
	v_and_b32_e32 v105, 0xffff0000, v111
	v_lshlrev_b32_e32 v106, 16, v76
	v_and_b32_e32 v107, 0xffff0000, v76
	v_pk_fma_f32 v[110:111], v[144:145], v[0:1], 0 op_sel_hi:[0,1,0]
	v_pk_fma_f32 v[0:1], v[144:145], v[0:1], 0 op_sel:[1,0,0] op_sel_hi:[1,1,0]
	v_pk_fma_f32 v[110:111], v[146:147], v[106:107], v[110:111] op_sel_hi:[0,1,1]
	v_pk_fma_f32 v[0:1], v[146:147], v[106:107], v[0:1] op_sel:[1,0,0]
	v_lshlrev_b32_e32 v106, 16, v60
	v_and_b32_e32 v107, 0xffff0000, v60
	v_pk_fma_f32 v[110:111], v[148:149], v[106:107], v[110:111] op_sel_hi:[0,1,1]
	v_pk_fma_f32 v[0:1], v[148:149], v[106:107], v[0:1] op_sel:[1,0,0]
	v_lshlrev_b32_e32 v106, 16, v56
	v_and_b32_e32 v107, 0xffff0000, v56
	v_pk_fma_f32 v[110:111], v[150:151], v[106:107], v[110:111] op_sel_hi:[0,1,1]
	v_pk_fma_f32 v[0:1], v[150:151], v[106:107], v[0:1] op_sel:[1,0,0]
	v_lshlrev_b32_e32 v106, 16, v52
	v_and_b32_e32 v107, 0xffff0000, v52
	v_pk_fma_f32 v[110:111], v[152:153], v[106:107], v[110:111] op_sel_hi:[0,1,1]
	v_pk_fma_f32 v[0:1], v[152:153], v[106:107], v[0:1] op_sel:[1,0,0]
	v_lshlrev_b32_e32 v106, 16, v48
	v_and_b32_e32 v107, 0xffff0000, v48
	v_pk_fma_f32 v[110:111], v[154:155], v[106:107], v[110:111] op_sel_hi:[0,1,1]
	v_pk_fma_f32 v[0:1], v[154:155], v[106:107], v[0:1] op_sel:[1,0,0]
	v_lshlrev_b32_e32 v106, 16, v44
	v_and_b32_e32 v107, 0xffff0000, v44
	v_pk_fma_f32 v[110:111], v[156:157], v[106:107], v[110:111] op_sel_hi:[0,1,1]
	v_pk_fma_f32 v[0:1], v[156:157], v[106:107], v[0:1] op_sel:[1,0,0]
	v_lshlrev_b32_e32 v106, 16, v40
	v_and_b32_e32 v107, 0xffff0000, v40
	v_pk_fma_f32 v[0:1], v[158:159], v[106:107], v[0:1] op_sel:[1,0,0]
	v_lshlrev_b32_e32 v72, 16, v109
	v_and_b32_e32 v73, 0xffff0000, v109
	v_pk_fma_f32 v[110:111], v[158:159], v[106:107], v[110:111] op_sel_hi:[0,1,1]
	v_pk_mul_f32 v[106:107], v[10:11], v[0:1]
	v_pk_mul_f32 v[0:1], v[160:161], v[0:1]
	v_lshlrev_b32_e32 v76, 16, v77
	v_and_b32_e32 v77, 0xffff0000, v77
	v_pk_fma_f32 v[106:107], v[160:161], v[110:111], v[106:107] neg_lo:[0,0,1] neg_hi:[0,0,1]
	v_pk_fma_f32 v[0:1], v[10:11], v[110:111], v[0:1]
	v_pk_fma_f32 v[110:111], v[144:145], v[72:73], 0 op_sel_hi:[0,1,0]
	v_pk_fma_f32 v[72:73], v[144:145], v[72:73], 0 op_sel:[1,0,0] op_sel_hi:[1,1,0]
	v_pk_fma_f32 v[110:111], v[146:147], v[76:77], v[110:111] op_sel_hi:[0,1,1]
	v_pk_fma_f32 v[72:73], v[146:147], v[76:77], v[72:73] op_sel:[1,0,0]
	v_lshlrev_b32_e32 v60, 16, v61
	v_and_b32_e32 v61, 0xffff0000, v61
	v_pk_fma_f32 v[76:77], v[148:149], v[60:61], v[110:111] op_sel_hi:[0,1,1]
	v_pk_fma_f32 v[60:61], v[148:149], v[60:61], v[72:73] op_sel:[1,0,0]
	v_lshlrev_b32_e32 v56, 16, v57
	v_and_b32_e32 v57, 0xffff0000, v57
	v_pk_fma_f32 v[72:73], v[150:151], v[56:57], v[76:77] op_sel_hi:[0,1,1]
	v_pk_fma_f32 v[56:57], v[150:151], v[56:57], v[60:61] op_sel:[1,0,0]
	v_lshlrev_b32_e32 v52, 16, v53
	v_and_b32_e32 v53, 0xffff0000, v53
	v_pk_fma_f32 v[60:61], v[152:153], v[52:53], v[72:73] op_sel_hi:[0,1,1]
	v_pk_fma_f32 v[52:53], v[152:153], v[52:53], v[56:57] op_sel:[1,0,0]
	v_lshlrev_b32_e32 v48, 16, v49
	v_and_b32_e32 v49, 0xffff0000, v49
	v_pk_fma_f32 v[56:57], v[154:155], v[48:49], v[60:61] op_sel_hi:[0,1,1]
	v_pk_fma_f32 v[48:49], v[154:155], v[48:49], v[52:53] op_sel:[1,0,0]
	v_lshlrev_b32_e32 v44, 16, v45
	v_and_b32_e32 v45, 0xffff0000, v45
	v_pk_fma_f32 v[52:53], v[156:157], v[44:45], v[56:57] op_sel_hi:[0,1,1]
	v_pk_fma_f32 v[44:45], v[156:157], v[44:45], v[48:49] op_sel:[1,0,0]
	v_lshlrev_b32_e32 v40, 16, v41
	v_and_b32_e32 v41, 0xffff0000, v41
	v_pk_fma_f32 v[48:49], v[158:159], v[40:41], v[52:53] op_sel_hi:[0,1,1]
	v_pk_fma_f32 v[40:41], v[158:159], v[40:41], v[44:45] op_sel:[1,0,0]
	v_lshlrev_b32_e32 v108, 16, v78
	v_pk_mul_f32 v[44:45], v[14:15], v[40:41]
	v_pk_mul_f32 v[40:41], v[8:9], v[40:41]
	v_and_b32_e32 v109, 0xffff0000, v78
	v_pk_fma_f32 v[44:45], v[8:9], v[48:49], v[44:45] neg_lo:[0,0,1] neg_hi:[0,0,1]
	v_pk_fma_f32 v[48:49], v[14:15], v[48:49], v[40:41]
	v_pk_fma_f32 v[40:41], v[144:145], v[74:75], 0 op_sel_hi:[0,1,0]
	v_pk_fma_f32 v[52:53], v[144:145], v[74:75], 0 op_sel:[1,0,0] op_sel_hi:[1,1,0]
	v_pk_fma_f32 v[40:41], v[146:147], v[108:109], v[40:41] op_sel_hi:[0,1,1]
	v_pk_fma_f32 v[52:53], v[146:147], v[108:109], v[52:53] op_sel:[1,0,0]
	v_lshlrev_b32_e32 v56, 16, v62
	v_and_b32_e32 v57, 0xffff0000, v62
	v_pk_fma_f32 v[40:41], v[148:149], v[56:57], v[40:41] op_sel_hi:[0,1,1]
	v_pk_fma_f32 v[52:53], v[148:149], v[56:57], v[52:53] op_sel:[1,0,0]
	v_lshlrev_b32_e32 v56, 16, v58
	v_and_b32_e32 v57, 0xffff0000, v58
	v_pk_fma_f32 v[40:41], v[150:151], v[56:57], v[40:41] op_sel_hi:[0,1,1]
	v_pk_fma_f32 v[52:53], v[150:151], v[56:57], v[52:53] op_sel:[1,0,0]
	v_lshlrev_b32_e32 v56, 16, v54
	v_and_b32_e32 v57, 0xffff0000, v54
	v_pk_fma_f32 v[40:41], v[152:153], v[56:57], v[40:41] op_sel_hi:[0,1,1]
	v_pk_fma_f32 v[52:53], v[152:153], v[56:57], v[52:53] op_sel:[1,0,0]
	v_lshlrev_b32_e32 v56, 16, v50
	v_and_b32_e32 v57, 0xffff0000, v50
	v_pk_fma_f32 v[40:41], v[154:155], v[56:57], v[40:41] op_sel_hi:[0,1,1]
	v_pk_fma_f32 v[52:53], v[154:155], v[56:57], v[52:53] op_sel:[1,0,0]
	v_lshlrev_b32_e32 v56, 16, v46
	v_and_b32_e32 v57, 0xffff0000, v46
	v_pk_fma_f32 v[40:41], v[156:157], v[56:57], v[40:41] op_sel_hi:[0,1,1]
	v_pk_fma_f32 v[52:53], v[156:157], v[56:57], v[52:53] op_sel:[1,0,0]
	v_lshlrev_b32_e32 v56, 16, v42
	v_and_b32_e32 v57, 0xffff0000, v42
	v_pk_fma_f32 v[52:53], v[158:159], v[56:57], v[52:53] op_sel:[1,0,0]
	v_pk_fma_f32 v[40:41], v[158:159], v[56:57], v[40:41] op_sel_hi:[0,1,1]
	v_pk_mul_f32 v[56:57], v[6:7], v[52:53]
	v_pk_mul_f32 v[52:53], v[12:13], v[52:53]
	v_lshlrev_b32_e32 v78, 16, v79
	v_and_b32_e32 v79, 0xffff0000, v79
	v_pk_fma_f32 v[56:57], v[12:13], v[40:41], v[56:57] neg_lo:[0,0,1] neg_hi:[0,0,1]
	v_pk_fma_f32 v[52:53], v[6:7], v[40:41], v[52:53]
	v_pk_fma_f32 v[40:41], v[144:145], v[104:105], 0 op_sel_hi:[0,1,0]
	v_pk_fma_f32 v[60:61], v[144:145], v[104:105], 0 op_sel:[1,0,0] op_sel_hi:[1,1,0]
	v_pk_fma_f32 v[40:41], v[146:147], v[78:79], v[40:41] op_sel_hi:[0,1,1]
	v_pk_fma_f32 v[60:61], v[146:147], v[78:79], v[60:61] op_sel:[1,0,0]
	v_lshlrev_b32_e32 v62, 16, v63
	v_and_b32_e32 v63, 0xffff0000, v63
	v_pk_fma_f32 v[40:41], v[148:149], v[62:63], v[40:41] op_sel_hi:[0,1,1]
	v_pk_fma_f32 v[60:61], v[148:149], v[62:63], v[60:61] op_sel:[1,0,0]
	v_lshlrev_b32_e32 v58, 16, v59
	v_and_b32_e32 v59, 0xffff0000, v59
	v_pk_fma_f32 v[40:41], v[150:151], v[58:59], v[40:41] op_sel_hi:[0,1,1]
	v_pk_fma_f32 v[58:59], v[150:151], v[58:59], v[60:61] op_sel:[1,0,0]
	v_lshlrev_b32_e32 v54, 16, v55
	v_and_b32_e32 v55, 0xffff0000, v55
	v_lshlrev_b32_e32 v174, 16, v132
	v_and_b32_e32 v175, 0xffff0000, v132
	v_pk_fma_f32 v[40:41], v[152:153], v[54:55], v[40:41] op_sel_hi:[0,1,1]
	v_pk_fma_f32 v[54:55], v[152:153], v[54:55], v[58:59] op_sel:[1,0,0]
	v_lshlrev_b32_e32 v50, 16, v51
	v_and_b32_e32 v51, 0xffff0000, v51
	v_lshlrev_b32_e32 v178, 16, v128
	v_and_b32_e32 v179, 0xffff0000, v128
	v_pk_fma_f32 v[182:183], v[144:145], v[174:175], 0 op_sel_hi:[0,1,0]
	v_pk_fma_f32 v[174:175], v[144:145], v[174:175], 0 op_sel:[1,0,0] op_sel_hi:[1,1,0]
	v_pk_fma_f32 v[40:41], v[154:155], v[50:51], v[40:41] op_sel_hi:[0,1,1]
	v_pk_fma_f32 v[50:51], v[154:155], v[50:51], v[54:55] op_sel:[1,0,0]
	v_lshlrev_b32_e32 v46, 16, v47
	v_and_b32_e32 v47, 0xffff0000, v47
	v_pk_fma_f32 v[182:183], v[146:147], v[178:179], v[182:183] op_sel_hi:[0,1,1]
	v_pk_fma_f32 v[174:175], v[146:147], v[178:179], v[174:175] op_sel:[1,0,0]
	v_lshlrev_b32_e32 v178, 16, v100
	v_and_b32_e32 v179, 0xffff0000, v100
	v_pk_fma_f32 v[40:41], v[156:157], v[46:47], v[40:41] op_sel_hi:[0,1,1]
	v_pk_fma_f32 v[46:47], v[156:157], v[46:47], v[50:51] op_sel:[1,0,0]
	v_lshlrev_b32_e32 v42, 16, v43
	v_and_b32_e32 v43, 0xffff0000, v43
	v_pk_fma_f32 v[182:183], v[148:149], v[178:179], v[182:183] op_sel_hi:[0,1,1]
	v_pk_fma_f32 v[174:175], v[148:149], v[178:179], v[174:175] op_sel:[1,0,0]
	v_lshlrev_b32_e32 v178, 16, v96
	v_and_b32_e32 v179, 0xffff0000, v96
	v_pk_fma_f32 v[40:41], v[158:159], v[42:43], v[40:41] op_sel_hi:[0,1,1]
	v_pk_fma_f32 v[42:43], v[158:159], v[42:43], v[46:47] op_sel:[1,0,0]
	v_pk_fma_f32 v[182:183], v[150:151], v[178:179], v[182:183] op_sel_hi:[0,1,1]
	v_pk_fma_f32 v[174:175], v[150:151], v[178:179], v[174:175] op_sel:[1,0,0]
	v_lshlrev_b32_e32 v178, 16, v92
	v_and_b32_e32 v179, 0xffff0000, v92
	v_pk_mul_f32 v[46:47], v[2:3], v[42:43]
	v_pk_mul_f32 v[42:43], v[4:5], v[42:43]
	v_pk_fma_f32 v[182:183], v[152:153], v[178:179], v[182:183] op_sel_hi:[0,1,1]
	v_pk_fma_f32 v[174:175], v[152:153], v[178:179], v[174:175] op_sel:[1,0,0]
	v_lshlrev_b32_e32 v178, 16, v88
	v_and_b32_e32 v179, 0xffff0000, v88
	v_pk_fma_f32 v[46:47], v[4:5], v[40:41], v[46:47] neg_lo:[0,0,1] neg_hi:[0,0,1]
	v_pk_fma_f32 v[50:51], v[2:3], v[40:41], v[42:43]
	v_cvt_pk_bf16_f32 v41, v44, v45
	v_mul_lo_u32 v44, v136, s6
	v_pk_fma_f32 v[182:183], v[154:155], v[178:179], v[182:183] op_sel_hi:[0,1,1]
	v_pk_fma_f32 v[174:175], v[154:155], v[178:179], v[174:175] op_sel:[1,0,0]
	v_lshlrev_b32_e32 v178, 16, v84
	v_and_b32_e32 v179, 0xffff0000, v84
	v_cvt_pk_bf16_f32 v40, v106, v107
	v_cvt_pk_bf16_f32 v42, v56, v57
	v_cvt_pk_bf16_f32 v43, v46, v47
	v_add3_u32 v44, 0, v44, v192
	v_bitop3_b32 v168, v172, 8, s0 bitop3:0x36
	v_mov_b32_e32 v169, v193
	v_pk_fma_f32 v[182:183], v[156:157], v[178:179], v[182:183] op_sel_hi:[0,1,1]
	v_pk_fma_f32 v[174:175], v[156:157], v[178:179], v[174:175] op_sel:[1,0,0]
	v_lshlrev_b32_e32 v178, 16, v80
	v_and_b32_e32 v179, 0xffff0000, v80
	ds_write_b128 v44, v[40:43]
	v_cvt_pk_bf16_f32 v40, v0, v1
	v_cvt_pk_bf16_f32 v41, v48, v49
	v_cvt_pk_bf16_f32 v42, v52, v53
	v_cvt_pk_bf16_f32 v43, v50, v51
	v_lshlrev_b64 v[0:1], 12, v[168:169]
	v_pk_fma_f32 v[174:175], v[158:159], v[178:179], v[174:175] op_sel:[1,0,0]
	ds_write_b128 v44, v[40:43] offset:512
	v_lshl_add_u64 v[0:1], v[162:163], 0, v[0:1]
	v_lshlrev_b32_e32 v132, 16, v133
	v_and_b32_e32 v133, 0xffff0000, v133
	v_pk_fma_f32 v[182:183], v[158:159], v[178:179], v[182:183] op_sel_hi:[0,1,1]
	v_pk_mul_f32 v[178:179], v[10:11], v[174:175]
	v_pk_mul_f32 v[174:175], v[160:161], v[174:175]
	global_load_dwordx4 v[140:143], v[0:1], off sc1
	global_load_dwordx4 v[136:139], v[0:1], off offset:512 sc1
	global_load_dwordx4 v[124:127], v[0:1], off offset:1024 sc1
	global_load_dwordx4 v[120:123], v[0:1], off offset:1536 sc1
	global_load_dwordx4 v[116:119], v[0:1], off offset:2048 sc1
	global_load_dwordx4 v[112:115], v[0:1], off offset:2560 sc1
	global_load_dwordx4 v[108:111], v[0:1], off offset:3072 sc1
	global_load_dwordx4 v[104:107], v[0:1], off offset:3584 sc1
	v_lshlrev_b32_e32 v128, 16, v129
	v_and_b32_e32 v129, 0xffff0000, v129
	v_pk_fma_f32 v[178:179], v[160:161], v[182:183], v[178:179] neg_lo:[0,0,1] neg_hi:[0,0,1]
	v_pk_fma_f32 v[174:175], v[10:11], v[182:183], v[174:175]
	v_pk_fma_f32 v[182:183], v[144:145], v[132:133], 0 op_sel_hi:[0,1,0]
	v_pk_fma_f32 v[132:133], v[144:145], v[132:133], 0 op_sel:[1,0,0] op_sel_hi:[1,1,0]
	v_pk_fma_f32 v[182:183], v[146:147], v[128:129], v[182:183] op_sel_hi:[0,1,1]
	v_pk_fma_f32 v[128:129], v[146:147], v[128:129], v[132:133] op_sel:[1,0,0]
	v_lshlrev_b32_e32 v100, 16, v101
	v_and_b32_e32 v101, 0xffff0000, v101
	v_pk_fma_f32 v[132:133], v[148:149], v[100:101], v[182:183] op_sel_hi:[0,1,1]
	v_pk_fma_f32 v[100:101], v[148:149], v[100:101], v[128:129] op_sel:[1,0,0]
	v_lshlrev_b32_e32 v96, 16, v97
	v_and_b32_e32 v97, 0xffff0000, v97
	v_pk_fma_f32 v[128:129], v[150:151], v[96:97], v[132:133] op_sel_hi:[0,1,1]
	v_pk_fma_f32 v[96:97], v[150:151], v[96:97], v[100:101] op_sel:[1,0,0]
	v_lshlrev_b32_e32 v92, 16, v93
	v_and_b32_e32 v93, 0xffff0000, v93
	v_pk_fma_f32 v[100:101], v[152:153], v[92:93], v[128:129] op_sel_hi:[0,1,1]
	v_pk_fma_f32 v[92:93], v[152:153], v[92:93], v[96:97] op_sel:[1,0,0]
	v_lshlrev_b32_e32 v88, 16, v89
	v_and_b32_e32 v89, 0xffff0000, v89
	v_pk_fma_f32 v[96:97], v[154:155], v[88:89], v[100:101] op_sel_hi:[0,1,1]
	v_pk_fma_f32 v[88:89], v[154:155], v[88:89], v[92:93] op_sel:[1,0,0]
	v_lshlrev_b32_e32 v84, 16, v85
	v_and_b32_e32 v85, 0xffff0000, v85
	v_pk_fma_f32 v[92:93], v[156:157], v[84:85], v[96:97] op_sel_hi:[0,1,1]
	v_pk_fma_f32 v[84:85], v[156:157], v[84:85], v[88:89] op_sel:[1,0,0]
	v_lshlrev_b32_e32 v80, 16, v81
	v_and_b32_e32 v81, 0xffff0000, v81
	v_pk_fma_f32 v[88:89], v[158:159], v[80:81], v[92:93] op_sel_hi:[0,1,1]
	v_pk_fma_f32 v[80:81], v[158:159], v[80:81], v[84:85] op_sel:[1,0,0]
	v_lshlrev_b32_e32 v176, 16, v134
	v_and_b32_e32 v177, 0xffff0000, v134
	v_pk_mul_f32 v[84:85], v[14:15], v[80:81]
	v_pk_mul_f32 v[80:81], v[8:9], v[80:81]
	v_lshlrev_b32_e32 v180, 16, v130
	v_and_b32_e32 v181, 0xffff0000, v130
	v_pk_fma_f32 v[84:85], v[8:9], v[88:89], v[84:85] neg_lo:[0,0,1] neg_hi:[0,0,1]
	v_pk_fma_f32 v[88:89], v[14:15], v[88:89], v[80:81]
	v_pk_fma_f32 v[80:81], v[144:145], v[176:177], 0 op_sel_hi:[0,1,0]
	v_pk_fma_f32 v[92:93], v[144:145], v[176:177], 0 op_sel:[1,0,0] op_sel_hi:[1,1,0]
	v_pk_fma_f32 v[80:81], v[146:147], v[180:181], v[80:81] op_sel_hi:[0,1,1]
	v_pk_fma_f32 v[92:93], v[146:147], v[180:181], v[92:93] op_sel:[1,0,0]
	v_lshlrev_b32_e32 v96, 16, v102
	v_and_b32_e32 v97, 0xffff0000, v102
	v_pk_fma_f32 v[80:81], v[148:149], v[96:97], v[80:81] op_sel_hi:[0,1,1]
	v_pk_fma_f32 v[92:93], v[148:149], v[96:97], v[92:93] op_sel:[1,0,0]
	v_lshlrev_b32_e32 v96, 16, v98
	v_and_b32_e32 v97, 0xffff0000, v98
	v_pk_fma_f32 v[80:81], v[150:151], v[96:97], v[80:81] op_sel_hi:[0,1,1]
	v_pk_fma_f32 v[92:93], v[150:151], v[96:97], v[92:93] op_sel:[1,0,0]
	v_lshlrev_b32_e32 v96, 16, v94
	v_and_b32_e32 v97, 0xffff0000, v94
	v_pk_fma_f32 v[80:81], v[152:153], v[96:97], v[80:81] op_sel_hi:[0,1,1]
	v_pk_fma_f32 v[92:93], v[152:153], v[96:97], v[92:93] op_sel:[1,0,0]
	v_lshlrev_b32_e32 v96, 16, v90
	v_and_b32_e32 v97, 0xffff0000, v90
	v_pk_fma_f32 v[80:81], v[154:155], v[96:97], v[80:81] op_sel_hi:[0,1,1]
	v_pk_fma_f32 v[92:93], v[154:155], v[96:97], v[92:93] op_sel:[1,0,0]
	v_lshlrev_b32_e32 v96, 16, v86
	v_and_b32_e32 v97, 0xffff0000, v86
	v_pk_fma_f32 v[80:81], v[156:157], v[96:97], v[80:81] op_sel_hi:[0,1,1]
	v_pk_fma_f32 v[92:93], v[156:157], v[96:97], v[92:93] op_sel:[1,0,0]
	v_lshlrev_b32_e32 v96, 16, v82
	v_and_b32_e32 v97, 0xffff0000, v82
	v_pk_fma_f32 v[92:93], v[158:159], v[96:97], v[92:93] op_sel:[1,0,0]
	v_lshlrev_b32_e32 v134, 16, v135
	v_and_b32_e32 v135, 0xffff0000, v135
	v_pk_fma_f32 v[80:81], v[158:159], v[96:97], v[80:81] op_sel_hi:[0,1,1]
	v_pk_mul_f32 v[96:97], v[6:7], v[92:93]
	v_pk_mul_f32 v[92:93], v[12:13], v[92:93]
	v_lshlrev_b32_e32 v130, 16, v131
	v_and_b32_e32 v131, 0xffff0000, v131
	v_pk_fma_f32 v[96:97], v[12:13], v[80:81], v[96:97] neg_lo:[0,0,1] neg_hi:[0,0,1]
	v_pk_fma_f32 v[92:93], v[6:7], v[80:81], v[92:93]
	v_pk_fma_f32 v[80:81], v[144:145], v[134:135], 0 op_sel_hi:[0,1,0]
	v_pk_fma_f32 v[100:101], v[144:145], v[134:135], 0 op_sel:[1,0,0] op_sel_hi:[1,1,0]
	v_pk_fma_f32 v[80:81], v[146:147], v[130:131], v[80:81] op_sel_hi:[0,1,1]
	v_pk_fma_f32 v[100:101], v[146:147], v[130:131], v[100:101] op_sel:[1,0,0]
	v_lshlrev_b32_e32 v102, 16, v103
	v_and_b32_e32 v103, 0xffff0000, v103
	v_pk_fma_f32 v[80:81], v[148:149], v[102:103], v[80:81] op_sel_hi:[0,1,1]
	v_pk_fma_f32 v[100:101], v[148:149], v[102:103], v[100:101] op_sel:[1,0,0]
	v_lshlrev_b32_e32 v98, 16, v99
	v_and_b32_e32 v99, 0xffff0000, v99
	v_pk_fma_f32 v[80:81], v[150:151], v[98:99], v[80:81] op_sel_hi:[0,1,1]
	v_pk_fma_f32 v[98:99], v[150:151], v[98:99], v[100:101] op_sel:[1,0,0]
	v_lshlrev_b32_e32 v94, 16, v95
	v_and_b32_e32 v95, 0xffff0000, v95
	v_pk_fma_f32 v[80:81], v[152:153], v[94:95], v[80:81] op_sel_hi:[0,1,1]
	v_pk_fma_f32 v[94:95], v[152:153], v[94:95], v[98:99] op_sel:[1,0,0]
	v_lshlrev_b32_e32 v90, 16, v91
	v_and_b32_e32 v91, 0xffff0000, v91
	v_pk_fma_f32 v[80:81], v[154:155], v[90:91], v[80:81] op_sel_hi:[0,1,1]
	v_pk_fma_f32 v[90:91], v[154:155], v[90:91], v[94:95] op_sel:[1,0,0]
	v_lshlrev_b32_e32 v86, 16, v87
	v_and_b32_e32 v87, 0xffff0000, v87
	v_pk_fma_f32 v[80:81], v[156:157], v[86:87], v[80:81] op_sel_hi:[0,1,1]
	v_pk_fma_f32 v[86:87], v[156:157], v[86:87], v[90:91] op_sel:[1,0,0]
	v_lshlrev_b32_e32 v82, 16, v83
	v_and_b32_e32 v83, 0xffff0000, v83
	v_readlane_b32 s0, v253, 49
	v_pk_fma_f32 v[80:81], v[158:159], v[82:83], v[80:81] op_sel_hi:[0,1,1]
	v_pk_fma_f32 v[82:83], v[158:159], v[82:83], v[86:87] op_sel:[1,0,0]
	v_or_b32_e32 v0, s0, v172
	v_mov_b32_e32 v1, v193
	v_pk_mul_f32 v[86:87], v[2:3], v[82:83]
	v_lshlrev_b64 v[40:41], 12, v[0:1]
	v_pk_fma_f32 v[86:87], v[4:5], v[80:81], v[86:87] neg_lo:[0,0,1] neg_hi:[0,0,1]
	v_pk_mul_f32 v[82:83], v[4:5], v[82:83]
	v_mul_lo_u32 v1, v166, s6
	v_lshl_add_u64 v[40:41], v[162:163], 0, v[40:41]
	v_pk_fma_f32 v[90:91], v[2:3], v[80:81], v[82:83]
	v_cvt_pk_bf16_f32 v80, v178, v179
	v_cvt_pk_bf16_f32 v81, v84, v85
	v_cvt_pk_bf16_f32 v82, v96, v97
	v_cvt_pk_bf16_f32 v83, v86, v87
	v_add3_u32 v1, 0, v1, v192
	global_load_dwordx4 v[76:79], v[40:41], off sc1
	global_load_dwordx4 v[72:75], v[40:41], off offset:512 sc1
	global_load_dwordx4 v[60:63], v[40:41], off offset:1024 sc1
	global_load_dwordx4 v[56:59], v[40:41], off offset:1536 sc1
	global_load_dwordx4 v[52:55], v[40:41], off offset:2048 sc1
	global_load_dwordx4 v[48:51], v[40:41], off offset:2560 sc1
	global_load_dwordx4 v[44:47], v[40:41], off offset:3072 sc1
	s_nop 0
	global_load_dwordx4 v[40:43], v[40:41], off offset:3584 sc1
	ds_write_b128 v1, v[80:83]
	v_cvt_pk_bf16_f32 v80, v174, v175
	v_cvt_pk_bf16_f32 v81, v88, v89
	v_cvt_pk_bf16_f32 v82, v92, v93
	v_cvt_pk_bf16_f32 v83, v90, v91
	ds_write_b128 v1, v[80:83] offset:512
	v_lshlrev_b32_e32 v80, 16, v68
	v_and_b32_e32 v81, 0xffff0000, v68
	v_lshlrev_b32_e32 v84, 16, v64
	v_and_b32_e32 v85, 0xffff0000, v64
	v_pk_fma_f32 v[88:89], v[144:145], v[80:81], 0 op_sel_hi:[0,1,0]
	v_pk_fma_f32 v[80:81], v[144:145], v[80:81], 0 op_sel:[1,0,0] op_sel_hi:[1,1,0]
	v_pk_fma_f32 v[88:89], v[146:147], v[84:85], v[88:89] op_sel_hi:[0,1,1]
	v_pk_fma_f32 v[80:81], v[146:147], v[84:85], v[80:81] op_sel:[1,0,0]
	v_lshlrev_b32_e32 v84, 16, v36
	v_and_b32_e32 v85, 0xffff0000, v36
	v_pk_fma_f32 v[88:89], v[148:149], v[84:85], v[88:89] op_sel_hi:[0,1,1]
	v_pk_fma_f32 v[80:81], v[148:149], v[84:85], v[80:81] op_sel:[1,0,0]
	v_lshlrev_b32_e32 v84, 16, v32
	v_and_b32_e32 v85, 0xffff0000, v32
	v_pk_fma_f32 v[88:89], v[150:151], v[84:85], v[88:89] op_sel_hi:[0,1,1]
	v_pk_fma_f32 v[80:81], v[150:151], v[84:85], v[80:81] op_sel:[1,0,0]
	v_lshlrev_b32_e32 v84, 16, v28
	v_and_b32_e32 v85, 0xffff0000, v28
	v_pk_fma_f32 v[88:89], v[152:153], v[84:85], v[88:89] op_sel_hi:[0,1,1]
	v_pk_fma_f32 v[80:81], v[152:153], v[84:85], v[80:81] op_sel:[1,0,0]
	v_lshlrev_b32_e32 v84, 16, v24
	v_and_b32_e32 v85, 0xffff0000, v24
	v_pk_fma_f32 v[88:89], v[154:155], v[84:85], v[88:89] op_sel_hi:[0,1,1]
	v_pk_fma_f32 v[80:81], v[154:155], v[84:85], v[80:81] op_sel:[1,0,0]
	v_lshlrev_b32_e32 v84, 16, v20
	v_and_b32_e32 v85, 0xffff0000, v20
	v_pk_fma_f32 v[88:89], v[156:157], v[84:85], v[88:89] op_sel_hi:[0,1,1]
	v_pk_fma_f32 v[80:81], v[156:157], v[84:85], v[80:81] op_sel:[1,0,0]
	v_lshlrev_b32_e32 v84, 16, v16
	v_and_b32_e32 v85, 0xffff0000, v16
	v_pk_fma_f32 v[80:81], v[158:159], v[84:85], v[80:81] op_sel:[1,0,0]
	v_lshlrev_b32_e32 v68, 16, v69
	v_and_b32_e32 v69, 0xffff0000, v69
	v_pk_fma_f32 v[88:89], v[158:159], v[84:85], v[88:89] op_sel_hi:[0,1,1]
	v_pk_mul_f32 v[84:85], v[10:11], v[80:81]
	v_pk_mul_f32 v[80:81], v[160:161], v[80:81]
	v_lshlrev_b32_e32 v64, 16, v65
	v_and_b32_e32 v65, 0xffff0000, v65
	v_pk_fma_f32 v[84:85], v[160:161], v[88:89], v[84:85] neg_lo:[0,0,1] neg_hi:[0,0,1]
	v_pk_fma_f32 v[80:81], v[10:11], v[88:89], v[80:81]
	v_pk_fma_f32 v[88:89], v[144:145], v[68:69], 0 op_sel_hi:[0,1,0]
	v_pk_fma_f32 v[68:69], v[144:145], v[68:69], 0 op_sel:[1,0,0] op_sel_hi:[1,1,0]
	v_pk_fma_f32 v[88:89], v[146:147], v[64:65], v[88:89] op_sel_hi:[0,1,1]
	v_pk_fma_f32 v[64:65], v[146:147], v[64:65], v[68:69] op_sel:[1,0,0]
	v_lshlrev_b32_e32 v36, 16, v37
	v_and_b32_e32 v37, 0xffff0000, v37
	v_pk_fma_f32 v[68:69], v[148:149], v[36:37], v[88:89] op_sel_hi:[0,1,1]
	v_pk_fma_f32 v[36:37], v[148:149], v[36:37], v[64:65] op_sel:[1,0,0]
	v_lshlrev_b32_e32 v32, 16, v33
	v_and_b32_e32 v33, 0xffff0000, v33
	v_pk_fma_f32 v[64:65], v[150:151], v[32:33], v[68:69] op_sel_hi:[0,1,1]
	v_pk_fma_f32 v[32:33], v[150:151], v[32:33], v[36:37] op_sel:[1,0,0]
	v_lshlrev_b32_e32 v28, 16, v29
	v_and_b32_e32 v29, 0xffff0000, v29
	v_pk_fma_f32 v[36:37], v[152:153], v[28:29], v[64:65] op_sel_hi:[0,1,1]
	v_pk_fma_f32 v[28:29], v[152:153], v[28:29], v[32:33] op_sel:[1,0,0]
	v_lshlrev_b32_e32 v24, 16, v25
	v_and_b32_e32 v25, 0xffff0000, v25
	v_pk_fma_f32 v[32:33], v[154:155], v[24:25], v[36:37] op_sel_hi:[0,1,1]
	v_pk_fma_f32 v[24:25], v[154:155], v[24:25], v[28:29] op_sel:[1,0,0]
	v_lshlrev_b32_e32 v20, 16, v21
	v_and_b32_e32 v21, 0xffff0000, v21
	v_pk_fma_f32 v[28:29], v[156:157], v[20:21], v[32:33] op_sel_hi:[0,1,1]
	v_pk_fma_f32 v[20:21], v[156:157], v[20:21], v[24:25] op_sel:[1,0,0]
	v_lshlrev_b32_e32 v16, 16, v17
	v_and_b32_e32 v17, 0xffff0000, v17
	v_pk_fma_f32 v[24:25], v[158:159], v[16:17], v[28:29] op_sel_hi:[0,1,1]
	v_pk_fma_f32 v[16:17], v[158:159], v[16:17], v[20:21] op_sel:[1,0,0]
	v_lshlrev_b32_e32 v82, 16, v70
	v_and_b32_e32 v83, 0xffff0000, v70
	v_pk_mul_f32 v[20:21], v[14:15], v[16:17]
	v_pk_mul_f32 v[16:17], v[8:9], v[16:17]
	v_lshlrev_b32_e32 v86, 16, v66
	v_and_b32_e32 v87, 0xffff0000, v66
	v_pk_fma_f32 v[20:21], v[8:9], v[24:25], v[20:21] neg_lo:[0,0,1] neg_hi:[0,0,1]
	v_pk_fma_f32 v[24:25], v[14:15], v[24:25], v[16:17]
	v_pk_fma_f32 v[16:17], v[144:145], v[82:83], 0 op_sel_hi:[0,1,0]
	v_pk_fma_f32 v[28:29], v[144:145], v[82:83], 0 op_sel:[1,0,0] op_sel_hi:[1,1,0]
	v_pk_fma_f32 v[16:17], v[146:147], v[86:87], v[16:17] op_sel_hi:[0,1,1]
	v_pk_fma_f32 v[28:29], v[146:147], v[86:87], v[28:29] op_sel:[1,0,0]
	v_lshlrev_b32_e32 v32, 16, v38
	v_and_b32_e32 v33, 0xffff0000, v38
	v_pk_fma_f32 v[16:17], v[148:149], v[32:33], v[16:17] op_sel_hi:[0,1,1]
	v_pk_fma_f32 v[28:29], v[148:149], v[32:33], v[28:29] op_sel:[1,0,0]
	v_lshlrev_b32_e32 v32, 16, v34
	v_and_b32_e32 v33, 0xffff0000, v34
	v_pk_fma_f32 v[16:17], v[150:151], v[32:33], v[16:17] op_sel_hi:[0,1,1]
	v_pk_fma_f32 v[28:29], v[150:151], v[32:33], v[28:29] op_sel:[1,0,0]
	v_lshlrev_b32_e32 v32, 16, v30
	v_and_b32_e32 v33, 0xffff0000, v30
	v_pk_fma_f32 v[16:17], v[152:153], v[32:33], v[16:17] op_sel_hi:[0,1,1]
	v_pk_fma_f32 v[28:29], v[152:153], v[32:33], v[28:29] op_sel:[1,0,0]
	v_lshlrev_b32_e32 v32, 16, v26
	v_and_b32_e32 v33, 0xffff0000, v26
	v_pk_fma_f32 v[16:17], v[154:155], v[32:33], v[16:17] op_sel_hi:[0,1,1]
	v_pk_fma_f32 v[28:29], v[154:155], v[32:33], v[28:29] op_sel:[1,0,0]
	v_lshlrev_b32_e32 v32, 16, v22
	v_and_b32_e32 v33, 0xffff0000, v22
	v_pk_fma_f32 v[16:17], v[156:157], v[32:33], v[16:17] op_sel_hi:[0,1,1]
	v_pk_fma_f32 v[28:29], v[156:157], v[32:33], v[28:29] op_sel:[1,0,0]
	v_lshlrev_b32_e32 v32, 16, v18
	v_and_b32_e32 v33, 0xffff0000, v18
	v_pk_fma_f32 v[28:29], v[158:159], v[32:33], v[28:29] op_sel:[1,0,0]
	v_lshlrev_b32_e32 v70, 16, v71
	v_and_b32_e32 v71, 0xffff0000, v71
	v_pk_fma_f32 v[16:17], v[158:159], v[32:33], v[16:17] op_sel_hi:[0,1,1]
	v_pk_mul_f32 v[32:33], v[6:7], v[28:29]
	v_pk_mul_f32 v[28:29], v[12:13], v[28:29]
	v_lshlrev_b32_e32 v66, 16, v67
	v_and_b32_e32 v67, 0xffff0000, v67
	v_pk_fma_f32 v[32:33], v[12:13], v[16:17], v[32:33] neg_lo:[0,0,1] neg_hi:[0,0,1]
	v_pk_fma_f32 v[28:29], v[6:7], v[16:17], v[28:29]
	v_pk_fma_f32 v[16:17], v[144:145], v[70:71], 0 op_sel_hi:[0,1,0]
	v_pk_fma_f32 v[36:37], v[144:145], v[70:71], 0 op_sel:[1,0,0] op_sel_hi:[1,1,0]
	v_pk_fma_f32 v[16:17], v[146:147], v[66:67], v[16:17] op_sel_hi:[0,1,1]
	v_pk_fma_f32 v[36:37], v[146:147], v[66:67], v[36:37] op_sel:[1,0,0]
	v_lshlrev_b32_e32 v38, 16, v39
	v_and_b32_e32 v39, 0xffff0000, v39
	v_pk_fma_f32 v[16:17], v[148:149], v[38:39], v[16:17] op_sel_hi:[0,1,1]
	v_pk_fma_f32 v[36:37], v[148:149], v[38:39], v[36:37] op_sel:[1,0,0]
	v_lshlrev_b32_e32 v34, 16, v35
	v_and_b32_e32 v35, 0xffff0000, v35
	v_pk_fma_f32 v[16:17], v[150:151], v[34:35], v[16:17] op_sel_hi:[0,1,1]
	v_pk_fma_f32 v[34:35], v[150:151], v[34:35], v[36:37] op_sel:[1,0,0]
	v_lshlrev_b32_e32 v30, 16, v31
	v_and_b32_e32 v31, 0xffff0000, v31
	v_pk_fma_f32 v[16:17], v[152:153], v[30:31], v[16:17] op_sel_hi:[0,1,1]
	v_pk_fma_f32 v[30:31], v[152:153], v[30:31], v[34:35] op_sel:[1,0,0]
	v_lshlrev_b32_e32 v26, 16, v27
	v_and_b32_e32 v27, 0xffff0000, v27
	v_pk_fma_f32 v[16:17], v[154:155], v[26:27], v[16:17] op_sel_hi:[0,1,1]
	v_pk_fma_f32 v[26:27], v[154:155], v[26:27], v[30:31] op_sel:[1,0,0]
	v_lshlrev_b32_e32 v22, 16, v23
	v_and_b32_e32 v23, 0xffff0000, v23
	v_pk_fma_f32 v[16:17], v[156:157], v[22:23], v[16:17] op_sel_hi:[0,1,1]
	v_pk_fma_f32 v[22:23], v[156:157], v[22:23], v[26:27] op_sel:[1,0,0]
	v_lshlrev_b32_e32 v18, 16, v19
	v_and_b32_e32 v19, 0xffff0000, v19
	v_pk_fma_f32 v[16:17], v[158:159], v[18:19], v[16:17] op_sel_hi:[0,1,1]
	v_pk_fma_f32 v[18:19], v[158:159], v[18:19], v[22:23] op_sel:[1,0,0]
	v_mul_lo_u32 v1, v164, s6
	v_pk_mul_f32 v[22:23], v[2:3], v[18:19]
	v_pk_mul_f32 v[18:19], v[4:5], v[18:19]
	v_pk_fma_f32 v[22:23], v[4:5], v[16:17], v[22:23] neg_lo:[0,0,1] neg_hi:[0,0,1]
	v_pk_fma_f32 v[26:27], v[2:3], v[16:17], v[18:19]
	v_cvt_pk_bf16_f32 v16, v84, v85
	v_cvt_pk_bf16_f32 v17, v20, v21
	v_cvt_pk_bf16_f32 v18, v32, v33
	v_cvt_pk_bf16_f32 v19, v22, v23
	v_add3_u32 v1, 0, v1, v192
	v_readlane_b32 s0, v253, 50
	ds_write_b128 v1, v[16:19]
	v_cvt_pk_bf16_f32 v16, v80, v81
	v_cvt_pk_bf16_f32 v17, v24, v25
	v_cvt_pk_bf16_f32 v18, v28, v29
	v_cvt_pk_bf16_f32 v19, v26, v27
	v_or_b32_e32 v166, s0, v172
	ds_write_b128 v1, v[16:19] offset:512
	v_lshlrev_b64 v[16:17], 12, v[166:167]
	v_readlane_b32 s0, v253, 52
	v_lshl_add_u64 v[16:17], v[162:163], 0, v[16:17]
	global_load_dwordx4 v[132:135], v[16:17], off sc1
	global_load_dwordx4 v[128:131], v[16:17], off offset:512 sc1
	global_load_dwordx4 v[100:103], v[16:17], off offset:1024 sc1
	global_load_dwordx4 v[96:99], v[16:17], off offset:1536 sc1
	global_load_dwordx4 v[92:95], v[16:17], off offset:2048 sc1
	global_load_dwordx4 v[88:91], v[16:17], off offset:2560 sc1
	global_load_dwordx4 v[84:87], v[16:17], off offset:3072 sc1
	global_load_dwordx4 v[80:83], v[16:17], off offset:3584 sc1
	v_or_b32_e32 v164, s0, v172
	v_lshlrev_b64 v[16:17], 12, v[164:165]
	v_lshl_add_u64 v[16:17], v[162:163], 0, v[16:17]
	s_waitcnt vmcnt(23)
	v_lshlrev_b32_e32 v162, 16, v140
	v_and_b32_e32 v163, 0xffff0000, v140
	s_waitcnt vmcnt(22)
	v_lshlrev_b32_e32 v174, 16, v136
	v_and_b32_e32 v175, 0xffff0000, v136
	v_pk_fma_f32 v[178:179], v[144:145], v[162:163], 0 op_sel_hi:[0,1,0]
	v_pk_fma_f32 v[162:163], v[144:145], v[162:163], 0 op_sel:[1,0,0] op_sel_hi:[1,1,0]
	v_pk_fma_f32 v[178:179], v[146:147], v[174:175], v[178:179] op_sel_hi:[0,1,1]
	v_pk_fma_f32 v[162:163], v[146:147], v[174:175], v[162:163] op_sel:[1,0,0]
	s_waitcnt vmcnt(21)
	v_lshlrev_b32_e32 v174, 16, v124
	v_and_b32_e32 v175, 0xffff0000, v124
	v_pk_fma_f32 v[178:179], v[148:149], v[174:175], v[178:179] op_sel_hi:[0,1,1]
	v_pk_fma_f32 v[162:163], v[148:149], v[174:175], v[162:163] op_sel:[1,0,0]
	s_waitcnt vmcnt(20)
	v_lshlrev_b32_e32 v174, 16, v120
	v_and_b32_e32 v175, 0xffff0000, v120
	v_pk_fma_f32 v[178:179], v[150:151], v[174:175], v[178:179] op_sel_hi:[0,1,1]
	v_pk_fma_f32 v[162:163], v[150:151], v[174:175], v[162:163] op_sel:[1,0,0]
	s_waitcnt vmcnt(19)
	v_lshlrev_b32_e32 v174, 16, v116
	v_and_b32_e32 v175, 0xffff0000, v116
	v_pk_fma_f32 v[178:179], v[152:153], v[174:175], v[178:179] op_sel_hi:[0,1,1]
	v_pk_fma_f32 v[162:163], v[152:153], v[174:175], v[162:163] op_sel:[1,0,0]
	s_waitcnt vmcnt(18)
	v_lshlrev_b32_e32 v174, 16, v112
	v_and_b32_e32 v175, 0xffff0000, v112
	v_pk_fma_f32 v[178:179], v[154:155], v[174:175], v[178:179] op_sel_hi:[0,1,1]
	v_pk_fma_f32 v[162:163], v[154:155], v[174:175], v[162:163] op_sel:[1,0,0]
	s_waitcnt vmcnt(17)
	v_lshlrev_b32_e32 v174, 16, v108
	v_and_b32_e32 v175, 0xffff0000, v108
	v_pk_fma_f32 v[178:179], v[156:157], v[174:175], v[178:179] op_sel_hi:[0,1,1]
	v_pk_fma_f32 v[162:163], v[156:157], v[174:175], v[162:163] op_sel:[1,0,0]
	s_waitcnt vmcnt(16)
	v_lshlrev_b32_e32 v174, 16, v104
	v_and_b32_e32 v175, 0xffff0000, v104
	v_pk_fma_f32 v[162:163], v[158:159], v[174:175], v[162:163] op_sel:[1,0,0]
	v_lshlrev_b32_e32 v140, 16, v141
	v_and_b32_e32 v141, 0xffff0000, v141
	v_pk_fma_f32 v[178:179], v[158:159], v[174:175], v[178:179] op_sel_hi:[0,1,1]
	v_pk_mul_f32 v[174:175], v[10:11], v[162:163]
	v_pk_mul_f32 v[162:163], v[160:161], v[162:163]
	v_lshlrev_b32_e32 v136, 16, v137
	v_and_b32_e32 v137, 0xffff0000, v137
	v_pk_fma_f32 v[174:175], v[160:161], v[178:179], v[174:175] neg_lo:[0,0,1] neg_hi:[0,0,1]
	v_pk_fma_f32 v[162:163], v[10:11], v[178:179], v[162:163]
	v_pk_fma_f32 v[178:179], v[144:145], v[140:141], 0 op_sel_hi:[0,1,0]
	v_pk_fma_f32 v[140:141], v[144:145], v[140:141], 0 op_sel:[1,0,0] op_sel_hi:[1,1,0]
	v_pk_fma_f32 v[178:179], v[146:147], v[136:137], v[178:179] op_sel_hi:[0,1,1]
	v_pk_fma_f32 v[136:137], v[146:147], v[136:137], v[140:141] op_sel:[1,0,0]
	v_lshlrev_b32_e32 v124, 16, v125
	v_and_b32_e32 v125, 0xffff0000, v125
	v_pk_fma_f32 v[140:141], v[148:149], v[124:125], v[178:179] op_sel_hi:[0,1,1]
	v_pk_fma_f32 v[124:125], v[148:149], v[124:125], v[136:137] op_sel:[1,0,0]
	v_lshlrev_b32_e32 v120, 16, v121
	v_and_b32_e32 v121, 0xffff0000, v121
	v_pk_fma_f32 v[136:137], v[150:151], v[120:121], v[140:141] op_sel_hi:[0,1,1]
	v_pk_fma_f32 v[120:121], v[150:151], v[120:121], v[124:125] op_sel:[1,0,0]
	v_lshlrev_b32_e32 v116, 16, v117
	v_and_b32_e32 v117, 0xffff0000, v117
	v_pk_fma_f32 v[124:125], v[152:153], v[116:117], v[136:137] op_sel_hi:[0,1,1]
	v_pk_fma_f32 v[116:117], v[152:153], v[116:117], v[120:121] op_sel:[1,0,0]
	v_lshlrev_b32_e32 v112, 16, v113
	v_and_b32_e32 v113, 0xffff0000, v113
	v_pk_fma_f32 v[120:121], v[154:155], v[112:113], v[124:125] op_sel_hi:[0,1,1]
	v_pk_fma_f32 v[112:113], v[154:155], v[112:113], v[116:117] op_sel:[1,0,0]
	v_lshlrev_b32_e32 v108, 16, v109
	v_and_b32_e32 v109, 0xffff0000, v109
	v_pk_fma_f32 v[116:117], v[156:157], v[108:109], v[120:121] op_sel_hi:[0,1,1]
	v_pk_fma_f32 v[108:109], v[156:157], v[108:109], v[112:113] op_sel:[1,0,0]
	v_lshlrev_b32_e32 v104, 16, v105
	v_and_b32_e32 v105, 0xffff0000, v105
	v_pk_fma_f32 v[112:113], v[158:159], v[104:105], v[116:117] op_sel_hi:[0,1,1]
	v_pk_fma_f32 v[104:105], v[158:159], v[104:105], v[108:109] op_sel:[1,0,0]
	v_lshlrev_b32_e32 v172, 16, v142
	v_and_b32_e32 v173, 0xffff0000, v142
	v_pk_mul_f32 v[108:109], v[14:15], v[104:105]
	v_pk_mul_f32 v[104:105], v[8:9], v[104:105]
	v_lshlrev_b32_e32 v176, 16, v138
	v_and_b32_e32 v177, 0xffff0000, v138
	v_pk_fma_f32 v[108:109], v[8:9], v[112:113], v[108:109] neg_lo:[0,0,1] neg_hi:[0,0,1]
	v_pk_fma_f32 v[112:113], v[14:15], v[112:113], v[104:105]
	v_pk_fma_f32 v[104:105], v[144:145], v[172:173], 0 op_sel_hi:[0,1,0]
	v_pk_fma_f32 v[116:117], v[144:145], v[172:173], 0 op_sel:[1,0,0] op_sel_hi:[1,1,0]
	v_pk_fma_f32 v[104:105], v[146:147], v[176:177], v[104:105] op_sel_hi:[0,1,1]
	v_pk_fma_f32 v[116:117], v[146:147], v[176:177], v[116:117] op_sel:[1,0,0]
	v_lshlrev_b32_e32 v120, 16, v126
	v_and_b32_e32 v121, 0xffff0000, v126
	v_pk_fma_f32 v[104:105], v[148:149], v[120:121], v[104:105] op_sel_hi:[0,1,1]
	v_pk_fma_f32 v[116:117], v[148:149], v[120:121], v[116:117] op_sel:[1,0,0]
	v_lshlrev_b32_e32 v120, 16, v122
	v_and_b32_e32 v121, 0xffff0000, v122
	v_pk_fma_f32 v[104:105], v[150:151], v[120:121], v[104:105] op_sel_hi:[0,1,1]
	v_pk_fma_f32 v[116:117], v[150:151], v[120:121], v[116:117] op_sel:[1,0,0]
	v_lshlrev_b32_e32 v120, 16, v118
	v_and_b32_e32 v121, 0xffff0000, v118
	v_pk_fma_f32 v[104:105], v[152:153], v[120:121], v[104:105] op_sel_hi:[0,1,1]
	v_pk_fma_f32 v[116:117], v[152:153], v[120:121], v[116:117] op_sel:[1,0,0]
	v_lshlrev_b32_e32 v120, 16, v114
	v_and_b32_e32 v121, 0xffff0000, v114
	v_pk_fma_f32 v[104:105], v[154:155], v[120:121], v[104:105] op_sel_hi:[0,1,1]
	v_pk_fma_f32 v[116:117], v[154:155], v[120:121], v[116:117] op_sel:[1,0,0]
	v_lshlrev_b32_e32 v120, 16, v110
	v_and_b32_e32 v121, 0xffff0000, v110
	v_pk_fma_f32 v[104:105], v[156:157], v[120:121], v[104:105] op_sel_hi:[0,1,1]
	v_pk_fma_f32 v[116:117], v[156:157], v[120:121], v[116:117] op_sel:[1,0,0]
	v_lshlrev_b32_e32 v120, 16, v106
	v_and_b32_e32 v121, 0xffff0000, v106
	v_pk_fma_f32 v[116:117], v[158:159], v[120:121], v[116:117] op_sel:[1,0,0]
	v_lshlrev_b32_e32 v142, 16, v143
	v_and_b32_e32 v143, 0xffff0000, v143
	v_pk_fma_f32 v[104:105], v[158:159], v[120:121], v[104:105] op_sel_hi:[0,1,1]
	v_pk_mul_f32 v[120:121], v[6:7], v[116:117]
	v_pk_mul_f32 v[116:117], v[12:13], v[116:117]
	v_lshlrev_b32_e32 v138, 16, v139
	v_and_b32_e32 v139, 0xffff0000, v139
	v_pk_fma_f32 v[120:121], v[12:13], v[104:105], v[120:121] neg_lo:[0,0,1] neg_hi:[0,0,1]
	v_pk_fma_f32 v[116:117], v[6:7], v[104:105], v[116:117]
	v_pk_fma_f32 v[104:105], v[144:145], v[142:143], 0 op_sel_hi:[0,1,0]
	v_pk_fma_f32 v[124:125], v[144:145], v[142:143], 0 op_sel:[1,0,0] op_sel_hi:[1,1,0]
	v_pk_fma_f32 v[104:105], v[146:147], v[138:139], v[104:105] op_sel_hi:[0,1,1]
	v_pk_fma_f32 v[124:125], v[146:147], v[138:139], v[124:125] op_sel:[1,0,0]
	v_lshlrev_b32_e32 v126, 16, v127
	v_and_b32_e32 v127, 0xffff0000, v127
	v_pk_fma_f32 v[104:105], v[148:149], v[126:127], v[104:105] op_sel_hi:[0,1,1]
	v_pk_fma_f32 v[124:125], v[148:149], v[126:127], v[124:125] op_sel:[1,0,0]
	v_lshlrev_b32_e32 v122, 16, v123
	v_and_b32_e32 v123, 0xffff0000, v123
	v_pk_fma_f32 v[104:105], v[150:151], v[122:123], v[104:105] op_sel_hi:[0,1,1]
	v_pk_fma_f32 v[122:123], v[150:151], v[122:123], v[124:125] op_sel:[1,0,0]
	v_lshlrev_b32_e32 v118, 16, v119
	v_and_b32_e32 v119, 0xffff0000, v119
	v_pk_fma_f32 v[104:105], v[152:153], v[118:119], v[104:105] op_sel_hi:[0,1,1]
	v_pk_fma_f32 v[118:119], v[152:153], v[118:119], v[122:123] op_sel:[1,0,0]
	v_lshlrev_b32_e32 v114, 16, v115
	v_and_b32_e32 v115, 0xffff0000, v115
	v_pk_fma_f32 v[104:105], v[154:155], v[114:115], v[104:105] op_sel_hi:[0,1,1]
	v_pk_fma_f32 v[114:115], v[154:155], v[114:115], v[118:119] op_sel:[1,0,0]
	v_lshlrev_b32_e32 v110, 16, v111
	v_and_b32_e32 v111, 0xffff0000, v111
	v_pk_fma_f32 v[104:105], v[156:157], v[110:111], v[104:105] op_sel_hi:[0,1,1]
	v_pk_fma_f32 v[110:111], v[156:157], v[110:111], v[114:115] op_sel:[1,0,0]
	v_lshlrev_b32_e32 v106, 16, v107
	v_and_b32_e32 v107, 0xffff0000, v107
	v_pk_fma_f32 v[104:105], v[158:159], v[106:107], v[104:105] op_sel_hi:[0,1,1]
	v_pk_fma_f32 v[106:107], v[158:159], v[106:107], v[110:111] op_sel:[1,0,0]
	v_mul_lo_u32 v1, v168, s6
	v_pk_mul_f32 v[110:111], v[2:3], v[106:107]
	v_pk_mul_f32 v[106:107], v[4:5], v[106:107]
	v_pk_fma_f32 v[110:111], v[4:5], v[104:105], v[110:111] neg_lo:[0,0,1] neg_hi:[0,0,1]
	v_pk_fma_f32 v[114:115], v[2:3], v[104:105], v[106:107]
	v_cvt_pk_bf16_f32 v104, v174, v175
	v_cvt_pk_bf16_f32 v105, v108, v109
	v_cvt_pk_bf16_f32 v106, v120, v121
	v_cvt_pk_bf16_f32 v107, v110, v111
	v_add3_u32 v1, 0, v1, v192
	global_load_dwordx4 v[68:71], v[16:17], off sc1
	global_load_dwordx4 v[64:67], v[16:17], off offset:512 sc1
	global_load_dwordx4 v[36:39], v[16:17], off offset:1024 sc1
	global_load_dwordx4 v[32:35], v[16:17], off offset:1536 sc1
	global_load_dwordx4 v[28:31], v[16:17], off offset:2048 sc1
	global_load_dwordx4 v[24:27], v[16:17], off offset:2560 sc1
	global_load_dwordx4 v[20:23], v[16:17], off offset:3072 sc1
	s_nop 0
	global_load_dwordx4 v[16:19], v[16:17], off offset:3584 sc1
	ds_write_b128 v1, v[104:107]
	v_cvt_pk_bf16_f32 v104, v162, v163
	v_cvt_pk_bf16_f32 v105, v112, v113
	v_cvt_pk_bf16_f32 v106, v116, v117
	v_cvt_pk_bf16_f32 v107, v114, v115
	ds_write_b128 v1, v[104:107] offset:512
	s_waitcnt vmcnt(23)
	v_lshlrev_b32_e32 v104, 16, v76
	v_and_b32_e32 v105, 0xffff0000, v76
	s_waitcnt vmcnt(22)
	v_lshlrev_b32_e32 v108, 16, v72
	v_and_b32_e32 v109, 0xffff0000, v72
	v_pk_fma_f32 v[112:113], v[144:145], v[104:105], 0 op_sel_hi:[0,1,0]
	v_pk_fma_f32 v[104:105], v[144:145], v[104:105], 0 op_sel:[1,0,0] op_sel_hi:[1,1,0]
	v_pk_fma_f32 v[112:113], v[146:147], v[108:109], v[112:113] op_sel_hi:[0,1,1]
	v_pk_fma_f32 v[104:105], v[146:147], v[108:109], v[104:105] op_sel:[1,0,0]
	s_waitcnt vmcnt(21)
	v_lshlrev_b32_e32 v108, 16, v60
	v_and_b32_e32 v109, 0xffff0000, v60
	v_pk_fma_f32 v[112:113], v[148:149], v[108:109], v[112:113] op_sel_hi:[0,1,1]
	v_pk_fma_f32 v[104:105], v[148:149], v[108:109], v[104:105] op_sel:[1,0,0]
	s_waitcnt vmcnt(20)
	v_lshlrev_b32_e32 v108, 16, v56
	v_and_b32_e32 v109, 0xffff0000, v56
	v_pk_fma_f32 v[112:113], v[150:151], v[108:109], v[112:113] op_sel_hi:[0,1,1]
	v_pk_fma_f32 v[104:105], v[150:151], v[108:109], v[104:105] op_sel:[1,0,0]
	s_waitcnt vmcnt(19)
	v_lshlrev_b32_e32 v108, 16, v52
	v_and_b32_e32 v109, 0xffff0000, v52
	v_pk_fma_f32 v[112:113], v[152:153], v[108:109], v[112:113] op_sel_hi:[0,1,1]
	v_pk_fma_f32 v[104:105], v[152:153], v[108:109], v[104:105] op_sel:[1,0,0]
	s_waitcnt vmcnt(18)
	v_lshlrev_b32_e32 v108, 16, v48
	v_and_b32_e32 v109, 0xffff0000, v48
	v_pk_fma_f32 v[112:113], v[154:155], v[108:109], v[112:113] op_sel_hi:[0,1,1]
	v_pk_fma_f32 v[104:105], v[154:155], v[108:109], v[104:105] op_sel:[1,0,0]
	s_waitcnt vmcnt(17)
	v_lshlrev_b32_e32 v108, 16, v44
	v_and_b32_e32 v109, 0xffff0000, v44
	v_pk_fma_f32 v[112:113], v[156:157], v[108:109], v[112:113] op_sel_hi:[0,1,1]
	v_pk_fma_f32 v[104:105], v[156:157], v[108:109], v[104:105] op_sel:[1,0,0]
	s_waitcnt vmcnt(16)
	v_lshlrev_b32_e32 v108, 16, v40
	v_and_b32_e32 v109, 0xffff0000, v40
	v_pk_fma_f32 v[104:105], v[158:159], v[108:109], v[104:105] op_sel:[1,0,0]
	v_lshlrev_b32_e32 v76, 16, v77
	v_and_b32_e32 v77, 0xffff0000, v77
	v_pk_fma_f32 v[112:113], v[158:159], v[108:109], v[112:113] op_sel_hi:[0,1,1]
	v_pk_mul_f32 v[108:109], v[10:11], v[104:105]
	v_pk_mul_f32 v[104:105], v[160:161], v[104:105]
	v_lshlrev_b32_e32 v72, 16, v73
	v_and_b32_e32 v73, 0xffff0000, v73
	v_pk_fma_f32 v[108:109], v[160:161], v[112:113], v[108:109] neg_lo:[0,0,1] neg_hi:[0,0,1]
	v_pk_fma_f32 v[104:105], v[10:11], v[112:113], v[104:105]
	v_pk_fma_f32 v[112:113], v[144:145], v[76:77], 0 op_sel_hi:[0,1,0]
	v_pk_fma_f32 v[76:77], v[144:145], v[76:77], 0 op_sel:[1,0,0] op_sel_hi:[1,1,0]
	v_pk_fma_f32 v[112:113], v[146:147], v[72:73], v[112:113] op_sel_hi:[0,1,1]
	v_pk_fma_f32 v[72:73], v[146:147], v[72:73], v[76:77] op_sel:[1,0,0]
	v_lshlrev_b32_e32 v60, 16, v61
	v_and_b32_e32 v61, 0xffff0000, v61
	v_pk_fma_f32 v[76:77], v[148:149], v[60:61], v[112:113] op_sel_hi:[0,1,1]
	v_pk_fma_f32 v[60:61], v[148:149], v[60:61], v[72:73] op_sel:[1,0,0]
	v_lshlrev_b32_e32 v56, 16, v57
	v_and_b32_e32 v57, 0xffff0000, v57
	v_pk_fma_f32 v[72:73], v[150:151], v[56:57], v[76:77] op_sel_hi:[0,1,1]
	v_pk_fma_f32 v[56:57], v[150:151], v[56:57], v[60:61] op_sel:[1,0,0]
	v_lshlrev_b32_e32 v52, 16, v53
	v_and_b32_e32 v53, 0xffff0000, v53
	v_pk_fma_f32 v[60:61], v[152:153], v[52:53], v[72:73] op_sel_hi:[0,1,1]
	v_pk_fma_f32 v[52:53], v[152:153], v[52:53], v[56:57] op_sel:[1,0,0]
	v_lshlrev_b32_e32 v48, 16, v49
	v_and_b32_e32 v49, 0xffff0000, v49
	v_pk_fma_f32 v[56:57], v[154:155], v[48:49], v[60:61] op_sel_hi:[0,1,1]
	v_pk_fma_f32 v[48:49], v[154:155], v[48:49], v[52:53] op_sel:[1,0,0]
	v_lshlrev_b32_e32 v44, 16, v45
	v_and_b32_e32 v45, 0xffff0000, v45
	v_pk_fma_f32 v[52:53], v[156:157], v[44:45], v[56:57] op_sel_hi:[0,1,1]
	v_pk_fma_f32 v[44:45], v[156:157], v[44:45], v[48:49] op_sel:[1,0,0]
	v_lshlrev_b32_e32 v40, 16, v41
	v_and_b32_e32 v41, 0xffff0000, v41
	v_pk_fma_f32 v[48:49], v[158:159], v[40:41], v[52:53] op_sel_hi:[0,1,1]
	v_pk_fma_f32 v[40:41], v[158:159], v[40:41], v[44:45] op_sel:[1,0,0]
	v_lshlrev_b32_e32 v106, 16, v78
	v_and_b32_e32 v107, 0xffff0000, v78
	v_pk_mul_f32 v[44:45], v[14:15], v[40:41]
	v_pk_mul_f32 v[40:41], v[8:9], v[40:41]
	v_lshlrev_b32_e32 v110, 16, v74
	v_and_b32_e32 v111, 0xffff0000, v74
	v_pk_fma_f32 v[44:45], v[8:9], v[48:49], v[44:45] neg_lo:[0,0,1] neg_hi:[0,0,1]
	v_pk_fma_f32 v[48:49], v[14:15], v[48:49], v[40:41]
	v_pk_fma_f32 v[40:41], v[144:145], v[106:107], 0 op_sel_hi:[0,1,0]
	v_pk_fma_f32 v[52:53], v[144:145], v[106:107], 0 op_sel:[1,0,0] op_sel_hi:[1,1,0]
	v_pk_fma_f32 v[40:41], v[146:147], v[110:111], v[40:41] op_sel_hi:[0,1,1]
	v_pk_fma_f32 v[52:53], v[146:147], v[110:111], v[52:53] op_sel:[1,0,0]
	v_lshlrev_b32_e32 v56, 16, v62
	v_and_b32_e32 v57, 0xffff0000, v62
	v_pk_fma_f32 v[40:41], v[148:149], v[56:57], v[40:41] op_sel_hi:[0,1,1]
	v_pk_fma_f32 v[52:53], v[148:149], v[56:57], v[52:53] op_sel:[1,0,0]
	v_lshlrev_b32_e32 v56, 16, v58
	v_and_b32_e32 v57, 0xffff0000, v58
	v_pk_fma_f32 v[40:41], v[150:151], v[56:57], v[40:41] op_sel_hi:[0,1,1]
	v_pk_fma_f32 v[52:53], v[150:151], v[56:57], v[52:53] op_sel:[1,0,0]
	v_lshlrev_b32_e32 v56, 16, v54
	v_and_b32_e32 v57, 0xffff0000, v54
	v_pk_fma_f32 v[40:41], v[152:153], v[56:57], v[40:41] op_sel_hi:[0,1,1]
	v_pk_fma_f32 v[52:53], v[152:153], v[56:57], v[52:53] op_sel:[1,0,0]
	v_lshlrev_b32_e32 v56, 16, v50
	v_and_b32_e32 v57, 0xffff0000, v50
	v_pk_fma_f32 v[40:41], v[154:155], v[56:57], v[40:41] op_sel_hi:[0,1,1]
	v_pk_fma_f32 v[52:53], v[154:155], v[56:57], v[52:53] op_sel:[1,0,0]
	v_lshlrev_b32_e32 v56, 16, v46
	v_and_b32_e32 v57, 0xffff0000, v46
	v_pk_fma_f32 v[40:41], v[156:157], v[56:57], v[40:41] op_sel_hi:[0,1,1]
	v_pk_fma_f32 v[52:53], v[156:157], v[56:57], v[52:53] op_sel:[1,0,0]
	v_lshlrev_b32_e32 v56, 16, v42
	v_and_b32_e32 v57, 0xffff0000, v42
	v_pk_fma_f32 v[52:53], v[158:159], v[56:57], v[52:53] op_sel:[1,0,0]
	v_lshlrev_b32_e32 v78, 16, v79
	v_and_b32_e32 v79, 0xffff0000, v79
	v_pk_fma_f32 v[40:41], v[158:159], v[56:57], v[40:41] op_sel_hi:[0,1,1]
	v_pk_mul_f32 v[56:57], v[6:7], v[52:53]
	v_pk_mul_f32 v[52:53], v[12:13], v[52:53]
	v_lshlrev_b32_e32 v74, 16, v75
	v_and_b32_e32 v75, 0xffff0000, v75
	v_pk_fma_f32 v[56:57], v[12:13], v[40:41], v[56:57] neg_lo:[0,0,1] neg_hi:[0,0,1]
	v_pk_fma_f32 v[52:53], v[6:7], v[40:41], v[52:53]
	v_pk_fma_f32 v[40:41], v[144:145], v[78:79], 0 op_sel_hi:[0,1,0]
	v_pk_fma_f32 v[60:61], v[144:145], v[78:79], 0 op_sel:[1,0,0] op_sel_hi:[1,1,0]
	v_pk_fma_f32 v[40:41], v[146:147], v[74:75], v[40:41] op_sel_hi:[0,1,1]
	v_pk_fma_f32 v[60:61], v[146:147], v[74:75], v[60:61] op_sel:[1,0,0]
	v_lshlrev_b32_e32 v62, 16, v63
	v_and_b32_e32 v63, 0xffff0000, v63
	v_pk_fma_f32 v[40:41], v[148:149], v[62:63], v[40:41] op_sel_hi:[0,1,1]
	v_pk_fma_f32 v[60:61], v[148:149], v[62:63], v[60:61] op_sel:[1,0,0]
	v_lshlrev_b32_e32 v58, 16, v59
	v_and_b32_e32 v59, 0xffff0000, v59
	v_pk_fma_f32 v[40:41], v[150:151], v[58:59], v[40:41] op_sel_hi:[0,1,1]
	v_pk_fma_f32 v[58:59], v[150:151], v[58:59], v[60:61] op_sel:[1,0,0]
	v_lshlrev_b32_e32 v54, 16, v55
	v_and_b32_e32 v55, 0xffff0000, v55
	v_pk_fma_f32 v[40:41], v[152:153], v[54:55], v[40:41] op_sel_hi:[0,1,1]
	v_pk_fma_f32 v[54:55], v[152:153], v[54:55], v[58:59] op_sel:[1,0,0]
	v_lshlrev_b32_e32 v50, 16, v51
	v_and_b32_e32 v51, 0xffff0000, v51
	v_pk_fma_f32 v[40:41], v[154:155], v[50:51], v[40:41] op_sel_hi:[0,1,1]
	v_pk_fma_f32 v[50:51], v[154:155], v[50:51], v[54:55] op_sel:[1,0,0]
	v_lshlrev_b32_e32 v46, 16, v47
	v_and_b32_e32 v47, 0xffff0000, v47
	v_pk_fma_f32 v[40:41], v[156:157], v[46:47], v[40:41] op_sel_hi:[0,1,1]
	v_pk_fma_f32 v[46:47], v[156:157], v[46:47], v[50:51] op_sel:[1,0,0]
	v_lshlrev_b32_e32 v42, 16, v43
	v_and_b32_e32 v43, 0xffff0000, v43
	v_pk_fma_f32 v[40:41], v[158:159], v[42:43], v[40:41] op_sel_hi:[0,1,1]
	v_pk_fma_f32 v[42:43], v[158:159], v[42:43], v[46:47] op_sel:[1,0,0]
	v_mul_lo_u32 v0, v0, s6
	v_pk_mul_f32 v[46:47], v[2:3], v[42:43]
	v_pk_mul_f32 v[42:43], v[4:5], v[42:43]
	v_pk_fma_f32 v[46:47], v[4:5], v[40:41], v[46:47] neg_lo:[0,0,1] neg_hi:[0,0,1]
	v_pk_fma_f32 v[50:51], v[2:3], v[40:41], v[42:43]
	v_cvt_pk_bf16_f32 v40, v108, v109
	v_cvt_pk_bf16_f32 v41, v44, v45
	v_cvt_pk_bf16_f32 v42, v56, v57
	v_cvt_pk_bf16_f32 v43, v46, v47
	v_add3_u32 v0, 0, v0, v192
	ds_write_b128 v0, v[40:43]
	v_cvt_pk_bf16_f32 v40, v104, v105
	v_cvt_pk_bf16_f32 v41, v48, v49
	v_cvt_pk_bf16_f32 v42, v52, v53
	v_cvt_pk_bf16_f32 v43, v50, v51
	ds_write_b128 v0, v[40:43] offset:512
	s_waitcnt vmcnt(15)
	v_lshlrev_b32_e32 v0, 16, v132
	v_and_b32_e32 v1, 0xffff0000, v132
	s_waitcnt vmcnt(14)
	v_lshlrev_b32_e32 v46, 16, v128
	v_and_b32_e32 v47, 0xffff0000, v128
	v_pk_fma_f32 v[54:55], v[144:145], v[0:1], 0 op_sel_hi:[0,1,0]
	v_pk_fma_f32 v[0:1], v[144:145], v[0:1], 0 op_sel:[1,0,0] op_sel_hi:[1,1,0]
	v_pk_fma_f32 v[54:55], v[146:147], v[46:47], v[54:55] op_sel_hi:[0,1,1]
	v_pk_fma_f32 v[0:1], v[146:147], v[46:47], v[0:1] op_sel:[1,0,0]
	s_waitcnt vmcnt(13)
	v_lshlrev_b32_e32 v46, 16, v100
	v_and_b32_e32 v47, 0xffff0000, v100
	v_pk_fma_f32 v[54:55], v[148:149], v[46:47], v[54:55] op_sel_hi:[0,1,1]
	v_pk_fma_f32 v[0:1], v[148:149], v[46:47], v[0:1] op_sel:[1,0,0]
	s_waitcnt vmcnt(12)
	v_lshlrev_b32_e32 v46, 16, v96
	v_and_b32_e32 v47, 0xffff0000, v96
	v_pk_fma_f32 v[54:55], v[150:151], v[46:47], v[54:55] op_sel_hi:[0,1,1]
	v_pk_fma_f32 v[0:1], v[150:151], v[46:47], v[0:1] op_sel:[1,0,0]
	s_waitcnt vmcnt(11)
	v_lshlrev_b32_e32 v46, 16, v92
	v_and_b32_e32 v47, 0xffff0000, v92
	v_pk_fma_f32 v[54:55], v[152:153], v[46:47], v[54:55] op_sel_hi:[0,1,1]
	v_pk_fma_f32 v[0:1], v[152:153], v[46:47], v[0:1] op_sel:[1,0,0]
	s_waitcnt vmcnt(10)
	v_lshlrev_b32_e32 v46, 16, v88
	v_and_b32_e32 v47, 0xffff0000, v88
	v_pk_fma_f32 v[54:55], v[154:155], v[46:47], v[54:55] op_sel_hi:[0,1,1]
	v_pk_fma_f32 v[0:1], v[154:155], v[46:47], v[0:1] op_sel:[1,0,0]
	s_waitcnt vmcnt(9)
	v_lshlrev_b32_e32 v46, 16, v84
	v_and_b32_e32 v47, 0xffff0000, v84
	v_pk_fma_f32 v[54:55], v[156:157], v[46:47], v[54:55] op_sel_hi:[0,1,1]
	v_pk_fma_f32 v[0:1], v[156:157], v[46:47], v[0:1] op_sel:[1,0,0]
	s_waitcnt vmcnt(8)
	v_lshlrev_b32_e32 v46, 16, v80
	v_and_b32_e32 v47, 0xffff0000, v80
	v_pk_fma_f32 v[0:1], v[158:159], v[46:47], v[0:1] op_sel:[1,0,0]
	v_lshlrev_b32_e32 v40, 16, v133
	v_and_b32_e32 v41, 0xffff0000, v133
	v_pk_fma_f32 v[54:55], v[158:159], v[46:47], v[54:55] op_sel_hi:[0,1,1]
	v_pk_mul_f32 v[46:47], v[10:11], v[0:1]
	v_pk_mul_f32 v[0:1], v[160:161], v[0:1]
	v_lshlrev_b32_e32 v48, 16, v129
	v_and_b32_e32 v49, 0xffff0000, v129
	v_pk_fma_f32 v[46:47], v[160:161], v[54:55], v[46:47] neg_lo:[0,0,1] neg_hi:[0,0,1]
	v_pk_fma_f32 v[0:1], v[10:11], v[54:55], v[0:1]
	v_pk_fma_f32 v[54:55], v[144:145], v[40:41], 0 op_sel_hi:[0,1,0]
	v_pk_fma_f32 v[40:41], v[144:145], v[40:41], 0 op_sel:[1,0,0] op_sel_hi:[1,1,0]
	v_pk_fma_f32 v[54:55], v[146:147], v[48:49], v[54:55] op_sel_hi:[0,1,1]
	v_pk_fma_f32 v[40:41], v[146:147], v[48:49], v[40:41] op_sel:[1,0,0]
	v_lshlrev_b32_e32 v48, 16, v101
	v_and_b32_e32 v49, 0xffff0000, v101
	v_pk_fma_f32 v[54:55], v[148:149], v[48:49], v[54:55] op_sel_hi:[0,1,1]
	v_pk_fma_f32 v[40:41], v[148:149], v[48:49], v[40:41] op_sel:[1,0,0]
	v_lshlrev_b32_e32 v48, 16, v97
	v_and_b32_e32 v49, 0xffff0000, v97
	v_pk_fma_f32 v[54:55], v[150:151], v[48:49], v[54:55] op_sel_hi:[0,1,1]
	v_pk_fma_f32 v[40:41], v[150:151], v[48:49], v[40:41] op_sel:[1,0,0]
	v_lshlrev_b32_e32 v48, 16, v93
	v_and_b32_e32 v49, 0xffff0000, v93
	v_pk_fma_f32 v[54:55], v[152:153], v[48:49], v[54:55] op_sel_hi:[0,1,1]
	v_pk_fma_f32 v[40:41], v[152:153], v[48:49], v[40:41] op_sel:[1,0,0]
	v_lshlrev_b32_e32 v48, 16, v89
	v_and_b32_e32 v49, 0xffff0000, v89
	v_pk_fma_f32 v[54:55], v[154:155], v[48:49], v[54:55] op_sel_hi:[0,1,1]
	v_pk_fma_f32 v[40:41], v[154:155], v[48:49], v[40:41] op_sel:[1,0,0]
	v_lshlrev_b32_e32 v48, 16, v85
	v_and_b32_e32 v49, 0xffff0000, v85
	v_pk_fma_f32 v[54:55], v[156:157], v[48:49], v[54:55] op_sel_hi:[0,1,1]
	v_pk_fma_f32 v[40:41], v[156:157], v[48:49], v[40:41] op_sel:[1,0,0]
	v_lshlrev_b32_e32 v48, 16, v81
	v_and_b32_e32 v49, 0xffff0000, v81
	v_pk_fma_f32 v[40:41], v[158:159], v[48:49], v[40:41] op_sel:[1,0,0]
	v_lshlrev_b32_e32 v42, 16, v134
	v_and_b32_e32 v43, 0xffff0000, v134
	v_pk_fma_f32 v[54:55], v[158:159], v[48:49], v[54:55] op_sel_hi:[0,1,1]
	v_pk_mul_f32 v[48:49], v[14:15], v[40:41]
	v_pk_mul_f32 v[40:41], v[8:9], v[40:41]
	v_lshlrev_b32_e32 v50, 16, v130
	v_and_b32_e32 v51, 0xffff0000, v130
	v_pk_fma_f32 v[48:49], v[8:9], v[54:55], v[48:49] neg_lo:[0,0,1] neg_hi:[0,0,1]
	v_pk_fma_f32 v[54:55], v[14:15], v[54:55], v[40:41]
	v_pk_fma_f32 v[40:41], v[144:145], v[42:43], 0 op_sel_hi:[0,1,0]
	v_pk_fma_f32 v[42:43], v[144:145], v[42:43], 0 op_sel:[1,0,0] op_sel_hi:[1,1,0]
	v_pk_fma_f32 v[40:41], v[146:147], v[50:51], v[40:41] op_sel_hi:[0,1,1]
	v_pk_fma_f32 v[42:43], v[146:147], v[50:51], v[42:43] op_sel:[1,0,0]
	v_lshlrev_b32_e32 v50, 16, v102
	v_and_b32_e32 v51, 0xffff0000, v102
	v_pk_fma_f32 v[40:41], v[148:149], v[50:51], v[40:41] op_sel_hi:[0,1,1]
	v_pk_fma_f32 v[42:43], v[148:149], v[50:51], v[42:43] op_sel:[1,0,0]
	v_lshlrev_b32_e32 v50, 16, v98
	v_and_b32_e32 v51, 0xffff0000, v98
	v_pk_fma_f32 v[40:41], v[150:151], v[50:51], v[40:41] op_sel_hi:[0,1,1]
	v_pk_fma_f32 v[42:43], v[150:151], v[50:51], v[42:43] op_sel:[1,0,0]
	v_lshlrev_b32_e32 v50, 16, v94
	v_and_b32_e32 v51, 0xffff0000, v94
	v_pk_fma_f32 v[40:41], v[152:153], v[50:51], v[40:41] op_sel_hi:[0,1,1]
	v_pk_fma_f32 v[42:43], v[152:153], v[50:51], v[42:43] op_sel:[1,0,0]
	v_lshlrev_b32_e32 v50, 16, v90
	v_and_b32_e32 v51, 0xffff0000, v90
	v_pk_fma_f32 v[40:41], v[154:155], v[50:51], v[40:41] op_sel_hi:[0,1,1]
	v_pk_fma_f32 v[42:43], v[154:155], v[50:51], v[42:43] op_sel:[1,0,0]
	v_lshlrev_b32_e32 v50, 16, v86
	v_and_b32_e32 v51, 0xffff0000, v86
	v_pk_fma_f32 v[40:41], v[156:157], v[50:51], v[40:41] op_sel_hi:[0,1,1]
	v_pk_fma_f32 v[42:43], v[156:157], v[50:51], v[42:43] op_sel:[1,0,0]
	v_lshlrev_b32_e32 v50, 16, v82
	v_and_b32_e32 v51, 0xffff0000, v82
	v_pk_fma_f32 v[42:43], v[158:159], v[50:51], v[42:43] op_sel:[1,0,0]
	v_lshlrev_b32_e32 v44, 16, v135
	v_and_b32_e32 v45, 0xffff0000, v135
	v_pk_fma_f32 v[40:41], v[158:159], v[50:51], v[40:41] op_sel_hi:[0,1,1]
	v_pk_mul_f32 v[50:51], v[6:7], v[42:43]
	v_pk_mul_f32 v[42:43], v[12:13], v[42:43]
	v_lshlrev_b32_e32 v52, 16, v131
	v_and_b32_e32 v53, 0xffff0000, v131
	v_pk_fma_f32 v[50:51], v[12:13], v[40:41], v[50:51] neg_lo:[0,0,1] neg_hi:[0,0,1]
	v_pk_fma_f32 v[56:57], v[6:7], v[40:41], v[42:43]
	v_pk_fma_f32 v[40:41], v[144:145], v[44:45], 0 op_sel_hi:[0,1,0]
	v_pk_fma_f32 v[42:43], v[144:145], v[44:45], 0 op_sel:[1,0,0] op_sel_hi:[1,1,0]
	v_pk_fma_f32 v[40:41], v[146:147], v[52:53], v[40:41] op_sel_hi:[0,1,1]
	v_pk_fma_f32 v[42:43], v[146:147], v[52:53], v[42:43] op_sel:[1,0,0]
	v_lshlrev_b32_e32 v44, 16, v103
	v_and_b32_e32 v45, 0xffff0000, v103
	v_pk_fma_f32 v[40:41], v[148:149], v[44:45], v[40:41] op_sel_hi:[0,1,1]
	v_pk_fma_f32 v[42:43], v[148:149], v[44:45], v[42:43] op_sel:[1,0,0]
	v_lshlrev_b32_e32 v44, 16, v99
	v_and_b32_e32 v45, 0xffff0000, v99
	v_pk_fma_f32 v[40:41], v[150:151], v[44:45], v[40:41] op_sel_hi:[0,1,1]
	v_pk_fma_f32 v[42:43], v[150:151], v[44:45], v[42:43] op_sel:[1,0,0]
	v_lshlrev_b32_e32 v44, 16, v95
	v_and_b32_e32 v45, 0xffff0000, v95
	v_pk_fma_f32 v[40:41], v[152:153], v[44:45], v[40:41] op_sel_hi:[0,1,1]
	v_pk_fma_f32 v[42:43], v[152:153], v[44:45], v[42:43] op_sel:[1,0,0]
	v_lshlrev_b32_e32 v44, 16, v91
	v_and_b32_e32 v45, 0xffff0000, v91
	v_pk_fma_f32 v[40:41], v[154:155], v[44:45], v[40:41] op_sel_hi:[0,1,1]
	v_pk_fma_f32 v[42:43], v[154:155], v[44:45], v[42:43] op_sel:[1,0,0]
	v_lshlrev_b32_e32 v44, 16, v87
	v_and_b32_e32 v45, 0xffff0000, v87
	v_pk_fma_f32 v[40:41], v[156:157], v[44:45], v[40:41] op_sel_hi:[0,1,1]
	v_pk_fma_f32 v[42:43], v[156:157], v[44:45], v[42:43] op_sel:[1,0,0]
	v_lshlrev_b32_e32 v44, 16, v83
	v_and_b32_e32 v45, 0xffff0000, v83
	v_pk_fma_f32 v[42:43], v[158:159], v[44:45], v[42:43] op_sel:[1,0,0]
	v_pk_fma_f32 v[40:41], v[158:159], v[44:45], v[40:41] op_sel_hi:[0,1,1]
	v_pk_mul_f32 v[44:45], v[2:3], v[42:43]
	v_pk_mul_f32 v[42:43], v[4:5], v[42:43]
	v_pk_fma_f32 v[44:45], v[4:5], v[40:41], v[44:45] neg_lo:[0,0,1] neg_hi:[0,0,1]
	v_pk_fma_f32 v[52:53], v[2:3], v[40:41], v[42:43]
	v_cvt_pk_bf16_f32 v43, v44, v45
	v_mul_lo_u32 v44, v166, s6
	v_cvt_pk_bf16_f32 v40, v46, v47
	v_cvt_pk_bf16_f32 v41, v48, v49
	v_cvt_pk_bf16_f32 v42, v50, v51
	v_add3_u32 v44, 0, v44, v192
	ds_write_b128 v44, v[40:43]
	v_cvt_pk_bf16_f32 v40, v0, v1
	s_waitcnt vmcnt(7)
	v_lshlrev_b32_e32 v0, 16, v68
	v_and_b32_e32 v1, 0xffff0000, v68
	v_cvt_pk_bf16_f32 v41, v54, v55
	s_waitcnt vmcnt(6)
	v_lshlrev_b32_e32 v46, 16, v64
	v_and_b32_e32 v47, 0xffff0000, v64
	v_pk_fma_f32 v[54:55], v[144:145], v[0:1], 0 op_sel_hi:[0,1,0]
	v_pk_fma_f32 v[0:1], v[144:145], v[0:1], 0 op_sel:[1,0,0] op_sel_hi:[1,1,0]
	v_pk_fma_f32 v[54:55], v[146:147], v[46:47], v[54:55] op_sel_hi:[0,1,1]
	v_pk_fma_f32 v[0:1], v[146:147], v[46:47], v[0:1] op_sel:[1,0,0]
	s_waitcnt vmcnt(5)
	v_lshlrev_b32_e32 v46, 16, v36
	v_and_b32_e32 v47, 0xffff0000, v36
	v_pk_fma_f32 v[54:55], v[148:149], v[46:47], v[54:55] op_sel_hi:[0,1,1]
	v_pk_fma_f32 v[0:1], v[148:149], v[46:47], v[0:1] op_sel:[1,0,0]
	s_waitcnt vmcnt(4)
	v_lshlrev_b32_e32 v46, 16, v32
	v_and_b32_e32 v47, 0xffff0000, v32
	v_pk_fma_f32 v[54:55], v[150:151], v[46:47], v[54:55] op_sel_hi:[0,1,1]
	v_pk_fma_f32 v[0:1], v[150:151], v[46:47], v[0:1] op_sel:[1,0,0]
	s_waitcnt vmcnt(3)
	v_lshlrev_b32_e32 v46, 16, v28
	v_and_b32_e32 v47, 0xffff0000, v28
	v_pk_fma_f32 v[54:55], v[152:153], v[46:47], v[54:55] op_sel_hi:[0,1,1]
	v_pk_fma_f32 v[0:1], v[152:153], v[46:47], v[0:1] op_sel:[1,0,0]
	s_waitcnt vmcnt(2)
	v_lshlrev_b32_e32 v46, 16, v24
	v_and_b32_e32 v47, 0xffff0000, v24
	v_pk_fma_f32 v[54:55], v[154:155], v[46:47], v[54:55] op_sel_hi:[0,1,1]
	v_pk_fma_f32 v[0:1], v[154:155], v[46:47], v[0:1] op_sel:[1,0,0]
	s_waitcnt vmcnt(1)
	v_lshlrev_b32_e32 v46, 16, v20
	v_and_b32_e32 v47, 0xffff0000, v20
	v_pk_fma_f32 v[54:55], v[156:157], v[46:47], v[54:55] op_sel_hi:[0,1,1]
	v_pk_fma_f32 v[0:1], v[156:157], v[46:47], v[0:1] op_sel:[1,0,0]
	s_waitcnt vmcnt(0)
	v_lshlrev_b32_e32 v46, 16, v16
	v_and_b32_e32 v47, 0xffff0000, v16
	v_cvt_pk_bf16_f32 v42, v56, v57
	v_cvt_pk_bf16_f32 v43, v52, v53
	v_pk_fma_f32 v[0:1], v[158:159], v[46:47], v[0:1] op_sel:[1,0,0]
	ds_write_b128 v44, v[40:43] offset:512
	v_lshlrev_b32_e32 v40, 16, v69
	v_and_b32_e32 v41, 0xffff0000, v69
	v_pk_fma_f32 v[54:55], v[158:159], v[46:47], v[54:55] op_sel_hi:[0,1,1]
	v_pk_mul_f32 v[46:47], v[10:11], v[0:1]
	v_pk_mul_f32 v[0:1], v[160:161], v[0:1]
	v_lshlrev_b32_e32 v48, 16, v65
	v_and_b32_e32 v49, 0xffff0000, v65
	v_pk_fma_f32 v[10:11], v[10:11], v[54:55], v[0:1]
	v_pk_fma_f32 v[0:1], v[144:145], v[40:41], 0 op_sel_hi:[0,1,0]
	v_pk_fma_f32 v[40:41], v[144:145], v[40:41], 0 op_sel:[1,0,0] op_sel_hi:[1,1,0]
	v_pk_fma_f32 v[0:1], v[146:147], v[48:49], v[0:1] op_sel_hi:[0,1,1]
	v_pk_fma_f32 v[40:41], v[146:147], v[48:49], v[40:41] op_sel:[1,0,0]
	v_lshlrev_b32_e32 v36, 16, v37
	v_and_b32_e32 v37, 0xffff0000, v37
	v_pk_fma_f32 v[0:1], v[148:149], v[36:37], v[0:1] op_sel_hi:[0,1,1]
	v_pk_fma_f32 v[36:37], v[148:149], v[36:37], v[40:41] op_sel:[1,0,0]
	v_lshlrev_b32_e32 v32, 16, v33
	v_and_b32_e32 v33, 0xffff0000, v33
	v_pk_fma_f32 v[0:1], v[150:151], v[32:33], v[0:1] op_sel_hi:[0,1,1]
	v_pk_fma_f32 v[32:33], v[150:151], v[32:33], v[36:37] op_sel:[1,0,0]
	v_lshlrev_b32_e32 v28, 16, v29
	v_and_b32_e32 v29, 0xffff0000, v29
	v_pk_fma_f32 v[0:1], v[152:153], v[28:29], v[0:1] op_sel_hi:[0,1,1]
	v_pk_fma_f32 v[28:29], v[152:153], v[28:29], v[32:33] op_sel:[1,0,0]
	v_lshlrev_b32_e32 v24, 16, v25
	v_and_b32_e32 v25, 0xffff0000, v25
	v_pk_fma_f32 v[0:1], v[154:155], v[24:25], v[0:1] op_sel_hi:[0,1,1]
; #define GAS __attribute__((address_space(1)))
; #define BU_LOAD(buf, ib) do { _Pragma("unroll") for (int h = 0; h < 2; ++h) { const int it = (2 * (ib) + h + k2) & 7, l = 16 * w + 2 * it + rp; \
;             _Pragma("unroll") for (int s2 = 0; s2 < 8; ++s2) c4[buf][h][s2] = *(const GAS u32x4*)(z0 + (size_t)l * 2048 + 256 * s2); } } while (0)
; __device__ __forceinline__ void b_unit(Frame& F, int u, bool dry) {
;     ...
;         BU_LOAD(0, 0);
;         BU_LOAD(1, 1); BU_RED(0, 0);
;         BU_LOAD(0, 2); BU_RED(1, 1);
;         BU_LOAD(1, 3); BU_RED(0, 2);
;         BU_RED(1, 3);
;     ...
;     }
;     __syncthreads();
;     const int fr = lane & 15, fq = lane >> 4;
;     f32x4 ur[2][8], ui[2][8];
;     {
;         const bf16x8 Wr = *(const GAS bf16x8*)(ws_ + WS_W16F + (size_t)lane * 16), Wi = *(const GAS bf16x8*)(ws_ + WS_W16F + 1024 + (size_t)lane * 16);
	v_pk_fma_f32 v[24:25], v[154:155], v[24:25], v[28:29] op_sel:[1,0,0]
	v_lshlrev_b32_e32 v20, 16, v21
	v_and_b32_e32 v21, 0xffff0000, v21
	v_pk_fma_f32 v[0:1], v[156:157], v[20:21], v[0:1] op_sel_hi:[0,1,1]
	v_pk_fma_f32 v[20:21], v[156:157], v[20:21], v[24:25] op_sel:[1,0,0]
	v_lshlrev_b32_e32 v16, 16, v17
	v_and_b32_e32 v17, 0xffff0000, v17
	v_pk_fma_f32 v[0:1], v[158:159], v[16:17], v[0:1] op_sel_hi:[0,1,1]
	v_pk_fma_f32 v[16:17], v[158:159], v[16:17], v[20:21] op_sel:[1,0,0]
	v_lshlrev_b32_e32 v42, 16, v70
	v_pk_mul_f32 v[20:21], v[14:15], v[16:17]
	v_and_b32_e32 v43, 0xffff0000, v70
	v_pk_fma_f32 v[20:21], v[8:9], v[0:1], v[20:21] neg_lo:[0,0,1] neg_hi:[0,0,1]
	v_pk_mul_f32 v[8:9], v[8:9], v[16:17]
	v_lshlrev_b32_e32 v50, 16, v66
	v_and_b32_e32 v51, 0xffff0000, v66
	v_pk_fma_f32 v[8:9], v[14:15], v[0:1], v[8:9]
	v_pk_fma_f32 v[0:1], v[144:145], v[42:43], 0 op_sel_hi:[0,1,0]
	v_pk_fma_f32 v[14:15], v[144:145], v[42:43], 0 op_sel:[1,0,0] op_sel_hi:[1,1,0]
	v_pk_fma_f32 v[0:1], v[146:147], v[50:51], v[0:1] op_sel_hi:[0,1,1]
	v_pk_fma_f32 v[14:15], v[146:147], v[50:51], v[14:15] op_sel:[1,0,0]
	v_lshlrev_b32_e32 v16, 16, v38
	v_and_b32_e32 v17, 0xffff0000, v38
	v_pk_fma_f32 v[0:1], v[148:149], v[16:17], v[0:1] op_sel_hi:[0,1,1]
	v_pk_fma_f32 v[14:15], v[148:149], v[16:17], v[14:15] op_sel:[1,0,0]
	v_lshlrev_b32_e32 v16, 16, v34
	v_and_b32_e32 v17, 0xffff0000, v34
	v_pk_fma_f32 v[0:1], v[150:151], v[16:17], v[0:1] op_sel_hi:[0,1,1]
	v_pk_fma_f32 v[14:15], v[150:151], v[16:17], v[14:15] op_sel:[1,0,0]
	v_lshlrev_b32_e32 v16, 16, v30
	v_and_b32_e32 v17, 0xffff0000, v30
	v_pk_fma_f32 v[0:1], v[152:153], v[16:17], v[0:1] op_sel_hi:[0,1,1]
	v_pk_fma_f32 v[14:15], v[152:153], v[16:17], v[14:15] op_sel:[1,0,0]
	v_lshlrev_b32_e32 v16, 16, v26
	v_and_b32_e32 v17, 0xffff0000, v26
	v_pk_fma_f32 v[0:1], v[154:155], v[16:17], v[0:1] op_sel_hi:[0,1,1]
	v_pk_fma_f32 v[14:15], v[154:155], v[16:17], v[14:15] op_sel:[1,0,0]
	v_lshlrev_b32_e32 v16, 16, v22
	v_and_b32_e32 v17, 0xffff0000, v22
	v_pk_fma_f32 v[0:1], v[156:157], v[16:17], v[0:1] op_sel_hi:[0,1,1]
	v_pk_fma_f32 v[14:15], v[156:157], v[16:17], v[14:15] op_sel:[1,0,0]
	v_lshlrev_b32_e32 v16, 16, v18
	v_and_b32_e32 v17, 0xffff0000, v18
	v_pk_fma_f32 v[14:15], v[158:159], v[16:17], v[14:15] op_sel:[1,0,0]
	v_pk_fma_f32 v[0:1], v[158:159], v[16:17], v[0:1] op_sel_hi:[0,1,1]
	v_pk_mul_f32 v[16:17], v[6:7], v[14:15]
	v_lshlrev_b32_e32 v44, 16, v71
	v_and_b32_e32 v45, 0xffff0000, v71
	v_pk_fma_f32 v[16:17], v[12:13], v[0:1], v[16:17] neg_lo:[0,0,1] neg_hi:[0,0,1]
	v_pk_mul_f32 v[12:13], v[12:13], v[14:15]
	v_lshlrev_b32_e32 v52, 16, v67
	v_and_b32_e32 v53, 0xffff0000, v67
	v_pk_fma_f32 v[6:7], v[6:7], v[0:1], v[12:13]
	v_pk_fma_f32 v[0:1], v[144:145], v[44:45], 0 op_sel_hi:[0,1,0]
	v_pk_fma_f32 v[12:13], v[144:145], v[44:45], 0 op_sel:[1,0,0] op_sel_hi:[1,1,0]
	v_pk_fma_f32 v[0:1], v[146:147], v[52:53], v[0:1] op_sel_hi:[0,1,1]
	v_pk_fma_f32 v[12:13], v[146:147], v[52:53], v[12:13] op_sel:[1,0,0]
	v_lshlrev_b32_e32 v14, 16, v39
	v_and_b32_e32 v15, 0xffff0000, v39
	v_pk_fma_f32 v[0:1], v[148:149], v[14:15], v[0:1] op_sel_hi:[0,1,1]
	v_pk_fma_f32 v[12:13], v[148:149], v[14:15], v[12:13] op_sel:[1,0,0]
	v_lshlrev_b32_e32 v14, 16, v35
	v_and_b32_e32 v15, 0xffff0000, v35
	v_pk_fma_f32 v[0:1], v[150:151], v[14:15], v[0:1] op_sel_hi:[0,1,1]
	v_pk_fma_f32 v[12:13], v[150:151], v[14:15], v[12:13] op_sel:[1,0,0]
	v_lshlrev_b32_e32 v14, 16, v31
	v_and_b32_e32 v15, 0xffff0000, v31
	v_pk_fma_f32 v[0:1], v[152:153], v[14:15], v[0:1] op_sel_hi:[0,1,1]
	v_pk_fma_f32 v[12:13], v[152:153], v[14:15], v[12:13] op_sel:[1,0,0]
	v_lshlrev_b32_e32 v14, 16, v27
	v_and_b32_e32 v15, 0xffff0000, v27
	v_pk_fma_f32 v[0:1], v[154:155], v[14:15], v[0:1] op_sel_hi:[0,1,1]
	v_pk_fma_f32 v[12:13], v[154:155], v[14:15], v[12:13] op_sel:[1,0,0]
	v_lshlrev_b32_e32 v14, 16, v23
	v_and_b32_e32 v15, 0xffff0000, v23
	v_pk_fma_f32 v[0:1], v[156:157], v[14:15], v[0:1] op_sel_hi:[0,1,1]
	v_pk_fma_f32 v[12:13], v[156:157], v[14:15], v[12:13] op_sel:[1,0,0]
	v_lshlrev_b32_e32 v14, 16, v19
	v_and_b32_e32 v15, 0xffff0000, v19
	v_pk_fma_f32 v[12:13], v[158:159], v[14:15], v[12:13] op_sel:[1,0,0]
	v_pk_fma_f32 v[0:1], v[158:159], v[14:15], v[0:1] op_sel_hi:[0,1,1]
	v_pk_mul_f32 v[14:15], v[2:3], v[12:13]
	v_pk_fma_f32 v[46:47], v[160:161], v[54:55], v[46:47] neg_lo:[0,0,1] neg_hi:[0,0,1]
	v_pk_fma_f32 v[14:15], v[4:5], v[0:1], v[14:15] neg_lo:[0,0,1] neg_hi:[0,0,1]
	v_pk_mul_f32 v[4:5], v[4:5], v[12:13]
	v_mul_lo_u32 v12, v164, s6
	v_pk_fma_f32 v[4:5], v[2:3], v[0:1], v[4:5]
	v_cvt_pk_bf16_f32 v0, v46, v47
	v_cvt_pk_bf16_f32 v1, v20, v21
	v_cvt_pk_bf16_f32 v2, v16, v17
	v_cvt_pk_bf16_f32 v3, v14, v15
	v_add3_u32 v12, 0, v12, v192
	ds_write_b128 v12, v[0:3]
	v_cvt_pk_bf16_f32 v0, v10, v11
	v_cvt_pk_bf16_f32 v1, v8, v9
	v_cvt_pk_bf16_f32 v2, v6, v7
	v_cvt_pk_bf16_f32 v3, v4, v5
	v_lshlrev_b32_e32 v192, 4, v171
	ds_write_b128 v12, v[0:3] offset:512
	v_lshl_add_u64 v[0:1], s[2:3], 0, v[192:193]
	v_add_co_u32_e32 v4, vcc, s7, v0
	s_waitcnt lgkmcnt(0)
	s_nop 0
	v_addc_co_u32_e32 v5, vcc, 0, v1, vcc
	s_barrier
; #define LAS __attribute__((address_space(3)))
; #define GAS __attribute__((address_space(1)))
; __device__ __forceinline__ unsigned cvtpk(float lo, float hi) { f32x2 v = {lo, hi}; bf16x2_t b = __builtin_convertvector(v, bf16x2_t); return __builtin_bit_cast(unsigned, b); }
; __device__ __forceinline__ void b_unit(Frame& F, int u, bool dry) {
;     ...
;         const bf16x8 Wr = *(const GAS bf16x8*)(ws_ + WS_W16F + (size_t)lane * 16), Wi = *(const GAS bf16x8*)(ws_ + WS_W16F + 1024 + (size_t)lane * 16);
;         f32x2 t2[4];
; #pragma unroll
;         for (int j = 0; j < 4; ++j) t2[j] = *(const GAS f32x2*)(ws_ + WS_TW2 + (size_t)(lane * 4 + j) * 8);
;         const f32x4 zero4 = (f32x4){0.f, 0.f, 0.f, 0.f};
;         const unsigned rbase = (unsigned)(size_t)Bt + (unsigned)(16 * w) * 1040u + (unsigned)(fq >> 1) * 512u + (unsigned)(16 * (8 * (fq & 1) + (fr >> 2)) + 4 * (fr & 3)) * 2u;
;         u32x2 q0[16], q1[16];
;     ...
;         BU_TR8(0); BU_TR8(8);
;     ...
;         LAS unsigned char* vrow = Bt + (size_t)(16 * w) * 1040 + 64 * fr + 8 * fq;
; #pragma unroll
;         for (int i = 0; i < 16; ++i) {
;             u32x4 f4; f4.x = q0[i].x; f4.y = q0[i].y; f4.z = q1[i].x; f4.w = q1[i].y;
;             const bf16x8 frag = __builtin_bit_cast(bf16x8, f4);
;             const f32x4 dr = __builtin_amdgcn_mfma_f32_16x16x32_bf16(frag, Wr, zero4, 0, 0, 0), di = __builtin_amdgcn_mfma_f32_16x16x32_bf16(frag, Wi, zero4, 0, 0, 0);
;             float vr[4], vi[4];
; #pragma unroll
;             for (int j = 0; j < 4; ++j) { vr[j] = dr[j] * t2[j].x + di[j] * t2[j].y; vi[j] = di[j] * t2[j].x - dr[j] * t2[j].y; }
;             u32x2 o; o.x = cvtpk(vr[0], vr[1]); o.y = cvtpk(vr[2], vr[3]); *(LAS u32x2*)(vrow + i * 1040) = o;
;             o.x = cvtpk(vi[0], vi[1]); o.y = cvtpk(vi[2], vi[3]); *(LAS u32x2*)(vrow + i * 1040 + 32) = o;
;         }
	global_load_dwordx4 v[0:3], v[4:5], off
	s_nop 0
	global_load_dwordx4 v[4:7], v[4:5], off offset:1024
	v_lshlrev_b32_e32 v8, 5, v171
	v_mov_b32_e32 v9, v193
	v_lshl_add_u64 v[8:9], s[2:3], 0, v[8:9]
	s_mov_b64 s[0:1], 0x1d90800
	v_lshl_add_u64 v[10:11], v[8:9], 0, s[0:1]
	v_add_co_u32_e32 v8, vcc, s7, v8
	v_lshrrev_b32_e32 v17, 1, v170
	s_nop 0
	v_addc_co_u32_e32 v9, vcc, 0, v9, vcc
	global_load_dwordx4 v[12:15], v[8:9], off offset:2048
	s_nop 0
	global_load_dwordx4 v[8:11], v[10:11], off offset:16
	v_bfe_u32 v18, v170, 2, 2
	v_and_b32_e32 v76, 24, v17
	v_and_or_b32 v17, v17, 8, v18
	v_lshlrev_b32_e32 v18, 3, v170
	v_and_b32_e32 v18, 24, v18
	v_readlane_b32 s0, v253, 54
	v_and_b32_e32 v16, 0x200, v192
	v_lshlrev_b32_e32 v17, 5, v17
	v_add_u32_e32 v18, s0, v18
	v_add3_u32 v64, v18, v16, v17
	ds_read_b64_tr_b16 v[82:83], v64 offset:0
	ds_read_b64_tr_b16 v[84:85], v64 offset:0+128
	ds_read_b64_tr_b16 v[78:79], v64 offset:0+1040
	ds_read_b64_tr_b16 v[80:81], v64 offset:0+1040+128
	ds_read_b64_tr_b16 v[72:73], v64 offset:0+2080
	ds_read_b64_tr_b16 v[74:75], v64 offset:0+2080+128
	ds_read_b64_tr_b16 v[68:69], v64 offset:0+3120
	ds_read_b64_tr_b16 v[70:71], v64 offset:0+3120+128
	ds_read_b64_tr_b16 v[60:61], v64 offset:0+4160
	ds_read_b64_tr_b16 v[62:63], v64 offset:0+4160+128
	ds_read_b64_tr_b16 v[56:57], v64 offset:0+5200
	ds_read_b64_tr_b16 v[58:59], v64 offset:0+5200+128
	ds_read_b64_tr_b16 v[52:53], v64 offset:0+6240
	ds_read_b64_tr_b16 v[54:55], v64 offset:0+6240+128
	ds_read_b64_tr_b16 v[48:49], v64 offset:0+7280
	ds_read_b64_tr_b16 v[50:51], v64 offset:0+7280+128
	s_waitcnt lgkmcnt(0)
	v_and_b32_e32 v77, 15, v170
	s_waitcnt vmcnt(3)
	v_mfma_f32_16x16x32_bf16 v[86:89], v[82:85], v[0:3], 0
	ds_read_b64_tr_b16 v[44:45], v64 offset:0x2080
	ds_read_b64_tr_b16 v[46:47], v64 offset:0x2080+128
	ds_read_b64_tr_b16 v[40:41], v64 offset:0x2080+1040
	ds_read_b64_tr_b16 v[42:43], v64 offset:0x2080+1040+128
	ds_read_b64_tr_b16 v[36:37], v64 offset:0x2080+2080
	ds_read_b64_tr_b16 v[38:39], v64 offset:0x2080+2080+128
	ds_read_b64_tr_b16 v[32:33], v64 offset:0x2080+3120
	ds_read_b64_tr_b16 v[34:35], v64 offset:0x2080+3120+128
	ds_read_b64_tr_b16 v[28:29], v64 offset:0x2080+4160
	ds_read_b64_tr_b16 v[30:31], v64 offset:0x2080+4160+128
	ds_read_b64_tr_b16 v[24:25], v64 offset:0x2080+5200
	ds_read_b64_tr_b16 v[26:27], v64 offset:0x2080+5200+128
	ds_read_b64_tr_b16 v[20:21], v64 offset:0x2080+6240
	ds_read_b64_tr_b16 v[22:23], v64 offset:0x2080+6240+128
	ds_read_b64_tr_b16 v[16:17], v64 offset:0x2080+7280
	ds_read_b64_tr_b16 v[18:19], v64 offset:0x2080+7280+128
	s_waitcnt lgkmcnt(0)
	v_lshlrev_b32_e32 v64, 6, v77
	v_add3_u32 v66, s0, v64, v76
	s_waitcnt vmcnt(2)
	v_mfma_f32_16x16x32_bf16 v[82:85], v[82:85], v[4:7], 0
	v_add_u32_e32 v67, 0x800, v66
	v_readlane_b32 s0, v253, 60
	v_lshlrev_b32_e32 v192, 1, v76
	s_waitcnt vmcnt(1)
	v_mov_b32_e32 v65, v14
	v_mov_b32_e32 v14, v13
	v_mov_b32_e32 v64, v12
	s_nop 0
	v_pk_mul_f32 v[12:13], v[14:15], v[82:83]
	s_nop 0
	v_pk_fma_f32 v[90:91], v[64:65], v[86:87], v[12:13]
	v_pk_mul_f32 v[12:13], v[14:15], v[86:87]
	s_nop 0
	v_pk_fma_f32 v[82:83], v[64:65], v[82:83], v[12:13] neg_lo:[0,0,1] neg_hi:[0,0,1]
	s_waitcnt vmcnt(0)
	v_mov_b32_e32 v13, v10
	v_mov_b32_e32 v10, v9
	v_mov_b32_e32 v12, v8
	v_pk_mul_f32 v[8:9], v[10:11], v[84:85]
	v_pk_mul_f32 v[86:87], v[10:11], v[88:89]
	v_pk_fma_f32 v[8:9], v[12:13], v[88:89], v[8:9]
	v_pk_fma_f32 v[84:85], v[12:13], v[84:85], v[86:87] neg_lo:[0,0,1] neg_hi:[0,0,1]
	v_cvt_pk_bf16_f32 v87, v8, v9
	v_cvt_pk_bf16_f32 v8, v82, v83
	v_cvt_pk_bf16_f32 v9, v84, v85
	v_mfma_f32_16x16x32_bf16 v[82:85], v[78:81], v[0:3], 0
	v_cvt_pk_bf16_f32 v86, v90, v91
	ds_write2_b64 v66, v[86:87], v[8:9] offset1:4
	v_mfma_f32_16x16x32_bf16 v[78:81], v[78:81], v[4:7], 0
	s_nop 7
	v_pk_mul_f32 v[8:9], v[14:15], v[78:79]
	s_nop 0
	v_pk_fma_f32 v[8:9], v[64:65], v[82:83], v[8:9]
	v_pk_mul_f32 v[82:83], v[14:15], v[82:83]
	v_cvt_pk_bf16_f32 v8, v8, v9
	v_pk_fma_f32 v[78:79], v[64:65], v[78:79], v[82:83] neg_lo:[0,0,1] neg_hi:[0,0,1]
	v_pk_mul_f32 v[82:83], v[10:11], v[80:81]
	v_cvt_pk_bf16_f32 v78, v78, v79
	v_pk_fma_f32 v[82:83], v[12:13], v[84:85], v[82:83]
	v_pk_mul_f32 v[84:85], v[10:11], v[84:85]
	v_cvt_pk_bf16_f32 v9, v82, v83
	v_pk_fma_f32 v[80:81], v[12:13], v[80:81], v[84:85] neg_lo:[0,0,1] neg_hi:[0,0,1]
	s_nop 0
	v_cvt_pk_bf16_f32 v79, v80, v81
	ds_write2_b64 v66, v[8:9], v[78:79] offset0:130 offset1:134
	v_mfma_f32_16x16x32_bf16 v[78:81], v[72:75], v[0:3], 0
	v_mfma_f32_16x16x32_bf16 v[72:75], v[72:75], v[4:7], 0
	s_nop 7
	v_pk_mul_f32 v[8:9], v[14:15], v[72:73]
	s_nop 0
	v_pk_fma_f32 v[8:9], v[64:65], v[78:79], v[8:9]
	v_pk_mul_f32 v[78:79], v[14:15], v[78:79]
	v_cvt_pk_bf16_f32 v8, v8, v9
	v_pk_fma_f32 v[72:73], v[64:65], v[72:73], v[78:79] neg_lo:[0,0,1] neg_hi:[0,0,1]
	v_pk_mul_f32 v[78:79], v[10:11], v[74:75]
	v_cvt_pk_bf16_f32 v72, v72, v73
	v_pk_fma_f32 v[78:79], v[12:13], v[80:81], v[78:79]
	v_pk_mul_f32 v[80:81], v[10:11], v[80:81]
	v_cvt_pk_bf16_f32 v9, v78, v79
	v_pk_fma_f32 v[74:75], v[12:13], v[74:75], v[80:81] neg_lo:[0,0,1] neg_hi:[0,0,1]
	s_nop 0
	v_cvt_pk_bf16_f32 v73, v74, v75
	ds_write2_b64 v67, v[8:9], v[72:73] offset0:4 offset1:8
	v_mfma_f32_16x16x32_bf16 v[72:75], v[68:71], v[0:3], 0
	v_mfma_f32_16x16x32_bf16 v[68:71], v[68:71], v[4:7], 0
	s_nop 7
	v_pk_mul_f32 v[8:9], v[14:15], v[68:69]
	s_nop 0
	v_pk_fma_f32 v[8:9], v[64:65], v[72:73], v[8:9]
	v_pk_mul_f32 v[72:73], v[14:15], v[72:73]
	v_cvt_pk_bf16_f32 v8, v8, v9
	v_pk_fma_f32 v[68:69], v[64:65], v[68:69], v[72:73] neg_lo:[0,0,1] neg_hi:[0,0,1]
	v_pk_mul_f32 v[72:73], v[10:11], v[70:71]
	v_cvt_pk_bf16_f32 v68, v68, v69
; #define LAS __attribute__((address_space(3)))
; __device__ __forceinline__ unsigned cvtpk(float lo, float hi) { f32x2 v = {lo, hi}; bf16x2_t b = __builtin_convertvector(v, bf16x2_t); return __builtin_bit_cast(unsigned, b); }
; __device__ __forceinline__ void b_unit(Frame& F, int u, bool dry) {
;     ...
;         for (int i = 0; i < 16; ++i) {
;             u32x4 f4; f4.x = q0[i].x; f4.y = q0[i].y; f4.z = q1[i].x; f4.w = q1[i].y;
;             const bf16x8 frag = __builtin_bit_cast(bf16x8, f4);
;             const f32x4 dr = __builtin_amdgcn_mfma_f32_16x16x32_bf16(frag, Wr, zero4, 0, 0, 0), di = __builtin_amdgcn_mfma_f32_16x16x32_bf16(frag, Wi, zero4, 0, 0, 0);
;             float vr[4], vi[4];
; #pragma unroll
;             for (int j = 0; j < 4; ++j) { vr[j] = dr[j] * t2[j].x + di[j] * t2[j].y; vi[j] = di[j] * t2[j].x - dr[j] * t2[j].y; }
;             u32x2 o; o.x = cvtpk(vr[0], vr[1]); o.y = cvtpk(vr[2], vr[3]); *(LAS u32x2*)(vrow + i * 1040) = o;
;             o.x = cvtpk(vi[0], vi[1]); o.y = cvtpk(vi[2], vi[3]); *(LAS u32x2*)(vrow + i * 1040 + 32) = o;
;         }
	v_pk_fma_f32 v[72:73], v[12:13], v[74:75], v[72:73]
	v_pk_mul_f32 v[74:75], v[10:11], v[74:75]
	v_cvt_pk_bf16_f32 v9, v72, v73
	v_pk_fma_f32 v[70:71], v[12:13], v[70:71], v[74:75] neg_lo:[0,0,1] neg_hi:[0,0,1]
	s_nop 0
	v_cvt_pk_bf16_f32 v69, v70, v71
	ds_write2_b64 v67, v[8:9], v[68:69] offset0:134 offset1:138
	v_mfma_f32_16x16x32_bf16 v[68:71], v[60:63], v[0:3], 0
	v_add_u32_e32 v67, 0x1000, v66
	v_mfma_f32_16x16x32_bf16 v[60:63], v[60:63], v[4:7], 0
	s_nop 7
	v_pk_mul_f32 v[8:9], v[14:15], v[60:61]
	s_nop 0
	v_pk_fma_f32 v[8:9], v[64:65], v[68:69], v[8:9]
	v_pk_mul_f32 v[68:69], v[14:15], v[68:69]
	v_cvt_pk_bf16_f32 v8, v8, v9
	v_pk_fma_f32 v[60:61], v[64:65], v[60:61], v[68:69] neg_lo:[0,0,1] neg_hi:[0,0,1]
	v_pk_mul_f32 v[68:69], v[10:11], v[62:63]
	v_cvt_pk_bf16_f32 v60, v60, v61
	v_pk_fma_f32 v[68:69], v[12:13], v[70:71], v[68:69]
	v_pk_mul_f32 v[70:71], v[10:11], v[70:71]
	v_cvt_pk_bf16_f32 v9, v68, v69
	v_pk_fma_f32 v[62:63], v[12:13], v[62:63], v[70:71] neg_lo:[0,0,1] neg_hi:[0,0,1]
	s_nop 0
	v_cvt_pk_bf16_f32 v61, v62, v63
	ds_write2_b64 v67, v[8:9], v[60:61] offset0:8 offset1:12
	v_mfma_f32_16x16x32_bf16 v[60:63], v[56:59], v[0:3], 0
	v_mfma_f32_16x16x32_bf16 v[56:59], v[56:59], v[4:7], 0
	s_nop 7
	v_pk_mul_f32 v[8:9], v[14:15], v[56:57]
	s_nop 0
	v_pk_fma_f32 v[8:9], v[64:65], v[60:61], v[8:9]
	v_pk_mul_f32 v[60:61], v[14:15], v[60:61]
	v_cvt_pk_bf16_f32 v8, v8, v9
	v_pk_fma_f32 v[56:57], v[64:65], v[56:57], v[60:61] neg_lo:[0,0,1] neg_hi:[0,0,1]
	v_pk_mul_f32 v[60:61], v[10:11], v[58:59]
	v_cvt_pk_bf16_f32 v56, v56, v57
	v_pk_fma_f32 v[60:61], v[12:13], v[62:63], v[60:61]
	v_pk_mul_f32 v[62:63], v[10:11], v[62:63]
	v_cvt_pk_bf16_f32 v9, v60, v61
	v_pk_fma_f32 v[58:59], v[12:13], v[58:59], v[62:63] neg_lo:[0,0,1] neg_hi:[0,0,1]
	s_nop 0
	v_cvt_pk_bf16_f32 v57, v58, v59
	ds_write2_b64 v67, v[8:9], v[56:57] offset0:138 offset1:142
	v_mfma_f32_16x16x32_bf16 v[56:59], v[52:55], v[0:3], 0
	v_mfma_f32_16x16x32_bf16 v[52:55], v[52:55], v[4:7], 0
	s_nop 7
	v_pk_mul_f32 v[8:9], v[14:15], v[52:53]
	s_nop 0
	v_pk_fma_f32 v[8:9], v[64:65], v[56:57], v[8:9]
	v_pk_mul_f32 v[56:57], v[14:15], v[56:57]
	v_cvt_pk_bf16_f32 v8, v8, v9
	v_pk_fma_f32 v[52:53], v[64:65], v[52:53], v[56:57] neg_lo:[0,0,1] neg_hi:[0,0,1]
	v_pk_mul_f32 v[56:57], v[10:11], v[54:55]
	v_cvt_pk_bf16_f32 v52, v52, v53
	v_pk_fma_f32 v[56:57], v[12:13], v[58:59], v[56:57]
	v_pk_mul_f32 v[58:59], v[10:11], v[58:59]
	v_cvt_pk_bf16_f32 v9, v56, v57
	v_pk_fma_f32 v[54:55], v[12:13], v[54:55], v[58:59] neg_lo:[0,0,1] neg_hi:[0,0,1]
	v_add_u32_e32 v56, 0x1800, v66
	v_cvt_pk_bf16_f32 v53, v54, v55
	ds_write2_b64 v56, v[8:9], v[52:53] offset0:12 offset1:16
	v_mfma_f32_16x16x32_bf16 v[52:55], v[48:51], v[0:3], 0
	v_mfma_f32_16x16x32_bf16 v[48:51], v[48:51], v[4:7], 0
	s_nop 7
	v_pk_mul_f32 v[8:9], v[14:15], v[48:49]
	s_nop 0
	v_pk_fma_f32 v[8:9], v[64:65], v[52:53], v[8:9]
	v_pk_mul_f32 v[52:53], v[14:15], v[52:53]
	v_cvt_pk_bf16_f32 v8, v8, v9
	v_pk_fma_f32 v[48:49], v[64:65], v[48:49], v[52:53] neg_lo:[0,0,1] neg_hi:[0,0,1]
	v_pk_mul_f32 v[52:53], v[10:11], v[50:51]
	v_cvt_pk_bf16_f32 v48, v48, v49
	v_pk_fma_f32 v[52:53], v[12:13], v[54:55], v[52:53]
	v_pk_mul_f32 v[54:55], v[10:11], v[54:55]
	v_cvt_pk_bf16_f32 v9, v52, v53
	v_pk_fma_f32 v[50:51], v[12:13], v[50:51], v[54:55] neg_lo:[0,0,1] neg_hi:[0,0,1]
	v_mov_b32_e32 v52, 0x1c700
	v_cvt_pk_bf16_f32 v49, v50, v51
	ds_write2_b64 v56, v[8:9], v[48:49] offset0:142 offset1:146
	v_mfma_f32_16x16x32_bf16 v[48:51], v[44:47], v[0:3], 0
	v_mad_u32_u24 v134, v77, s6, v52
	v_mfma_f32_16x16x32_bf16 v[44:47], v[44:47], v[4:7], 0
	s_nop 7
	v_pk_mul_f32 v[8:9], v[14:15], v[44:45]
	s_nop 0
	v_pk_fma_f32 v[8:9], v[64:65], v[48:49], v[8:9]
	v_pk_mul_f32 v[48:49], v[14:15], v[48:49]
	v_cvt_pk_bf16_f32 v8, v8, v9
	v_pk_fma_f32 v[44:45], v[64:65], v[44:45], v[48:49] neg_lo:[0,0,1] neg_hi:[0,0,1]
	v_pk_mul_f32 v[48:49], v[10:11], v[46:47]
	v_cvt_pk_bf16_f32 v44, v44, v45
	v_pk_fma_f32 v[48:49], v[12:13], v[50:51], v[48:49]
	v_pk_mul_f32 v[50:51], v[10:11], v[50:51]
	v_cvt_pk_bf16_f32 v9, v48, v49
	v_pk_fma_f32 v[46:47], v[12:13], v[46:47], v[50:51] neg_lo:[0,0,1] neg_hi:[0,0,1]
	v_add_u32_e32 v48, 0x2000, v66
	v_cvt_pk_bf16_f32 v45, v46, v47
	ds_write2_b64 v48, v[8:9], v[44:45] offset0:16 offset1:20
	v_mfma_f32_16x16x32_bf16 v[44:47], v[40:43], v[0:3], 0
	v_mfma_f32_16x16x32_bf16 v[40:43], v[40:43], v[4:7], 0
	s_nop 7
	v_pk_mul_f32 v[8:9], v[14:15], v[40:41]
	s_nop 0
	v_pk_fma_f32 v[8:9], v[64:65], v[44:45], v[8:9]
	v_pk_mul_f32 v[44:45], v[14:15], v[44:45]
	v_cvt_pk_bf16_f32 v8, v8, v9
	v_pk_fma_f32 v[40:41], v[64:65], v[40:41], v[44:45] neg_lo:[0,0,1] neg_hi:[0,0,1]
	v_pk_mul_f32 v[44:45], v[10:11], v[42:43]
	v_cvt_pk_bf16_f32 v40, v40, v41
	v_pk_fma_f32 v[44:45], v[12:13], v[46:47], v[44:45]
	v_pk_mul_f32 v[46:47], v[10:11], v[46:47]
	v_cvt_pk_bf16_f32 v9, v44, v45
	v_pk_fma_f32 v[42:43], v[12:13], v[42:43], v[46:47] neg_lo:[0,0,1] neg_hi:[0,0,1]
	s_nop 0
	v_cvt_pk_bf16_f32 v41, v42, v43
	ds_write2_b64 v48, v[8:9], v[40:41] offset0:146 offset1:150
	v_mfma_f32_16x16x32_bf16 v[40:43], v[36:39], v[0:3], 0
	v_mfma_f32_16x16x32_bf16 v[36:39], v[36:39], v[4:7], 0
	s_nop 7
	v_pk_mul_f32 v[8:9], v[14:15], v[36:37]
	s_nop 0
	v_pk_fma_f32 v[8:9], v[64:65], v[40:41], v[8:9]
	v_pk_mul_f32 v[40:41], v[14:15], v[40:41]
	v_cvt_pk_bf16_f32 v8, v8, v9
	v_pk_fma_f32 v[36:37], v[64:65], v[36:37], v[40:41] neg_lo:[0,0,1] neg_hi:[0,0,1]
	v_pk_mul_f32 v[40:41], v[10:11], v[38:39]
	v_cvt_pk_bf16_f32 v36, v36, v37
	v_pk_fma_f32 v[40:41], v[12:13], v[42:43], v[40:41]
	v_pk_mul_f32 v[42:43], v[10:11], v[42:43]
	v_cvt_pk_bf16_f32 v9, v40, v41
; #define LAS __attribute__((address_space(3)))
; __device__ __forceinline__ unsigned cvtpk(float lo, float hi) { f32x2 v = {lo, hi}; bf16x2_t b = __builtin_convertvector(v, bf16x2_t); return __builtin_bit_cast(unsigned, b); }
; __device__ __forceinline__ void b_unit(Frame& F, int u, bool dry) {
;     ...
;         for (int i = 0; i < 16; ++i) {
;             u32x4 f4; f4.x = q0[i].x; f4.y = q0[i].y; f4.z = q1[i].x; f4.w = q1[i].y;
;             const bf16x8 frag = __builtin_bit_cast(bf16x8, f4);
;             const f32x4 dr = __builtin_amdgcn_mfma_f32_16x16x32_bf16(frag, Wr, zero4, 0, 0, 0), di = __builtin_amdgcn_mfma_f32_16x16x32_bf16(frag, Wi, zero4, 0, 0, 0);
;             float vr[4], vi[4];
; #pragma unroll
;             for (int j = 0; j < 4; ++j) { vr[j] = dr[j] * t2[j].x + di[j] * t2[j].y; vi[j] = di[j] * t2[j].x - dr[j] * t2[j].y; }
;             u32x2 o; o.x = cvtpk(vr[0], vr[1]); o.y = cvtpk(vr[2], vr[3]); *(LAS u32x2*)(vrow + i * 1040) = o;
;             o.x = cvtpk(vi[0], vi[1]); o.y = cvtpk(vi[2], vi[3]); *(LAS u32x2*)(vrow + i * 1040 + 32) = o;
;         }
;         __syncthreads();
; #pragma unroll
;         for (int cc = 0; cc < 2; ++cc)
; #pragma unroll
;             for (int lb = 0; lb < 8; ++lb) {
;                 const bf16x8 frag = *(const LAS bf16x8*)(Bt + (size_t)(16 * lb + fr) * 1040 + 64 * (2 * w + cc) + 16 * fq);
;                 ur[cc][lb] = __builtin_amdgcn_mfma_f32_16x16x32_bf16(frag, Wr, zero4, 0, 0, 0);
;                 ui[cc][lb] = __builtin_amdgcn_mfma_f32_16x16x32_bf16(frag, Wi, zero4, 0, 0, 0);
;             }
	v_pk_fma_f32 v[38:39], v[12:13], v[38:39], v[42:43] neg_lo:[0,0,1] neg_hi:[0,0,1]
	v_add_u32_e32 v40, 0x2800, v66
	v_cvt_pk_bf16_f32 v37, v38, v39
	ds_write2_b64 v40, v[8:9], v[36:37] offset0:20 offset1:24
	v_mfma_f32_16x16x32_bf16 v[36:39], v[32:35], v[0:3], 0
	v_mfma_f32_16x16x32_bf16 v[32:35], v[32:35], v[4:7], 0
	s_nop 7
	v_pk_mul_f32 v[8:9], v[14:15], v[32:33]
	s_nop 0
	v_pk_fma_f32 v[8:9], v[64:65], v[36:37], v[8:9]
	v_pk_mul_f32 v[36:37], v[14:15], v[36:37]
	v_cvt_pk_bf16_f32 v8, v8, v9
	v_pk_fma_f32 v[32:33], v[64:65], v[32:33], v[36:37] neg_lo:[0,0,1] neg_hi:[0,0,1]
	v_pk_mul_f32 v[36:37], v[10:11], v[34:35]
	v_cvt_pk_bf16_f32 v32, v32, v33
	v_pk_fma_f32 v[36:37], v[12:13], v[38:39], v[36:37]
	v_pk_mul_f32 v[38:39], v[10:11], v[38:39]
	v_cvt_pk_bf16_f32 v9, v36, v37
	v_pk_fma_f32 v[34:35], v[12:13], v[34:35], v[38:39] neg_lo:[0,0,1] neg_hi:[0,0,1]
	s_nop 0
	v_cvt_pk_bf16_f32 v33, v34, v35
	ds_write2_b64 v40, v[8:9], v[32:33] offset0:150 offset1:154
	v_mfma_f32_16x16x32_bf16 v[32:35], v[28:31], v[0:3], 0
	v_mov_b32_e32 v40, 0x14500
	v_mad_u32_u24 v118, v77, s6, v40
	v_mfma_f32_16x16x32_bf16 v[28:31], v[28:31], v[4:7], 0
	s_nop 7
	v_pk_mul_f32 v[8:9], v[14:15], v[28:29]
	s_nop 0
	v_pk_fma_f32 v[8:9], v[64:65], v[32:33], v[8:9]
	v_pk_mul_f32 v[32:33], v[14:15], v[32:33]
	v_cvt_pk_bf16_f32 v8, v8, v9
	v_pk_fma_f32 v[28:29], v[64:65], v[28:29], v[32:33] neg_lo:[0,0,1] neg_hi:[0,0,1]
	v_pk_mul_f32 v[32:33], v[10:11], v[30:31]
	v_cvt_pk_bf16_f32 v28, v28, v29
	v_pk_fma_f32 v[32:33], v[12:13], v[34:35], v[32:33]
	v_pk_mul_f32 v[34:35], v[10:11], v[34:35]
	v_cvt_pk_bf16_f32 v9, v32, v33
	v_pk_fma_f32 v[30:31], v[12:13], v[30:31], v[34:35] neg_lo:[0,0,1] neg_hi:[0,0,1]
	v_add_u32_e32 v32, 0x3000, v66
	v_cvt_pk_bf16_f32 v29, v30, v31
	ds_write2_b64 v32, v[8:9], v[28:29] offset0:24 offset1:28
	v_mfma_f32_16x16x32_bf16 v[28:31], v[24:27], v[0:3], 0
	v_mfma_f32_16x16x32_bf16 v[24:27], v[24:27], v[4:7], 0
	s_nop 7
	v_pk_mul_f32 v[8:9], v[14:15], v[24:25]
	s_nop 0
	v_pk_fma_f32 v[8:9], v[64:65], v[28:29], v[8:9]
	v_pk_mul_f32 v[28:29], v[14:15], v[28:29]
	v_cvt_pk_bf16_f32 v8, v8, v9
	v_pk_fma_f32 v[24:25], v[64:65], v[24:25], v[28:29] neg_lo:[0,0,1] neg_hi:[0,0,1]
	v_pk_mul_f32 v[28:29], v[10:11], v[26:27]
	v_cvt_pk_bf16_f32 v24, v24, v25
	v_pk_fma_f32 v[28:29], v[12:13], v[30:31], v[28:29]
	v_pk_mul_f32 v[30:31], v[10:11], v[30:31]
	v_cvt_pk_bf16_f32 v9, v28, v29
	v_pk_fma_f32 v[26:27], v[12:13], v[26:27], v[30:31] neg_lo:[0,0,1] neg_hi:[0,0,1]
	s_nop 0
	v_cvt_pk_bf16_f32 v25, v26, v27
	ds_write2_b64 v32, v[8:9], v[24:25] offset0:154 offset1:158
	v_mfma_f32_16x16x32_bf16 v[24:27], v[20:23], v[0:3], 0
	v_mfma_f32_16x16x32_bf16 v[20:23], v[20:23], v[4:7], 0
	s_nop 7
	v_pk_mul_f32 v[8:9], v[14:15], v[20:21]
	s_nop 0
	v_pk_fma_f32 v[8:9], v[64:65], v[24:25], v[8:9]
	v_pk_mul_f32 v[24:25], v[14:15], v[24:25]
	v_cvt_pk_bf16_f32 v8, v8, v9
	v_pk_fma_f32 v[20:21], v[64:65], v[20:21], v[24:25] neg_lo:[0,0,1] neg_hi:[0,0,1]
	v_pk_mul_f32 v[24:25], v[10:11], v[22:23]
	v_cvt_pk_bf16_f32 v20, v20, v21
	v_pk_fma_f32 v[24:25], v[12:13], v[26:27], v[24:25]
	v_pk_mul_f32 v[26:27], v[10:11], v[26:27]
	v_cvt_pk_bf16_f32 v9, v24, v25
	v_pk_fma_f32 v[22:23], v[12:13], v[22:23], v[26:27] neg_lo:[0,0,1] neg_hi:[0,0,1]
	v_add_u32_e32 v24, 0x3800, v66
	v_cvt_pk_bf16_f32 v21, v22, v23
	ds_write2_b64 v24, v[8:9], v[20:21] offset0:28 offset1:32
	v_mfma_f32_16x16x32_bf16 v[20:23], v[16:19], v[0:3], 0
	v_mfma_f32_16x16x32_bf16 v[16:19], v[16:19], v[4:7], 0
	s_nop 7
	v_pk_mul_f32 v[8:9], v[14:15], v[16:17]
	v_pk_mul_f32 v[14:15], v[14:15], v[20:21]
	v_pk_fma_f32 v[8:9], v[64:65], v[20:21], v[8:9]
	v_pk_fma_f32 v[14:15], v[64:65], v[16:17], v[14:15] neg_lo:[0,0,1] neg_hi:[0,0,1]
	v_pk_mul_f32 v[16:17], v[10:11], v[18:19]
	v_pk_mul_f32 v[10:11], v[10:11], v[22:23]
	v_pk_fma_f32 v[16:17], v[12:13], v[22:23], v[16:17]
	v_pk_fma_f32 v[10:11], v[12:13], v[18:19], v[10:11] neg_lo:[0,0,1] neg_hi:[0,0,1]
	v_cvt_pk_bf16_f32 v8, v8, v9
	v_cvt_pk_bf16_f32 v9, v16, v17
	v_cvt_pk_bf16_f32 v12, v14, v15
	v_cvt_pk_bf16_f32 v13, v10, v11
	ds_write2_b64 v24, v[8:9], v[12:13] offset0:158 offset1:162
	v_and_b32_e32 v8, 48, v170
	v_mov_b32_e32 v16, 0x10400
	v_add_u32_e32 v78, s0, v8
	v_mad_u32_u24 v110, v77, s6, v16
	v_add_u32_e32 v16, v78, v110
	v_add_u32_e32 v40, v78, v118
	s_waitcnt lgkmcnt(0)
	s_barrier
	ds_read_b128 v[16:19], v16
	ds_read_b128 v[40:43], v40
	s_waitcnt lgkmcnt(0)
	v_mfma_f32_16x16x32_bf16 v[64:67], v[40:43], v[0:3], 0
	v_add_u32_e32 v52, v78, v134
	ds_read_b128 v[52:55], v52
	v_mad_u32_u24 v102, v77, s6, v78
	v_mfma_f32_16x16x32_bf16 v[56:59], v[40:43], v[4:7], 0
	v_mov_b32_e32 v40, 0x18600
	v_mad_u32_u24 v126, v77, s6, v40
	v_add_u32_e32 v40, v78, v126
	ds_read_b128 v[40:43], v40
	ds_read_b128 v[8:11], v102
	s_waitcnt lgkmcnt(2)
	v_mfma_f32_16x16x32_bf16 v[72:75], v[52:55], v[0:3], 0
	v_add_u32_e32 v135, 64, v78
	ds_read_b128 v[12:15], v102 offset:49920
	s_mov_b32 s0, 0x1dd6000
	v_mfma_f32_16x16x32_bf16 v[68:71], v[52:55], v[4:7], 0
	ds_read_b128 v[52:55], v102 offset:64
	s_waitcnt lgkmcnt(2)
	v_mfma_f32_16x16x32_bf16 v[36:39], v[8:11], v[0:3], 0
	v_mfma_f32_16x16x32_bf16 v[20:23], v[8:11], v[4:7], 0
	ds_read_b128 v[8:11], v102 offset:16640
	s_waitcnt lgkmcnt(1)
	v_mfma_f32_16x16x32_bf16 v[78:81], v[52:55], v[0:3], 0
	v_mfma_f32_16x16x32_bf16 v[82:85], v[52:55], v[4:7], 0
	ds_read_b128 v[52:55], v102 offset:16704
	s_waitcnt lgkmcnt(1)
	v_mfma_f32_16x16x32_bf16 v[48:51], v[8:11], v[0:3], 0
	v_mfma_f32_16x16x32_bf16 v[24:27], v[8:11], v[4:7], 0
	ds_read_b128 v[8:11], v102 offset:33280
	s_waitcnt lgkmcnt(1)
	v_mfma_f32_16x16x32_bf16 v[86:89], v[52:55], v[0:3], 0
	v_mfma_f32_16x16x32_bf16 v[90:93], v[52:55], v[4:7], 0
	ds_read_b128 v[52:55], v102 offset:33344
	s_waitcnt lgkmcnt(0)
	v_mfma_f32_16x16x32_bf16 v[94:97], v[52:55], v[0:3], 0
	v_mfma_f32_16x16x32_bf16 v[98:101], v[52:55], v[4:7], 0
	ds_read_b128 v[52:55], v102 offset:49984
	s_waitcnt lgkmcnt(0)
	v_mfma_f32_16x16x32_bf16 v[102:105], v[52:55], v[0:3], 0
	v_mfma_f32_16x16x32_bf16 v[106:109], v[52:55], v[4:7], 0
	v_add_u32_e32 v52, v135, v110
	ds_read_b128 v[52:55], v52
	s_waitcnt lgkmcnt(0)
	v_mfma_f32_16x16x32_bf16 v[110:113], v[52:55], v[0:3], 0
	v_mfma_f32_16x16x32_bf16 v[114:117], v[52:55], v[4:7], 0
	v_add_u32_e32 v52, v135, v118
	ds_read_b128 v[52:55], v52
	s_waitcnt lgkmcnt(0)
	v_mfma_f32_16x16x32_bf16 v[118:121], v[52:55], v[0:3], 0
	v_mfma_f32_16x16x32_bf16 v[122:125], v[52:55], v[4:7], 0
	v_add_u32_e32 v52, v135, v126
	ds_read_b128 v[52:55], v52
	s_waitcnt lgkmcnt(0)
	v_mfma_f32_16x16x32_bf16 v[126:129], v[52:55], v[0:3], 0
	v_mfma_f32_16x16x32_bf16 v[130:133], v[52:55], v[4:7], 0
	v_add_u32_e32 v52, v135, v134
	ds_read_b128 v[52:55], v52
	s_waitcnt lgkmcnt(0)
	v_mfma_f32_16x16x32_bf16 v[44:47], v[16:19], v[0:3], 0
	s_barrier
; #define LAS __attribute__((address_space(3)))
; #define GAS __attribute__((address_space(1)))
; __device__ __forceinline__ unsigned cvtpk(float lo, float hi) { f32x2 v = {lo, hi}; bf16x2_t b = __builtin_convertvector(v, bf16x2_t); return __builtin_bit_cast(unsigned, b); }
; __device__ __forceinline__ void b_unit(Frame& F, int u, bool dry) {
;     ...
;     bf16x8 yr[2][4], yi[2][4];
; #pragma unroll
;     for (int mb = 0; mb < 2; ++mb)
; #pragma unroll
;         for (int t = 0; t < 4; ++t) {
;             u32x4 p; p.x = cvtpk(ur[mb][2 * t][0], ur[mb][2 * t][1]); p.y = cvtpk(ur[mb][2 * t][2], ur[mb][2 * t][3]); p.z = cvtpk(ur[mb][2 * t + 1][0], ur[mb][2 * t + 1][1]); p.w = cvtpk(ur[mb][2 * t + 1][2], ur[mb][2 * t + 1][3]);
;             yr[mb][t] = __builtin_bit_cast(bf16x8, p);
;             p.x = cvtpk(ui[mb][2 * t][0], ui[mb][2 * t][1]); p.y = cvtpk(ui[mb][2 * t][2], ui[mb][2 * t][3]); p.z = cvtpk(ui[mb][2 * t + 1][0], ui[mb][2 * t + 1][1]); p.w = cvtpk(ui[mb][2 * t + 1][2], ui[mb][2 * t + 1][3]);
;             yi[mb][t] = __builtin_bit_cast(bf16x8, p);
;         }
;     bf16_t* SBG = (bf16_t*)(ws_ + WS_SBG);
;     __syncthreads();
;     {   const GAS u32x4* src = (const GAS u32x4*)(ws_ + WS_GT) + (w * 64 + lane); u32x4 tv[8];
; #pragma unroll
;         for (int i = 0; i < 8; ++i) tv[i] = src[i * 512];
; #pragma unroll
;         for (int i = 0; i < 8; ++i) *(LAS u32x4*)(Bt + (size_t)(i * 512 + w * 64 + lane) * 16) = tv[i]; }
;     u32x4 sbq[4][2];
; #pragma unroll
;     for (int p = 0; p < 4; ++p)
; #pragma unroll
;         for (int mb = 0; mb < 2; ++mb) { const int k1 = 2 * w + mb + 16 * fr; const size_t tok = (size_t)b * SEQ + 8 * k1 + k2; sbq[p][mb] = *(const GAS u32x4*)(SBG + tok * 512 + g * 128 + 32 * p + 8 * fq); }
	v_mfma_f32_16x16x32_bf16 v[60:63], v[40:43], v[0:3], 0
	v_mfma_f32_16x16x32_bf16 v[40:43], v[40:43], v[4:7], 0
	v_mfma_f32_16x16x32_bf16 v[134:137], v[52:55], v[0:3], 0
	v_mfma_f32_16x16x32_bf16 v[138:141], v[52:55], v[4:7], 0
	v_cvt_pk_bf16_f32 v54, v48, v49
	v_cvt_pk_bf16_f32 v48, v20, v21
	s_nop 0
	v_cvt_pk_bf16_f32 v20, v44, v45
	v_cvt_pk_bf16_f32 v44, v98, v99
	v_or_b32_e32 v98, s70, v171
	v_ashrrev_i32_e32 v99, 31, v98
	v_mfma_f32_16x16x32_bf16 v[28:31], v[8:11], v[0:3], 0
	v_cvt_pk_bf16_f32 v49, v22, v23
	v_cvt_pk_bf16_f32 v22, v64, v65
	v_cvt_pk_bf16_f32 v53, v38, v39
	v_mfma_f32_16x16x32_bf16 v[32:35], v[12:15], v[0:3], 0
	v_cvt_pk_bf16_f32 v0, v40, v41
	v_cvt_pk_bf16_f32 v40, v94, v95
	v_lshl_add_u64 v[94:95], v[98:99], 4, s[2:3]
	v_mfma_f32_16x16x32_bf16 v[8:11], v[8:11], v[4:7], 0
	v_add_co_u32_e32 v64, vcc, s8, v94
	v_cvt_pk_bf16_f32 v2, v68, v69
	s_nop 0
	v_addc_co_u32_e32 v65, vcc, 0, v95, vcc
	v_mfma_f32_16x16x32_bf16 v[16:19], v[16:19], v[4:7], 0
	v_add_co_u32_e32 v68, vcc, s0, v94
	s_mov_b32 s0, 0x1dd8000
	s_nop 0
	v_addc_co_u32_e32 v69, vcc, 0, v95, vcc
	v_cvt_pk_bf16_f32 v38, v32, v33
	v_cvt_pk_bf16_f32 v33, v10, v11
	v_cvt_pk_bf16_f32 v10, v72, v73
	v_add_co_u32_e32 v72, vcc, s0, v94
	s_mov_b32 s0, 0x1dda000
	s_nop 0
	v_addc_co_u32_e32 v73, vcc, 0, v95, vcc
	v_cvt_pk_bf16_f32 v16, v16, v17
	v_cvt_pk_bf16_f32 v17, v18, v19
	v_cvt_pk_bf16_f32 v18, v56, v57
	v_cvt_pk_bf16_f32 v56, v78, v79
	v_add_co_u32_e32 v78, vcc, s0, v94
	s_mov_b32 s0, 0x1ddc000
	s_nop 0
	v_addc_co_u32_e32 v79, vcc, 0, v95, vcc
	v_cvt_pk_bf16_f32 v32, v8, v9
	v_cvt_pk_bf16_f32 v8, v60, v61
	v_cvt_pk_bf16_f32 v60, v82, v83
	v_add_co_u32_e32 v82, vcc, s0, v94
	v_cvt_pk_bf16_f32 v23, v66, v67
	global_load_dwordx4 v[64:67], v[64:65], off offset:64
	v_addc_co_u32_e32 v83, vcc, 0, v95, vcc
	s_mov_b32 s0, 0x1dde000
	v_cvt_pk_bf16_f32 v19, v58, v59
	v_cvt_pk_bf16_f32 v3, v70, v71
	v_cvt_pk_bf16_f32 v58, v86, v87
	global_load_dwordx4 v[68:71], v[68:69], off offset:64
	v_add_co_u32_e32 v86, vcc, s0, v94
	v_cvt_pk_bf16_f32 v11, v74, v75
	global_load_dwordx4 v[72:75], v[72:73], off offset:64
	v_addc_co_u32_e32 v87, vcc, 0, v95, vcc
	s_mov_b32 s0, 0x1de0000
	v_cvt_pk_bf16_f32 v9, v62, v63
	v_cvt_pk_bf16_f32 v57, v80, v81
	v_cvt_pk_bf16_f32 v62, v90, v91
	global_load_dwordx4 v[78:81], v[78:79], off offset:64
	v_add_co_u32_e32 v90, vcc, s0, v94
	v_cvt_pk_bf16_f32 v61, v84, v85
	global_load_dwordx4 v[82:85], v[82:83], off offset:64
	v_addc_co_u32_e32 v91, vcc, 0, v95, vcc
	s_mov_b32 s0, 0x1de2000
	v_cvt_pk_bf16_f32 v59, v88, v89
	global_load_dwordx4 v[86:89], v[86:87], off offset:64
	v_add_co_u32_e32 v94, vcc, s0, v94
	v_cvt_pk_bf16_f32 v63, v92, v93
	global_load_dwordx4 v[90:93], v[90:91], off offset:64
	v_addc_co_u32_e32 v95, vcc, 0, v95, vcc
	v_cvt_pk_bf16_f32 v41, v96, v97
	global_load_dwordx4 v[94:97], v[94:95], off offset:64
	v_lshl_add_u32 v98, v98, 4, 0
	v_readlane_b32 s0, v253, 51
	s_waitcnt vmcnt(7)
	ds_write_b128 v98, v[64:67]
	s_waitcnt vmcnt(6)
	ds_write_b128 v98, v[68:71] offset:8192
	s_waitcnt vmcnt(5)
	ds_write_b128 v98, v[72:75] offset:16384
	s_waitcnt vmcnt(4)
	ds_write_b128 v98, v[78:81] offset:24576
	s_waitcnt vmcnt(3)
	ds_write_b128 v98, v[82:85] offset:32768
	s_waitcnt vmcnt(2)
	ds_write_b128 v98, v[86:89] offset:40960
	s_waitcnt vmcnt(1)
	ds_write_b128 v98, v[90:93] offset:49152
	s_waitcnt vmcnt(0)
	ds_write_b128 v98, v[94:97] offset:57344
	v_lshl_add_u32 v64, v77, 7, s0
	v_readlane_b32 s0, v254, 31
	s_add_u32 s0, s2, s0
	s_addc_u32 s1, s3, 0
	v_lshl_add_u64 v[66:67], s[0:1], 0, v[192:193]
	s_mov_b64 s[0:1], 0xa000000
	v_lshl_add_u64 v[66:67], v[66:67], 0, s[0:1]
	v_readlane_b32 s0, v254, 21
	v_mov_b32_e32 v65, v193
	v_readlane_b32 s1, v254, 22
	v_or_b32_e32 v192, 8, v64
	v_cvt_pk_bf16_f32 v45, v100, v101
	v_lshl_add_u64 v[68:69], s[0:1], 0, v[64:65]
	v_lshlrev_b64 v[68:69], 10, v[68:69]
	v_lshl_add_u64 v[98:99], v[66:67], 0, v[68:69]
	global_load_dwordx4 v[92:95], v[98:99], off sc1
	v_lshl_add_u64 v[64:65], s[0:1], 0, v[192:193]
	v_lshlrev_b32_e32 v100, 4, v170
	v_lshlrev_b64 v[64:65], 10, v[64:65]
	v_and_b32_e32 v100, 0x3f0, v100
	v_lshl_add_u64 v[96:97], v[66:67], 0, v[64:65]
	v_add_u32_e32 v100, 0, v100
	v_cvt_pk_bf16_f32 v21, v46, v47
	v_cvt_pk_bf16_f32 v1, v42, v43
	v_cvt_pk_bf16_f32 v42, v102, v103
	v_cvt_pk_bf16_f32 v43, v104, v105
	v_cvt_pk_bf16_f32 v46, v106, v107
	v_cvt_pk_bf16_f32 v47, v108, v109
	global_load_dwordx4 v[88:91], v[96:97], off sc1
	global_load_dwordx4 v[84:87], v[98:99], off offset:64 sc1
	global_load_dwordx4 v[80:83], v[96:97], off offset:64 sc1
	global_load_dwordx4 v[76:79], v[98:99], off offset:128 sc1
	global_load_dwordx4 v[72:75], v[96:97], off offset:128 sc1
	global_load_dwordx4 v[68:71], v[98:99], off offset:192 sc1
	global_load_dwordx4 v[64:67], v[96:97], off offset:192 sc1
	s_waitcnt lgkmcnt(0)
	s_barrier
; #define LAS __attribute__((address_space(3)))
; #define GAS __attribute__((address_space(1)))
; __device__ __forceinline__ unsigned cvtpk(float lo, float hi) { f32x2 v = {lo, hi}; bf16x2_t b = __builtin_convertvector(v, bf16x2_t); return __builtin_bit_cast(unsigned, b); }
; __device__ __forceinline__ float bflo(unsigned w) { return __uint_as_float(w << 16); }
; __device__ __forceinline__ float bfhi(unsigned w) { return __uint_as_float(w & 0xffff0000u); }
; __device__ __forceinline__ void b_unit(Frame& F, int u, bool dry) {
;     ...
;     const LAS unsigned char* XF = Bt + (size_t)(fq * 16 + fr) * 16;
; #pragma unroll
;     for (int p = 0; p < 4; ++p) {
;         f32x4 o3[2][2];
; #pragma unroll
;         for (int h = 0; h < 2; ++h) { const int lb = 2 * p + h;
;             o3[h][0] = (f32x4){0.f, 0.f, 0.f, 0.f}; o3[h][1] = (f32x4){0.f, 0.f, 0.f, 0.f};
; #pragma unroll
;             for (int t = 0; t < 4; ++t) {
;                 const bf16x8 xc = *(const LAS bf16x8*)(XF + (size_t)((lb * 4 + t) * 2 + 0) * 1024), xs = *(const LAS bf16x8*)(XF + (size_t)((lb * 4 + t) * 2 + 1) * 1024);
; #pragma unroll
;                 for (int mb = 0; mb < 2; ++mb) { o3[h][mb] = __builtin_amdgcn_mfma_f32_16x16x32_bf16(xc, yr[mb][t], o3[h][mb], 0, 0, 0); o3[h][mb] = __builtin_amdgcn_mfma_f32_16x16x32_bf16(xs, yi[mb][t], o3[h][mb], 0, 0, 0); }
;             }
;         }
; #pragma unroll
;         for (int mb = 0; mb < 2; ++mb) { const int k1 = 2 * w + mb + 16 * fr; const size_t tok = (size_t)b * SEQ + 8 * k1 + k2; const u32x4 sb = sbq[p][mb]; const f32x4 a0 = o3[0][mb] * 0.001953125f, a1 = o3[1][mb] * 0.001953125f;
;             u32x4 o; o.x = cvtpk(bflo(sb.x) * a0[0], bfhi(sb.x) * a0[1]); o.y = cvtpk(bflo(sb.y) * a0[2], bfhi(sb.y) * a0[3]); o.z = cvtpk(bflo(sb.z) * a1[0], bfhi(sb.z) * a1[1]); o.w = cvtpk(bflo(sb.w) * a1[2], bfhi(sb.w) * a1[3]);
;             if (!dry) *(GAS u32x4*)(SBG + tok * 512 + g * 128 + 32 * p + 8 * fq) = o; }
	ds_read_b128 v[102:105], v100
	ds_read_b128 v[106:109], v100 offset:1024
	v_cvt_pk_bf16_f32 v52, v36, v37
	v_cvt_pk_bf16_f32 v55, v50, v51
	v_cvt_pk_bf16_f32 v50, v24, v25
	v_cvt_pk_bf16_f32 v24, v110, v111
	v_cvt_pk_bf16_f32 v25, v112, v113
	s_waitcnt lgkmcnt(1)
	v_mfma_f32_16x16x32_bf16 v[110:113], v[102:105], v[52:55], 0
	v_cvt_pk_bf16_f32 v51, v26, v27
	v_cvt_pk_bf16_f32 v36, v28, v29
	v_cvt_pk_bf16_f32 v28, v114, v115
	v_mfma_f32_16x16x32_bf16 v[102:105], v[102:105], v[56:59], 0
	v_cvt_pk_bf16_f32 v29, v116, v117
	v_cvt_pk_bf16_f32 v37, v30, v31
	v_cvt_pk_bf16_f32 v39, v34, v35
	s_waitcnt lgkmcnt(0)
	v_mfma_f32_16x16x32_bf16 v[110:113], v[106:109], v[48:51], v[110:113]
	v_cvt_pk_bf16_f32 v26, v118, v119
	v_cvt_pk_bf16_f32 v27, v120, v121
	v_cvt_pk_bf16_f32 v30, v122, v123
	v_mfma_f32_16x16x32_bf16 v[102:105], v[106:109], v[60:63], v[102:105]
	ds_read_b128 v[106:109], v100 offset:2048
	ds_read_b128 v[114:117], v100 offset:3072
	v_cvt_pk_bf16_f32 v31, v124, v125
	s_mov_b32 s0, 0x3b000000
	v_mfma_f32_16x16x32_bf16 v[12:15], v[12:15], v[4:7], 0
	v_cvt_pk_bf16_f32 v4, v130, v131
	v_cvt_pk_bf16_f32 v5, v132, v133
	v_cvt_pk_bf16_f32 v6, v138, v139
	s_waitcnt lgkmcnt(1)
	v_mfma_f32_16x16x32_bf16 v[110:113], v[106:109], v[36:39], v[110:113]
	v_cvt_pk_bf16_f32 v7, v140, v141
	s_nop 1
	v_cvt_pk_bf16_f32 v34, v12, v13
	v_cvt_pk_bf16_f32 v35, v14, v15
	v_mfma_f32_16x16x32_bf16 v[102:105], v[106:109], v[40:43], v[102:105]
	v_cvt_pk_bf16_f32 v12, v126, v127
	v_cvt_pk_bf16_f32 v13, v128, v129
	v_cvt_pk_bf16_f32 v14, v134, v135
	s_waitcnt lgkmcnt(0)
	v_mfma_f32_16x16x32_bf16 v[110:113], v[114:117], v[32:35], v[110:113]
	v_cvt_pk_bf16_f32 v15, v136, v137
	v_mfma_f32_16x16x32_bf16 v[102:105], v[114:117], v[44:47], v[102:105]
	ds_read_b128 v[106:109], v100 offset:4096
	ds_read_b128 v[114:117], v100 offset:5120
	s_waitcnt lgkmcnt(1)
	v_mfma_f32_16x16x32_bf16 v[110:113], v[106:109], v[20:23], v[110:113]
	v_mfma_f32_16x16x32_bf16 v[102:105], v[106:109], v[24:27], v[102:105]
	s_waitcnt lgkmcnt(0)
	v_mfma_f32_16x16x32_bf16 v[110:113], v[114:117], v[16:19], v[110:113]
	v_mfma_f32_16x16x32_bf16 v[102:105], v[114:117], v[28:31], v[102:105]
	ds_read_b128 v[106:109], v100 offset:6144
	ds_read_b128 v[114:117], v100 offset:7168
	s_waitcnt lgkmcnt(1)
	v_mfma_f32_16x16x32_bf16 v[110:113], v[106:109], v[8:11], v[110:113]
	v_mfma_f32_16x16x32_bf16 v[102:105], v[106:109], v[12:15], v[102:105]
	s_waitcnt lgkmcnt(0)
	v_mfma_f32_16x16x32_bf16 v[110:113], v[114:117], v[0:3], v[110:113]
	v_mfma_f32_16x16x32_bf16 v[102:105], v[114:117], v[4:7], v[102:105]
	ds_read_b128 v[106:109], v100 offset:8192
	ds_read_b128 v[114:117], v100 offset:9216
	s_nop 4
	v_pk_mul_f32 v[110:111], v[110:111], s[0:1] op_sel_hi:[1,0]
	v_pk_mul_f32 v[112:113], v[112:113], s[0:1] op_sel_hi:[1,0]
	s_waitcnt lgkmcnt(1)
	v_mfma_f32_16x16x32_bf16 v[118:121], v[106:109], v[52:55], 0
	v_mfma_f32_16x16x32_bf16 v[106:109], v[106:109], v[56:59], 0
	s_waitcnt lgkmcnt(0)
	v_mfma_f32_16x16x32_bf16 v[118:121], v[114:117], v[48:51], v[118:121]
	v_mfma_f32_16x16x32_bf16 v[106:109], v[114:117], v[60:63], v[106:109]
	ds_read_b128 v[114:117], v100 offset:10240
	ds_read_b128 v[122:125], v100 offset:11264
	s_waitcnt lgkmcnt(1)
	v_mfma_f32_16x16x32_bf16 v[118:121], v[114:117], v[36:39], v[118:121]
	v_mfma_f32_16x16x32_bf16 v[106:109], v[114:117], v[40:43], v[106:109]
	s_waitcnt lgkmcnt(0)
	v_mfma_f32_16x16x32_bf16 v[118:121], v[122:125], v[32:35], v[118:121]
	v_mfma_f32_16x16x32_bf16 v[106:109], v[122:125], v[44:47], v[106:109]
	ds_read_b128 v[114:117], v100 offset:12288
	ds_read_b128 v[122:125], v100 offset:13312
	s_waitcnt lgkmcnt(1)
	v_mfma_f32_16x16x32_bf16 v[118:121], v[114:117], v[20:23], v[118:121]
	v_mfma_f32_16x16x32_bf16 v[106:109], v[114:117], v[24:27], v[106:109]
	s_waitcnt lgkmcnt(0)
	v_mfma_f32_16x16x32_bf16 v[118:121], v[122:125], v[16:19], v[118:121]
	v_mfma_f32_16x16x32_bf16 v[106:109], v[122:125], v[28:31], v[106:109]
	ds_read_b128 v[114:117], v100 offset:14336
	ds_read_b128 v[122:125], v100 offset:15360
	s_waitcnt lgkmcnt(1)
	v_mfma_f32_16x16x32_bf16 v[118:121], v[114:117], v[8:11], v[118:121]
	s_waitcnt lgkmcnt(0)
	v_mfma_f32_16x16x32_bf16 v[118:121], v[122:125], v[0:3], v[118:121]
	v_mfma_f32_16x16x32_bf16 v[106:109], v[114:117], v[12:15], v[106:109]
	v_mfma_f32_16x16x32_bf16 v[106:109], v[122:125], v[4:7], v[106:109]
	s_nop 5
	v_mul_f32_e64 v116, v118, s0
	v_mul_f32_e64 v117, v119, s0
	s_waitcnt vmcnt(7)
	v_lshlrev_b32_e32 v118, 16, v92
	v_and_b32_e32 v119, 0xffff0000, v92
	v_pk_mul_f32 v[110:111], v[110:111], v[118:119]
	v_pk_mul_f32 v[114:115], v[120:121], s[0:1] op_sel_hi:[1,0]
	v_cvt_pk_bf16_f32 v92, v110, v111
	v_lshlrev_b32_e32 v110, 16, v93
	v_and_b32_e32 v111, 0xffff0000, v93
	v_pk_mul_f32 v[110:111], v[112:113], v[110:111]
	s_nop 0
	v_cvt_pk_bf16_f32 v93, v110, v111
	v_lshlrev_b32_e32 v110, 16, v94
	v_and_b32_e32 v111, 0xffff0000, v94
	v_pk_mul_f32 v[110:111], v[116:117], v[110:111]
	s_nop 0
	v_cvt_pk_bf16_f32 v94, v110, v111
	v_lshlrev_b32_e32 v110, 16, v95
	v_and_b32_e32 v111, 0xffff0000, v95
	v_pk_mul_f32 v[110:111], v[114:115], v[110:111]
	s_nop 0
	v_cvt_pk_bf16_f32 v95, v110, v111
	global_store_dwordx4 v[98:99], v[92:95], off
	s_nop 1
	v_pk_mul_f32 v[92:93], v[104:105], s[0:1] op_sel_hi:[1,0]
	v_pk_mul_f32 v[94:95], v[102:103], s[0:1] op_sel_hi:[1,0]
	v_pk_mul_f32 v[104:105], v[106:107], s[0:1] op_sel_hi:[1,0]
	s_waitcnt vmcnt(7)
; #define LAS __attribute__((address_space(3)))
; #define GAS __attribute__((address_space(1)))
; __device__ __forceinline__ unsigned cvtpk(float lo, float hi) { f32x2 v = {lo, hi}; bf16x2_t b = __builtin_convertvector(v, bf16x2_t); return __builtin_bit_cast(unsigned, b); }
; __device__ __forceinline__ float bflo(unsigned w) { return __uint_as_float(w << 16); }
; __device__ __forceinline__ float bfhi(unsigned w) { return __uint_as_float(w & 0xffff0000u); }
; __device__ __forceinline__ void b_unit(Frame& F, int u, bool dry) {
;     ...
;     for (int p = 0; p < 4; ++p) {
;         f32x4 o3[2][2];
; #pragma unroll
;         for (int h = 0; h < 2; ++h) { const int lb = 2 * p + h;
;             o3[h][0] = (f32x4){0.f, 0.f, 0.f, 0.f}; o3[h][1] = (f32x4){0.f, 0.f, 0.f, 0.f};
; #pragma unroll
;             for (int t = 0; t < 4; ++t) {
;                 const bf16x8 xc = *(const LAS bf16x8*)(XF + (size_t)((lb * 4 + t) * 2 + 0) * 1024), xs = *(const LAS bf16x8*)(XF + (size_t)((lb * 4 + t) * 2 + 1) * 1024);
; #pragma unroll
;                 for (int mb = 0; mb < 2; ++mb) { o3[h][mb] = __builtin_amdgcn_mfma_f32_16x16x32_bf16(xc, yr[mb][t], o3[h][mb], 0, 0, 0); o3[h][mb] = __builtin_amdgcn_mfma_f32_16x16x32_bf16(xs, yi[mb][t], o3[h][mb], 0, 0, 0); }
;             }
;         }
; #pragma unroll
;         for (int mb = 0; mb < 2; ++mb) { const int k1 = 2 * w + mb + 16 * fr; const size_t tok = (size_t)b * SEQ + 8 * k1 + k2; const u32x4 sb = sbq[p][mb]; const f32x4 a0 = o3[0][mb] * 0.001953125f, a1 = o3[1][mb] * 0.001953125f;
;             u32x4 o; o.x = cvtpk(bflo(sb.x) * a0[0], bfhi(sb.x) * a0[1]); o.y = cvtpk(bflo(sb.y) * a0[2], bfhi(sb.y) * a0[3]); o.z = cvtpk(bflo(sb.z) * a1[0], bfhi(sb.z) * a1[1]); o.w = cvtpk(bflo(sb.w) * a1[2], bfhi(sb.w) * a1[3]);
;             if (!dry) *(GAS u32x4*)(SBG + tok * 512 + g * 128 + 32 * p + 8 * fq) = o; }
	v_lshlrev_b32_e32 v106, 16, v88
	v_and_b32_e32 v107, 0xffff0000, v88
	v_pk_mul_f32 v[94:95], v[94:95], v[106:107]
	v_pk_mul_f32 v[102:103], v[108:109], s[0:1] op_sel_hi:[1,0]
	v_cvt_pk_bf16_f32 v88, v94, v95
	v_lshlrev_b32_e32 v94, 16, v89
	v_and_b32_e32 v95, 0xffff0000, v89
	v_pk_mul_f32 v[92:93], v[92:93], v[94:95]
	s_nop 0
	v_cvt_pk_bf16_f32 v89, v92, v93
	v_lshlrev_b32_e32 v92, 16, v90
	v_and_b32_e32 v93, 0xffff0000, v90
	v_pk_mul_f32 v[92:93], v[104:105], v[92:93]
	s_nop 0
	v_cvt_pk_bf16_f32 v90, v92, v93
	v_lshlrev_b32_e32 v92, 16, v91
	v_and_b32_e32 v93, 0xffff0000, v91
	v_pk_mul_f32 v[92:93], v[102:103], v[92:93]
	s_nop 0
	v_cvt_pk_bf16_f32 v91, v92, v93
	global_store_dwordx4 v[96:97], v[88:91], off
	ds_read_b128 v[88:91], v100 offset:16384
	ds_read_b128 v[92:95], v100 offset:17408
	s_waitcnt lgkmcnt(1)
	v_mfma_f32_16x16x32_bf16 v[102:105], v[88:91], v[52:55], 0
	v_mfma_f32_16x16x32_bf16 v[88:91], v[88:91], v[56:59], 0
	s_waitcnt lgkmcnt(0)
	v_mfma_f32_16x16x32_bf16 v[102:105], v[92:95], v[48:51], v[102:105]
	v_mfma_f32_16x16x32_bf16 v[88:91], v[92:95], v[60:63], v[88:91]
	ds_read_b128 v[92:95], v100 offset:18432
	ds_read_b128 v[106:109], v100 offset:19456
	s_waitcnt lgkmcnt(1)
	v_mfma_f32_16x16x32_bf16 v[102:105], v[92:95], v[36:39], v[102:105]
	v_mfma_f32_16x16x32_bf16 v[88:91], v[92:95], v[40:43], v[88:91]
	s_waitcnt lgkmcnt(0)
	v_mfma_f32_16x16x32_bf16 v[102:105], v[106:109], v[32:35], v[102:105]
	v_mfma_f32_16x16x32_bf16 v[88:91], v[106:109], v[44:47], v[88:91]
	ds_read_b128 v[92:95], v100 offset:20480
	ds_read_b128 v[106:109], v100 offset:21504
	s_waitcnt lgkmcnt(1)
	v_mfma_f32_16x16x32_bf16 v[102:105], v[92:95], v[20:23], v[102:105]
	v_mfma_f32_16x16x32_bf16 v[88:91], v[92:95], v[24:27], v[88:91]
	s_waitcnt lgkmcnt(0)
	v_mfma_f32_16x16x32_bf16 v[102:105], v[106:109], v[16:19], v[102:105]
	v_mfma_f32_16x16x32_bf16 v[88:91], v[106:109], v[28:31], v[88:91]
	ds_read_b128 v[92:95], v100 offset:22528
	ds_read_b128 v[106:109], v100 offset:23552
	s_waitcnt lgkmcnt(1)
	v_mfma_f32_16x16x32_bf16 v[102:105], v[92:95], v[8:11], v[102:105]
	v_mfma_f32_16x16x32_bf16 v[88:91], v[92:95], v[12:15], v[88:91]
	s_waitcnt lgkmcnt(0)
	v_mfma_f32_16x16x32_bf16 v[102:105], v[106:109], v[0:3], v[102:105]
	v_mfma_f32_16x16x32_bf16 v[88:91], v[106:109], v[4:7], v[88:91]
	ds_read_b128 v[92:95], v100 offset:24576
	ds_read_b128 v[106:109], v100 offset:25600
	s_nop 4
	v_pk_mul_f32 v[102:103], v[102:103], s[0:1] op_sel_hi:[1,0]
	v_pk_mul_f32 v[104:105], v[104:105], s[0:1] op_sel_hi:[1,0]
	s_waitcnt lgkmcnt(1)
	v_mfma_f32_16x16x32_bf16 v[110:113], v[92:95], v[52:55], 0
	v_mfma_f32_16x16x32_bf16 v[92:95], v[92:95], v[56:59], 0
	s_waitcnt lgkmcnt(0)
	v_mfma_f32_16x16x32_bf16 v[110:113], v[106:109], v[48:51], v[110:113]
	v_mfma_f32_16x16x32_bf16 v[92:95], v[106:109], v[60:63], v[92:95]
	ds_read_b128 v[106:109], v100 offset:26624
	ds_read_b128 v[114:117], v100 offset:27648
	s_waitcnt lgkmcnt(1)
	v_mfma_f32_16x16x32_bf16 v[110:113], v[106:109], v[36:39], v[110:113]
	v_mfma_f32_16x16x32_bf16 v[92:95], v[106:109], v[40:43], v[92:95]
	s_waitcnt lgkmcnt(0)
	v_mfma_f32_16x16x32_bf16 v[110:113], v[114:117], v[32:35], v[110:113]
	v_mfma_f32_16x16x32_bf16 v[92:95], v[114:117], v[44:47], v[92:95]
	ds_read_b128 v[106:109], v100 offset:28672
	ds_read_b128 v[114:117], v100 offset:29696
	s_waitcnt lgkmcnt(1)
	v_mfma_f32_16x16x32_bf16 v[110:113], v[106:109], v[20:23], v[110:113]
	v_mfma_f32_16x16x32_bf16 v[92:95], v[106:109], v[24:27], v[92:95]
	s_waitcnt lgkmcnt(0)
	v_mfma_f32_16x16x32_bf16 v[110:113], v[114:117], v[16:19], v[110:113]
	v_mfma_f32_16x16x32_bf16 v[92:95], v[114:117], v[28:31], v[92:95]
	ds_read_b128 v[106:109], v100 offset:30720
	ds_read_b128 v[114:117], v100 offset:31744
	s_waitcnt lgkmcnt(1)
	v_mfma_f32_16x16x32_bf16 v[110:113], v[106:109], v[8:11], v[110:113]
	s_waitcnt lgkmcnt(0)
	v_mfma_f32_16x16x32_bf16 v[110:113], v[114:117], v[0:3], v[110:113]
	v_mfma_f32_16x16x32_bf16 v[92:95], v[106:109], v[12:15], v[92:95]
	v_mfma_f32_16x16x32_bf16 v[92:95], v[114:117], v[4:7], v[92:95]
	s_nop 5
	v_mul_f32_e64 v108, v110, s0
	v_mul_f32_e64 v109, v111, s0
	s_waitcnt vmcnt(7)
	v_lshlrev_b32_e32 v110, 16, v84
	v_and_b32_e32 v111, 0xffff0000, v84
	v_pk_mul_f32 v[102:103], v[102:103], v[110:111]
	v_pk_mul_f32 v[106:107], v[112:113], s[0:1] op_sel_hi:[1,0]
	v_cvt_pk_bf16_f32 v84, v102, v103
	v_lshlrev_b32_e32 v102, 16, v85
	v_and_b32_e32 v103, 0xffff0000, v85
	v_pk_mul_f32 v[102:103], v[104:105], v[102:103]
	s_nop 0
	v_cvt_pk_bf16_f32 v85, v102, v103
	v_lshlrev_b32_e32 v102, 16, v86
	v_and_b32_e32 v103, 0xffff0000, v86
	v_pk_mul_f32 v[102:103], v[108:109], v[102:103]
	s_nop 0
	v_cvt_pk_bf16_f32 v86, v102, v103
	v_lshlrev_b32_e32 v102, 16, v87
	v_and_b32_e32 v103, 0xffff0000, v87
	v_pk_mul_f32 v[102:103], v[106:107], v[102:103]
	s_nop 0
	v_cvt_pk_bf16_f32 v87, v102, v103
	global_store_dwordx4 v[98:99], v[84:87], off offset:64
	s_nop 1
	v_pk_mul_f32 v[84:85], v[90:91], s[0:1] op_sel_hi:[1,0]
	v_pk_mul_f32 v[86:87], v[88:89], s[0:1] op_sel_hi:[1,0]
	v_pk_mul_f32 v[90:91], v[92:93], s[0:1] op_sel_hi:[1,0]
	s_waitcnt vmcnt(7)
	v_lshlrev_b32_e32 v92, 16, v80
	v_and_b32_e32 v93, 0xffff0000, v80
	v_pk_mul_f32 v[86:87], v[86:87], v[92:93]
	v_pk_mul_f32 v[88:89], v[94:95], s[0:1] op_sel_hi:[1,0]
	v_cvt_pk_bf16_f32 v80, v86, v87
	v_lshlrev_b32_e32 v86, 16, v81
	v_and_b32_e32 v87, 0xffff0000, v81
	v_pk_mul_f32 v[84:85], v[84:85], v[86:87]
	s_nop 0
	v_cvt_pk_bf16_f32 v81, v84, v85
	v_lshlrev_b32_e32 v84, 16, v82
	v_and_b32_e32 v85, 0xffff0000, v82
	v_pk_mul_f32 v[84:85], v[90:91], v[84:85]
	s_nop 0
	v_cvt_pk_bf16_f32 v82, v84, v85
	v_lshlrev_b32_e32 v84, 16, v83
	v_and_b32_e32 v85, 0xffff0000, v83
	v_pk_mul_f32 v[84:85], v[88:89], v[84:85]
	s_nop 0
	v_cvt_pk_bf16_f32 v83, v84, v85
	global_store_dwordx4 v[96:97], v[80:83], off offset:64
	ds_read_b128 v[80:83], v100 offset:32768
	ds_read_b128 v[84:87], v100 offset:33792
	s_waitcnt lgkmcnt(1)
; #define LAS __attribute__((address_space(3)))
; #define GAS __attribute__((address_space(1)))
; __device__ __forceinline__ unsigned cvtpk(float lo, float hi) { f32x2 v = {lo, hi}; bf16x2_t b = __builtin_convertvector(v, bf16x2_t); return __builtin_bit_cast(unsigned, b); }
; __device__ __forceinline__ float bflo(unsigned w) { return __uint_as_float(w << 16); }
; __device__ __forceinline__ float bfhi(unsigned w) { return __uint_as_float(w & 0xffff0000u); }
; __device__ __forceinline__ void b_unit(Frame& F, int u, bool dry) {
;     ...
;     for (int p = 0; p < 4; ++p) {
;         f32x4 o3[2][2];
; #pragma unroll
;         for (int h = 0; h < 2; ++h) { const int lb = 2 * p + h;
;             o3[h][0] = (f32x4){0.f, 0.f, 0.f, 0.f}; o3[h][1] = (f32x4){0.f, 0.f, 0.f, 0.f};
; #pragma unroll
;             for (int t = 0; t < 4; ++t) {
;                 const bf16x8 xc = *(const LAS bf16x8*)(XF + (size_t)((lb * 4 + t) * 2 + 0) * 1024), xs = *(const LAS bf16x8*)(XF + (size_t)((lb * 4 + t) * 2 + 1) * 1024);
; #pragma unroll
;                 for (int mb = 0; mb < 2; ++mb) { o3[h][mb] = __builtin_amdgcn_mfma_f32_16x16x32_bf16(xc, yr[mb][t], o3[h][mb], 0, 0, 0); o3[h][mb] = __builtin_amdgcn_mfma_f32_16x16x32_bf16(xs, yi[mb][t], o3[h][mb], 0, 0, 0); }
;             }
;         }
; #pragma unroll
;         for (int mb = 0; mb < 2; ++mb) { const int k1 = 2 * w + mb + 16 * fr; const size_t tok = (size_t)b * SEQ + 8 * k1 + k2; const u32x4 sb = sbq[p][mb]; const f32x4 a0 = o3[0][mb] * 0.001953125f, a1 = o3[1][mb] * 0.001953125f;
;             u32x4 o; o.x = cvtpk(bflo(sb.x) * a0[0], bfhi(sb.x) * a0[1]); o.y = cvtpk(bflo(sb.y) * a0[2], bfhi(sb.y) * a0[3]); o.z = cvtpk(bflo(sb.z) * a1[0], bfhi(sb.z) * a1[1]); o.w = cvtpk(bflo(sb.w) * a1[2], bfhi(sb.w) * a1[3]);
;             if (!dry) *(GAS u32x4*)(SBG + tok * 512 + g * 128 + 32 * p + 8 * fq) = o; }
;     }
	v_mfma_f32_16x16x32_bf16 v[88:91], v[80:83], v[52:55], 0
	v_mfma_f32_16x16x32_bf16 v[80:83], v[80:83], v[56:59], 0
	s_waitcnt lgkmcnt(0)
	v_mfma_f32_16x16x32_bf16 v[88:91], v[84:87], v[48:51], v[88:91]
	v_mfma_f32_16x16x32_bf16 v[80:83], v[84:87], v[60:63], v[80:83]
	ds_read_b128 v[84:87], v100 offset:34816
	ds_read_b128 v[92:95], v100 offset:35840
	s_waitcnt lgkmcnt(1)
	v_mfma_f32_16x16x32_bf16 v[88:91], v[84:87], v[36:39], v[88:91]
	v_mfma_f32_16x16x32_bf16 v[80:83], v[84:87], v[40:43], v[80:83]
	s_waitcnt lgkmcnt(0)
	v_mfma_f32_16x16x32_bf16 v[88:91], v[92:95], v[32:35], v[88:91]
	v_mfma_f32_16x16x32_bf16 v[80:83], v[92:95], v[44:47], v[80:83]
	ds_read_b128 v[84:87], v100 offset:36864
	ds_read_b128 v[92:95], v100 offset:37888
	s_waitcnt lgkmcnt(1)
	v_mfma_f32_16x16x32_bf16 v[88:91], v[84:87], v[20:23], v[88:91]
	v_mfma_f32_16x16x32_bf16 v[80:83], v[84:87], v[24:27], v[80:83]
	s_waitcnt lgkmcnt(0)
	v_mfma_f32_16x16x32_bf16 v[88:91], v[92:95], v[16:19], v[88:91]
	v_mfma_f32_16x16x32_bf16 v[80:83], v[92:95], v[28:31], v[80:83]
	ds_read_b128 v[92:95], v100 offset:38912
	ds_read_b128 v[102:105], v100 offset:39936
	s_waitcnt lgkmcnt(1)
	v_mfma_f32_16x16x32_bf16 v[84:87], v[92:95], v[8:11], v[88:91]
	v_mfma_f32_16x16x32_bf16 v[80:83], v[92:95], v[12:15], v[80:83]
	s_nop 1
	ds_read_b128 v[88:91], v100 offset:40960
	ds_read_b128 v[92:95], v100 offset:41984
	s_waitcnt lgkmcnt(2)
	v_mfma_f32_16x16x32_bf16 v[84:87], v[102:105], v[0:3], v[84:87]
	v_mfma_f32_16x16x32_bf16 v[80:83], v[102:105], v[4:7], v[80:83]
	s_waitcnt lgkmcnt(1)
	v_mfma_f32_16x16x32_bf16 v[102:105], v[88:91], v[52:55], 0
	s_nop 4
	v_mul_f32_e64 v84, v84, s0
	v_mul_f32_e64 v85, v85, s0
	v_pk_mul_f32 v[86:87], v[86:87], s[0:1] op_sel_hi:[1,0]
	v_mfma_f32_16x16x32_bf16 v[88:91], v[88:91], v[56:59], 0
	s_waitcnt lgkmcnt(0)
	v_mfma_f32_16x16x32_bf16 v[102:105], v[92:95], v[48:51], v[102:105]
	v_mfma_f32_16x16x32_bf16 v[88:91], v[92:95], v[60:63], v[88:91]
	ds_read_b128 v[92:95], v100 offset:43008
	ds_read_b128 v[106:109], v100 offset:44032
	s_waitcnt lgkmcnt(1)
	v_mfma_f32_16x16x32_bf16 v[102:105], v[92:95], v[36:39], v[102:105]
	v_mfma_f32_16x16x32_bf16 v[88:91], v[92:95], v[40:43], v[88:91]
	s_waitcnt lgkmcnt(0)
	v_mfma_f32_16x16x32_bf16 v[102:105], v[106:109], v[32:35], v[102:105]
	v_mfma_f32_16x16x32_bf16 v[88:91], v[106:109], v[44:47], v[88:91]
	ds_read_b128 v[92:95], v100 offset:45056
	ds_read_b128 v[106:109], v100 offset:46080
	s_waitcnt lgkmcnt(1)
	v_mfma_f32_16x16x32_bf16 v[102:105], v[92:95], v[20:23], v[102:105]
	v_mfma_f32_16x16x32_bf16 v[88:91], v[92:95], v[24:27], v[88:91]
	s_waitcnt lgkmcnt(0)
	v_mfma_f32_16x16x32_bf16 v[102:105], v[106:109], v[16:19], v[102:105]
	v_mfma_f32_16x16x32_bf16 v[88:91], v[106:109], v[28:31], v[88:91]
	ds_read_b128 v[92:95], v100 offset:47104
	ds_read_b128 v[106:109], v100 offset:48128
	s_waitcnt lgkmcnt(1)
	v_mfma_f32_16x16x32_bf16 v[102:105], v[92:95], v[8:11], v[102:105]
	s_waitcnt lgkmcnt(0)
	v_mfma_f32_16x16x32_bf16 v[102:105], v[106:109], v[0:3], v[102:105]
	v_mfma_f32_16x16x32_bf16 v[88:91], v[92:95], v[12:15], v[88:91]
	v_mfma_f32_16x16x32_bf16 v[88:91], v[106:109], v[4:7], v[88:91]
	s_nop 5
	v_mul_f32_e64 v94, v102, s0
	v_mul_f32_e64 v95, v103, s0
	s_waitcnt vmcnt(7)
	v_lshlrev_b32_e32 v102, 16, v76
	v_and_b32_e32 v103, 0xffff0000, v76
	v_pk_mul_f32 v[84:85], v[84:85], v[102:103]
	v_pk_mul_f32 v[92:93], v[104:105], s[0:1] op_sel_hi:[1,0]
	v_cvt_pk_bf16_f32 v76, v84, v85
	v_lshlrev_b32_e32 v84, 16, v77
	v_and_b32_e32 v85, 0xffff0000, v77
	v_pk_mul_f32 v[84:85], v[86:87], v[84:85]
	s_nop 0
	v_cvt_pk_bf16_f32 v77, v84, v85
	v_lshlrev_b32_e32 v84, 16, v78
	v_and_b32_e32 v85, 0xffff0000, v78
	v_pk_mul_f32 v[84:85], v[94:95], v[84:85]
	s_nop 0
	v_cvt_pk_bf16_f32 v78, v84, v85
	v_lshlrev_b32_e32 v84, 16, v79
	v_and_b32_e32 v85, 0xffff0000, v79
	v_pk_mul_f32 v[84:85], v[92:93], v[84:85]
	s_nop 0
	v_cvt_pk_bf16_f32 v79, v84, v85
	global_store_dwordx4 v[98:99], v[76:79], off offset:128
	s_waitcnt vmcnt(7)
	v_lshlrev_b32_e32 v84, 16, v72
	v_and_b32_e32 v85, 0xffff0000, v72
	v_pk_mul_f32 v[78:79], v[80:81], s[0:1] op_sel_hi:[1,0]
	v_pk_mul_f32 v[76:77], v[82:83], s[0:1] op_sel_hi:[1,0]
	v_pk_mul_f32 v[78:79], v[78:79], v[84:85]
	v_pk_mul_f32 v[82:83], v[88:89], s[0:1] op_sel_hi:[1,0]
	v_cvt_pk_bf16_f32 v72, v78, v79
	v_lshlrev_b32_e32 v78, 16, v73
	v_and_b32_e32 v79, 0xffff0000, v73
	v_pk_mul_f32 v[76:77], v[76:77], v[78:79]
	v_pk_mul_f32 v[80:81], v[90:91], s[0:1] op_sel_hi:[1,0]
	v_cvt_pk_bf16_f32 v73, v76, v77
	v_lshlrev_b32_e32 v76, 16, v74
	v_and_b32_e32 v77, 0xffff0000, v74
	v_pk_mul_f32 v[76:77], v[82:83], v[76:77]
	s_nop 0
	v_cvt_pk_bf16_f32 v74, v76, v77
	v_lshlrev_b32_e32 v76, 16, v75
	v_and_b32_e32 v77, 0xffff0000, v75
	v_pk_mul_f32 v[76:77], v[80:81], v[76:77]
	s_nop 0
	v_cvt_pk_bf16_f32 v75, v76, v77
	global_store_dwordx4 v[96:97], v[72:75], off offset:128
	ds_read_b128 v[72:75], v100 offset:49152
	ds_read_b128 v[76:79], v100 offset:50176
	s_waitcnt lgkmcnt(1)
	v_mfma_f32_16x16x32_bf16 v[80:83], v[72:75], v[52:55], 0
	v_mfma_f32_16x16x32_bf16 v[72:75], v[72:75], v[56:59], 0
	s_waitcnt lgkmcnt(0)
	v_mfma_f32_16x16x32_bf16 v[80:83], v[76:79], v[48:51], v[80:83]
	v_mfma_f32_16x16x32_bf16 v[72:75], v[76:79], v[60:63], v[72:75]
	ds_read_b128 v[76:79], v100 offset:51200
	ds_read_b128 v[84:87], v100 offset:52224
	s_waitcnt lgkmcnt(1)
	v_mfma_f32_16x16x32_bf16 v[80:83], v[76:79], v[36:39], v[80:83]
	v_mfma_f32_16x16x32_bf16 v[72:75], v[76:79], v[40:43], v[72:75]
	s_waitcnt lgkmcnt(0)
	v_mfma_f32_16x16x32_bf16 v[80:83], v[84:87], v[32:35], v[80:83]
	v_mfma_f32_16x16x32_bf16 v[72:75], v[84:87], v[44:47], v[72:75]
	ds_read_b128 v[76:79], v100 offset:53248
	ds_read_b128 v[84:87], v100 offset:54272
	s_waitcnt lgkmcnt(1)
; #define LAS __attribute__((address_space(3)))
; #define GAS __attribute__((address_space(1)))
; __device__ __forceinline__ unsigned cvtpk(float lo, float hi) { f32x2 v = {lo, hi}; bf16x2_t b = __builtin_convertvector(v, bf16x2_t); return __builtin_bit_cast(unsigned, b); }
; __device__ __forceinline__ float bflo(unsigned w) { return __uint_as_float(w << 16); }
; __device__ __forceinline__ float bfhi(unsigned w) { return __uint_as_float(w & 0xffff0000u); }
; __device__ __forceinline__ unsigned xb_ld(unsigned* p)              { return __hip_atomic_load(p, __ATOMIC_RELAXED, __HIP_MEMORY_SCOPE_AGENT); }
; __device__ __forceinline__ void xcdl_wait_t0(const XcdBarrier& b) {
;     if (is_t0(b.wave)) {
;         unsigned* bar = b.bar; asm volatile("" : "+s"(bar));
;         const unsigned gen = b.st[5];
;         XB_SPIN(xb_ld(&bar[XB_LGEN(b.x)]) == gen, bar);
;         __builtin_amdgcn_fence(__ATOMIC_ACQUIRE, "agent");
;         asm volatile("s_waitcnt vmcnt(0)" ::: "memory");
;     }
; }
; __device__ __forceinline__ void b_unit(Frame& F, int u, bool dry) {
;     ...
;     for (int p = 0; p < 4; ++p) {
;         f32x4 o3[2][2];
; #pragma unroll
;         for (int h = 0; h < 2; ++h) { const int lb = 2 * p + h;
;             o3[h][0] = (f32x4){0.f, 0.f, 0.f, 0.f}; o3[h][1] = (f32x4){0.f, 0.f, 0.f, 0.f};
; #pragma unroll
;             for (int t = 0; t < 4; ++t) {
;                 const bf16x8 xc = *(const LAS bf16x8*)(XF + (size_t)((lb * 4 + t) * 2 + 0) * 1024), xs = *(const LAS bf16x8*)(XF + (size_t)((lb * 4 + t) * 2 + 1) * 1024);
; #pragma unroll
;                 for (int mb = 0; mb < 2; ++mb) { o3[h][mb] = __builtin_amdgcn_mfma_f32_16x16x32_bf16(xc, yr[mb][t], o3[h][mb], 0, 0, 0); o3[h][mb] = __builtin_amdgcn_mfma_f32_16x16x32_bf16(xs, yi[mb][t], o3[h][mb], 0, 0, 0); }
;             }
;         }
; #pragma unroll
;         for (int mb = 0; mb < 2; ++mb) { const int k1 = 2 * w + mb + 16 * fr; const size_t tok = (size_t)b * SEQ + 8 * k1 + k2; const u32x4 sb = sbq[p][mb]; const f32x4 a0 = o3[0][mb] * 0.001953125f, a1 = o3[1][mb] * 0.001953125f;
;             u32x4 o; o.x = cvtpk(bflo(sb.x) * a0[0], bfhi(sb.x) * a0[1]); o.y = cvtpk(bflo(sb.y) * a0[2], bfhi(sb.y) * a0[3]); o.z = cvtpk(bflo(sb.z) * a1[0], bfhi(sb.z) * a1[1]); o.w = cvtpk(bflo(sb.w) * a1[2], bfhi(sb.w) * a1[3]);
;             if (!dry) *(GAS u32x4*)(SBG + tok * 512 + g * 128 + 32 * p + 8 * fq) = o; }
;     }
	v_mfma_f32_16x16x32_bf16 v[80:83], v[76:79], v[20:23], v[80:83]
	v_mfma_f32_16x16x32_bf16 v[72:75], v[76:79], v[24:27], v[72:75]
	s_waitcnt lgkmcnt(0)
	v_mfma_f32_16x16x32_bf16 v[80:83], v[84:87], v[16:19], v[80:83]
	v_mfma_f32_16x16x32_bf16 v[72:75], v[84:87], v[28:31], v[72:75]
	ds_read_b128 v[84:87], v100 offset:55296
	ds_read_b128 v[88:91], v100 offset:56320
	s_waitcnt lgkmcnt(1)
	v_mfma_f32_16x16x32_bf16 v[76:79], v[84:87], v[8:11], v[80:83]
	v_mfma_f32_16x16x32_bf16 v[72:75], v[84:87], v[12:15], v[72:75]
	s_nop 1
	ds_read_b128 v[80:83], v100 offset:57344
	ds_read_b128 v[84:87], v100 offset:58368
	s_waitcnt lgkmcnt(1)
	v_mfma_f32_16x16x32_bf16 v[52:55], v[80:83], v[52:55], 0
	s_waitcnt lgkmcnt(0)
	v_mfma_f32_16x16x32_bf16 v[48:51], v[84:87], v[48:51], v[52:55]
	v_mfma_f32_16x16x32_bf16 v[52:55], v[80:83], v[56:59], 0
	v_mfma_f32_16x16x32_bf16 v[52:55], v[84:87], v[60:63], v[52:55]
	ds_read_b128 v[56:59], v100 offset:59392
	ds_read_b128 v[60:63], v100 offset:60416
	s_waitcnt lgkmcnt(1)
	v_mfma_f32_16x16x32_bf16 v[36:39], v[56:59], v[36:39], v[48:51]
	s_waitcnt lgkmcnt(0)
	v_mfma_f32_16x16x32_bf16 v[32:35], v[60:63], v[32:35], v[36:39]
	v_mfma_f32_16x16x32_bf16 v[36:39], v[56:59], v[40:43], v[52:55]
	v_mfma_f32_16x16x32_bf16 v[36:39], v[60:63], v[44:47], v[36:39]
	ds_read_b128 v[40:43], v100 offset:61440
	ds_read_b128 v[44:47], v100 offset:62464
	v_mov_b32_e32 v53, v193
	s_waitcnt lgkmcnt(1)
	v_mfma_f32_16x16x32_bf16 v[20:23], v[40:43], v[20:23], v[32:35]
	s_waitcnt lgkmcnt(0)
	v_mfma_f32_16x16x32_bf16 v[16:19], v[44:47], v[16:19], v[20:23]
	v_mfma_f32_16x16x32_bf16 v[20:23], v[40:43], v[24:27], v[36:39]
	v_mfma_f32_16x16x32_bf16 v[20:23], v[44:47], v[28:31], v[20:23]
	ds_read_b128 v[24:27], v100 offset:63488
	ds_read_b128 v[28:31], v100 offset:64512
	s_waitcnt lgkmcnt(1)
	v_mfma_f32_16x16x32_bf16 v[8:11], v[24:27], v[8:11], v[16:19]
	v_mfma_f32_16x16x32_bf16 v[76:79], v[88:91], v[0:3], v[76:79]
	s_waitcnt lgkmcnt(0)
	v_mfma_f32_16x16x32_bf16 v[0:3], v[28:31], v[0:3], v[8:11]
	v_mfma_f32_16x16x32_bf16 v[8:11], v[24:27], v[12:15], v[20:23]
	v_mfma_f32_16x16x32_bf16 v[72:75], v[88:91], v[4:7], v[72:75]
	s_nop 5
	v_mul_f32_e64 v12, v2, s0
	v_mul_f32_e64 v13, v3, s0
	v_pk_mul_f32 v[2:3], v[0:1], s[0:1] op_sel_hi:[1,0]
	s_waitcnt vmcnt(7)
	v_lshlrev_b32_e32 v0, 16, v68
	v_mfma_f32_16x16x32_bf16 v[4:7], v[28:31], v[4:7], v[8:11]
	v_and_b32_e32 v1, 0xffff0000, v68
	s_nop 1
	v_pk_mul_f32 v[10:11], v[76:77], s[0:1] op_sel_hi:[1,0]
	v_pk_mul_f32 v[8:9], v[78:79], s[0:1] op_sel_hi:[1,0]
	v_pk_mul_f32 v[0:1], v[10:11], v[0:1]
	v_lshlrev_b32_e32 v10, 16, v69
	v_and_b32_e32 v11, 0xffff0000, v69
	v_pk_mul_f32 v[8:9], v[8:9], v[10:11]
	v_cvt_pk_bf16_f32 v0, v0, v1
	v_cvt_pk_bf16_f32 v1, v8, v9
	v_lshlrev_b32_e32 v8, 16, v70
	v_and_b32_e32 v9, 0xffff0000, v70
	v_pk_mul_f32 v[2:3], v[2:3], v[8:9]
	v_lshlrev_b32_e32 v8, 16, v71
	v_and_b32_e32 v9, 0xffff0000, v71
	v_pk_mul_f32 v[8:9], v[12:13], v[8:9]
	v_cvt_pk_bf16_f32 v2, v2, v3
	v_cvt_pk_bf16_f32 v3, v8, v9
	global_store_dwordx4 v[98:99], v[0:3], off offset:192
	s_waitcnt vmcnt(7)
	v_lshlrev_b32_e32 v8, 16, v64
	v_and_b32_e32 v9, 0xffff0000, v64
	v_pk_mul_f32 v[0:1], v[72:73], s[0:1] op_sel_hi:[1,0]
	v_pk_mul_f32 v[2:3], v[74:75], s[0:1] op_sel_hi:[1,0]
	v_pk_mul_f32 v[0:1], v[0:1], v[8:9]
	v_lshlrev_b32_e32 v8, 16, v65
	v_and_b32_e32 v9, 0xffff0000, v65
	v_pk_mul_f32 v[2:3], v[2:3], v[8:9]
	v_pk_mul_f32 v[4:5], v[4:5], s[0:1] op_sel_hi:[1,0]
	v_cvt_pk_bf16_f32 v0, v0, v1
	v_cvt_pk_bf16_f32 v1, v2, v3
	v_lshlrev_b32_e32 v2, 16, v66
	v_and_b32_e32 v3, 0xffff0000, v66
	v_pk_mul_f32 v[6:7], v[6:7], s[0:1] op_sel_hi:[1,0]
	v_pk_mul_f32 v[2:3], v[4:5], v[2:3]
	v_lshlrev_b32_e32 v4, 16, v67
	v_and_b32_e32 v5, 0xffff0000, v67
	v_pk_mul_f32 v[4:5], v[6:7], v[4:5]
	v_cvt_pk_bf16_f32 v2, v2, v3
	v_cvt_pk_bf16_f32 v3, v4, v5
	v_readlane_b32 s0, v253, 55
	global_store_dwordx4 v[96:97], v[0:3], off offset:192
	s_nop 0
	s_nop 0
	s_nop 0
	s_and_b64 vcc, exec, s[46:47]
	s_cbranch_vccnz .Lsd_w_done
	v_readlane_b32 s2, v253, 3
	v_readlane_b32 s3, v253, 4
	s_cmp_lg_u64 s[2:3], 0
	s_cbranch_scc1 .Lsd_w_done
	s_mov_b64 s[16:17], exec
	s_lshl_b32 s2, s23, 1
	s_add_u32 s6, s26, 0x6000
	s_addc_u32 s7, s27, 0
	s_add_u32 s6, s6, s2
	s_addc_u32 s7, s7, 0
	s_add_i32 s2, s34, 1
	s_mov_b32 exec_lo, -1
	s_mov_b32 exec_hi, 0
	v_mbcnt_lo_u32_b32 v8, -1, 0
	v_lshlrev_b32_e32 v8, 2, v8
	v_mov_b32_e32 v9, s2
	s_mov_b32 s3, 0
.Lsd_w_poll:
	global_load_dword v10, v8, s[6:7] sc1
	s_waitcnt vmcnt(0)
	v_cmp_lt_u32_e32 vcc, v10, v9
	s_nop 1
	s_cmp_eq_u64 vcc, 0
	s_cbranch_scc1 .Lsd_w_ok
	s_sleep 1
	s_add_u32 s3, s3, 1
	s_cmp_lt_u32 s3, 0x4000
	s_cbranch_scc1 .Lsd_w_poll
	v_mov_b32_e32 v10, 1
	v_mov_b32_e32 v8, 0x200
	global_store_dword v8, v10, s[26:27] sc1
.Lsd_w_ok:
	s_waitcnt vmcnt(0)
	s_mov_b64 exec, s[16:17]
; #define LAS __attribute__((address_space(3)))
; #define GAS __attribute__((address_space(1)))
; __device__ __forceinline__ int otid(int wave) { return wave * 64 + olane(); }
; __device__ __forceinline__ float bflo(unsigned w) { return __uint_as_float(w << 16); }
; __device__ __forceinline__ float bfhi(unsigned w) { return __uint_as_float(w & 0xffff0000u); }
; __device__ __forceinline__ void a_unit(Frame& F, int L, int u, bool dry) {
;     ...
;     const int w = F.wave, lane = otid(F.wave) & 63, tg = lane & 15, cr = lane >> 4, fr = lane & 15, fq = lane >> 4;
;     const bf16_t* gvt = (const bf16_t*)(ws_ + WS_GVT) + (size_t)((b * 16 + chunk) * 512) * 128;
;     LAS unsigned char* VT = F.lds + w * 17408;
;     LAS float* part = (LAS float*)(F.lds + 139264);
;     const bf16_t* Wh = (const bf16_t*)(ws_ + WS_AWS) + (size_t)((L * 8 + w) * 2 + qh) * 8192 + (size_t)lane * 8;
;     float s[8], q[8];
; #pragma unroll
;     for (int j = 0; j < 8; ++j) { s[j] = 0.f; q[j] = 0.f; }
;     u32x4 raw[16];
;     {
; #pragma unroll
;         for (int i = 0; i < 16; ++i) raw[i] = *(const GAS u32x4*)(gvt + (size_t)(64 * w + 4 * i + cr) * 128 + 8 * tg);
; #pragma unroll
;         for (int i = 0; i < 16; ++i)
; #pragma unroll
;             for (int jj = 0; jj < 4; ++jj) { const float lo = bflo(raw[i][jj]), hi = bfhi(raw[i][jj]); s[2 * jj] += lo; q[2 * jj] = fmaf(lo, lo, q[2 * jj]); s[2 * jj + 1] += hi; q[2 * jj + 1] = fmaf(hi, hi, q[2 * jj + 1]); }
.Lsd_w_done:
	s_barrier
	v_mbcnt_lo_u32_b32 v176, -1, 0
	v_mbcnt_hi_u32_b32 v176, -1, v176
	v_readlane_b32 s1, v253, 56
	v_bfe_u32 v173, v176, 4, 2
	v_and_b32_e32 v190, 15, v176
	s_add_u32 s0, s28, s0
	s_addc_u32 s1, s29, s1
	v_or_b32_e32 v0, s70, v173
	v_lshlrev_b32_e32 v52, 4, v190
	v_lshl_add_u64 v[2:3], s[0:1], 0, v[52:53]
	s_mov_b64 s[0:1], 0x6000000
	v_ashrrev_i32_e32 v1, 31, v0
	v_lshl_add_u64 v[2:3], v[2:3], 0, s[0:1]
	v_lshlrev_b64 v[4:5], 8, v[0:1]
	v_lshl_add_u64 v[4:5], v[2:3], 0, v[4:5]
	global_load_dwordx4 v[56:59], v[4:5], off sc1
	v_or_b32_e32 v4, 4, v0
	v_ashrrev_i32_e32 v5, 31, v4
	v_lshlrev_b64 v[4:5], 8, v[4:5]
	v_lshl_add_u64 v[4:5], v[2:3], 0, v[4:5]
	global_load_dwordx4 v[60:63], v[4:5], off sc1
	v_or_b32_e32 v4, 8, v0
	v_ashrrev_i32_e32 v5, 31, v4
	v_lshlrev_b64 v[4:5], 8, v[4:5]
	v_lshl_add_u64 v[4:5], v[2:3], 0, v[4:5]
	global_load_dwordx4 v[70:73], v[4:5], off sc1
	v_or_b32_e32 v4, 12, v0
	v_ashrrev_i32_e32 v5, 31, v4
	v_lshlrev_b64 v[4:5], 8, v[4:5]
	v_lshl_add_u64 v[4:5], v[2:3], 0, v[4:5]
	global_load_dwordx4 v[48:51], v[4:5], off sc1
	v_or_b32_e32 v4, 16, v0
	v_ashrrev_i32_e32 v5, 31, v4
	v_lshlrev_b64 v[4:5], 8, v[4:5]
	v_lshl_add_u64 v[4:5], v[2:3], 0, v[4:5]
	global_load_dwordx4 v[44:47], v[4:5], off sc1
	v_or_b32_e32 v4, 20, v0
	v_ashrrev_i32_e32 v5, 31, v4
	v_lshlrev_b64 v[4:5], 8, v[4:5]
	v_lshl_add_u64 v[4:5], v[2:3], 0, v[4:5]
	global_load_dwordx4 v[40:43], v[4:5], off sc1
	v_or_b32_e32 v4, 24, v0
	v_ashrrev_i32_e32 v5, 31, v4
	v_lshlrev_b64 v[4:5], 8, v[4:5]
	v_lshl_add_u64 v[4:5], v[2:3], 0, v[4:5]
	global_load_dwordx4 v[36:39], v[4:5], off sc1
	v_or_b32_e32 v4, 28, v0
	v_ashrrev_i32_e32 v5, 31, v4
	v_lshlrev_b64 v[4:5], 8, v[4:5]
	v_lshl_add_u64 v[4:5], v[2:3], 0, v[4:5]
	global_load_dwordx4 v[32:35], v[4:5], off sc1
	v_or_b32_e32 v4, 32, v0
	v_ashrrev_i32_e32 v5, 31, v4
	v_lshlrev_b64 v[4:5], 8, v[4:5]
	v_lshl_add_u64 v[4:5], v[2:3], 0, v[4:5]
	global_load_dwordx4 v[28:31], v[4:5], off sc1
	v_or_b32_e32 v4, 36, v0
	v_ashrrev_i32_e32 v5, 31, v4
	v_lshlrev_b64 v[4:5], 8, v[4:5]
	v_lshl_add_u64 v[4:5], v[2:3], 0, v[4:5]
	global_load_dwordx4 v[24:27], v[4:5], off sc1
	v_or_b32_e32 v4, 40, v0
	v_ashrrev_i32_e32 v5, 31, v4
	v_lshlrev_b64 v[4:5], 8, v[4:5]
	v_lshl_add_u64 v[4:5], v[2:3], 0, v[4:5]
	global_load_dwordx4 v[20:23], v[4:5], off sc1
	v_or_b32_e32 v4, 44, v0
	v_ashrrev_i32_e32 v5, 31, v4
	v_lshlrev_b64 v[4:5], 8, v[4:5]
	v_lshl_add_u64 v[4:5], v[2:3], 0, v[4:5]
	global_load_dwordx4 v[16:19], v[4:5], off sc1
	v_or_b32_e32 v4, 48, v0
	v_ashrrev_i32_e32 v5, 31, v4
	v_lshlrev_b64 v[4:5], 8, v[4:5]
	v_lshl_add_u64 v[4:5], v[2:3], 0, v[4:5]
	global_load_dwordx4 v[12:15], v[4:5], off sc1
	v_or_b32_e32 v4, 52, v0
	v_ashrrev_i32_e32 v5, 31, v4
	v_lshlrev_b64 v[4:5], 8, v[4:5]
	v_lshl_add_u64 v[4:5], v[2:3], 0, v[4:5]
	global_load_dwordx4 v[8:11], v[4:5], off sc1
	v_or_b32_e32 v4, 56, v0
	v_ashrrev_i32_e32 v5, 31, v4
	v_or_b32_e32 v0, 60, v0
	v_lshlrev_b64 v[4:5], 8, v[4:5]
	v_ashrrev_i32_e32 v1, 31, v0
	v_lshl_add_u64 v[4:5], v[2:3], 0, v[4:5]
	v_lshlrev_b64 v[0:1], 8, v[0:1]
	global_load_dwordx4 v[4:7], v[4:5], off sc1
	v_lshl_add_u64 v[0:1], v[2:3], 0, v[0:1]
	global_load_dwordx4 v[0:3], v[0:1], off sc1
	v_and_b32_e32 v162, 63, v176
	v_cmp_gt_u32_e32 vcc, 16, v162
	s_waitcnt vmcnt(15)
	v_lshlrev_b32_e32 v64, 16, v57
	v_lshlrev_b32_e32 v156, 16, v56
	v_and_b32_e32 v157, 0xffff0000, v56
	v_and_b32_e32 v65, 0xffff0000, v57
	v_add_f32_e32 v68, 0, v64
	v_lshlrev_b32_e32 v56, 16, v58
	s_waitcnt vmcnt(14)
	v_lshlrev_b32_e32 v54, 16, v60
	v_and_b32_e32 v55, 0xffff0000, v60
	v_lshlrev_b32_e32 v60, 16, v61
	v_add_f32_e32 v66, 0, v156
	v_add_f32_e32 v69, 0, v65
	v_and_b32_e32 v57, 0xffff0000, v58
	v_add_f32_e32 v74, 0, v56
	v_lshlrev_b32_e32 v58, 16, v59
	v_and_b32_e32 v61, 0xffff0000, v61
	v_add_f32_e32 v80, v68, v60
	v_lshlrev_b32_e32 v68, 16, v62
	v_add_f32_e32 v67, 0, v157
	v_add_f32_e32 v75, 0, v57
	v_add_f32_e32 v76, 0, v58
	v_add_f32_e32 v66, v66, v54
	v_add_f32_e32 v81, v69, v61
	v_and_b32_e32 v69, 0xffff0000, v62
	v_add_f32_e32 v62, v74, v68
	v_lshlrev_b32_e32 v74, 16, v63
	s_waitcnt vmcnt(13)
	v_lshlrev_b32_e32 v78, 16, v70
	v_and_b32_e32 v59, 0xffff0000, v59
	v_add_f32_e32 v67, v67, v55
	v_add_f32_e32 v84, v75, v69
	v_and_b32_e32 v75, 0xffff0000, v63
	v_add_f32_e32 v63, v76, v74
	v_and_b32_e32 v79, 0xffff0000, v70
	v_add_f32_e32 v66, v66, v78
	v_lshlrev_b32_e32 v82, 16, v71
	v_lshlrev_b32_e32 v90, 16, v72
	v_lshlrev_b32_e32 v98, 16, v73
	s_waitcnt vmcnt(12)
	v_lshlrev_b32_e32 v100, 16, v48
	v_add_f32_e32 v77, 0, v59
	v_add_f32_e32 v67, v67, v79
	v_and_b32_e32 v83, 0xffff0000, v71
	v_add_f32_e32 v70, v80, v82
	v_add_f32_e32 v62, v62, v90
	v_add_f32_e32 v63, v63, v98
	v_and_b32_e32 v101, 0xffff0000, v48
	v_add_f32_e32 v48, v66, v100
	v_lshlrev_b32_e32 v114, 16, v49
	v_lshlrev_b32_e32 v126, 16, v50
	v_lshlrev_b32_e32 v136, 16, v51
	s_waitcnt vmcnt(11)
	v_lshlrev_b32_e32 v130, 16, v44
	v_add_f32_e32 v76, v77, v75
	v_add_f32_e32 v71, v81, v83
	v_and_b32_e32 v91, 0xffff0000, v72
	v_and_b32_e32 v99, 0xffff0000, v73
	v_add_f32_e32 v66, v67, v101
	v_and_b32_e32 v115, 0xffff0000, v49
	v_add_f32_e32 v49, v70, v114
	v_and_b32_e32 v127, 0xffff0000, v50
	v_add_f32_e32 v50, v62, v126
	v_and_b32_e32 v137, 0xffff0000, v51
	v_add_f32_e32 v51, v63, v136
	v_and_b32_e32 v131, 0xffff0000, v44
	v_add_f32_e32 v44, v48, v130
	v_lshlrev_b32_e32 v138, 16, v45
	v_lshlrev_b32_e32 v144, 16, v46
	v_lshlrev_b32_e32 v118, 16, v47
	s_waitcnt vmcnt(10)
; __device__ __forceinline__ float bflo(unsigned w) { return __uint_as_float(w << 16); }
; __device__ __forceinline__ float bfhi(unsigned w) { return __uint_as_float(w & 0xffff0000u); }
; __device__ __forceinline__ void a_unit(Frame& F, int L, int u, bool dry) {
;     ...
;         for (int i = 0; i < 16; ++i)
; #pragma unroll
;             for (int jj = 0; jj < 4; ++jj) { const float lo = bflo(raw[i][jj]), hi = bfhi(raw[i][jj]); s[2 * jj] += lo; q[2 * jj] = fmaf(lo, lo, q[2 * jj]); s[2 * jj + 1] += hi; q[2 * jj + 1] = fmaf(hi, hi, q[2 * jj + 1]); }
	v_lshlrev_b32_e32 v120, 16, v40
	v_fma_f32 v158, v58, v58, 0
	v_add_f32_e32 v72, v84, v91
	v_add_f32_e32 v73, v76, v99
	v_add_f32_e32 v67, v71, v115
	v_add_f32_e32 v48, v66, v131
	v_and_b32_e32 v139, 0xffff0000, v45
	v_add_f32_e32 v45, v49, v138
	v_and_b32_e32 v145, 0xffff0000, v46
	v_add_f32_e32 v46, v50, v144
	v_and_b32_e32 v119, 0xffff0000, v47
	v_add_f32_e32 v47, v51, v118
	v_and_b32_e32 v121, 0xffff0000, v40
	v_add_f32_e32 v40, v44, v120
	v_lshlrev_b32_e32 v132, 16, v41
	v_lshlrev_b32_e32 v140, 16, v42
	v_lshlrev_b32_e32 v112, 16, v43
	s_waitcnt vmcnt(9)
	v_lshlrev_b32_e32 v116, 16, v36
	v_fma_f32 v165, v156, v156, 0
	v_fma_f32 v164, v157, v157, 0
	v_fma_f32 v163, v64, v64, 0
	v_fma_f32 v161, v65, v65, 0
	v_fma_f32 v160, v56, v56, 0
	v_fma_f32 v159, v57, v57, 0
	v_fmac_f32_e32 v158, v74, v74
	v_add_f32_e32 v62, v72, v127
	v_add_f32_e32 v63, v73, v137
	v_add_f32_e32 v49, v67, v139
	v_add_f32_e32 v44, v48, v121
	v_and_b32_e32 v133, 0xffff0000, v41
	v_add_f32_e32 v41, v45, v132
	v_and_b32_e32 v141, 0xffff0000, v42
	v_add_f32_e32 v42, v46, v140
	v_and_b32_e32 v113, 0xffff0000, v43
	v_add_f32_e32 v43, v47, v112
	v_and_b32_e32 v117, 0xffff0000, v36
	v_add_f32_e32 v36, v40, v116
	v_lshlrev_b32_e32 v128, 16, v37
	v_lshlrev_b32_e32 v96, 16, v38
	v_lshlrev_b32_e32 v108, 16, v39
	s_waitcnt vmcnt(8)
	v_lshlrev_b32_e32 v110, 16, v32
	v_fma_f32 v53, v59, v59, 0
	v_fmac_f32_e32 v165, v54, v54
	v_fmac_f32_e32 v164, v55, v55
	v_fmac_f32_e32 v163, v60, v60
	v_fmac_f32_e32 v161, v61, v61
	v_fmac_f32_e32 v160, v68, v68
	v_fmac_f32_e32 v159, v69, v69
	v_fmac_f32_e32 v158, v98, v98
	v_add_f32_e32 v50, v62, v145
	v_add_f32_e32 v51, v63, v119
	v_add_f32_e32 v45, v49, v133
	v_add_f32_e32 v40, v44, v117
	v_and_b32_e32 v129, 0xffff0000, v37
	v_add_f32_e32 v37, v41, v128
	v_and_b32_e32 v97, 0xffff0000, v38
	v_add_f32_e32 v38, v42, v96
	v_and_b32_e32 v109, 0xffff0000, v39
	v_add_f32_e32 v39, v43, v108
	v_and_b32_e32 v111, 0xffff0000, v32
	v_add_f32_e32 v32, v36, v110
	v_lshlrev_b32_e32 v86, 16, v33
	v_lshlrev_b32_e32 v92, 16, v34
	v_lshlrev_b32_e32 v104, 16, v35
	s_waitcnt vmcnt(7)
	v_lshlrev_b32_e32 v102, 16, v28
	v_fmac_f32_e32 v53, v75, v75
	v_fmac_f32_e32 v165, v78, v78
	v_fmac_f32_e32 v164, v79, v79
	v_fmac_f32_e32 v163, v82, v82
	v_fmac_f32_e32 v161, v83, v83
	v_fmac_f32_e32 v160, v90, v90
	v_fmac_f32_e32 v159, v91, v91
	v_fmac_f32_e32 v158, v136, v136
	v_add_f32_e32 v46, v50, v141
	v_add_f32_e32 v47, v51, v113
	v_add_f32_e32 v41, v45, v129
	v_add_f32_e32 v36, v40, v111
	v_and_b32_e32 v87, 0xffff0000, v33
	v_add_f32_e32 v33, v37, v86
	v_and_b32_e32 v93, 0xffff0000, v34
	v_add_f32_e32 v34, v38, v92
	v_and_b32_e32 v105, 0xffff0000, v35
	v_add_f32_e32 v35, v39, v104
	v_and_b32_e32 v103, 0xffff0000, v28
	v_add_f32_e32 v28, v32, v102
	v_lshlrev_b32_e32 v194, 16, v29
	v_lshlrev_b32_e32 v32, 16, v30
	v_lshlrev_b32_e32 v244, 16, v31
	v_fmac_f32_e32 v53, v99, v99
	v_fmac_f32_e32 v165, v100, v100
	v_fmac_f32_e32 v164, v101, v101
	v_fmac_f32_e32 v163, v114, v114
	v_fmac_f32_e32 v161, v115, v115
	v_fmac_f32_e32 v160, v126, v126
	v_fmac_f32_e32 v159, v127, v127
	v_fmac_f32_e32 v158, v118, v118
	v_add_f32_e32 v42, v46, v97
	v_add_f32_e32 v43, v47, v109
	v_add_f32_e32 v37, v41, v87
	v_add_f32_e32 v36, v36, v103
	v_and_b32_e32 v195, 0xffff0000, v29
	v_add_f32_e32 v29, v33, v194
	v_and_b32_e32 v33, 0xffff0000, v30
	v_add_f32_e32 v30, v34, v32
	v_and_b32_e32 v245, 0xffff0000, v31
	v_add_f32_e32 v31, v35, v244
	s_waitcnt vmcnt(6)
	v_lshlrev_b32_e32 v34, 16, v24
	v_and_b32_e32 v35, 0xffff0000, v24
	v_fmac_f32_e32 v53, v137, v137
	v_fmac_f32_e32 v165, v130, v130
	v_fmac_f32_e32 v164, v131, v131
	v_fmac_f32_e32 v163, v138, v138
	v_fmac_f32_e32 v161, v139, v139
	v_fmac_f32_e32 v160, v144, v144
	v_fmac_f32_e32 v159, v145, v145
	v_fmac_f32_e32 v158, v112, v112
	v_add_f32_e32 v38, v42, v93
	v_add_f32_e32 v39, v43, v105
	v_add_f32_e32 v40, v37, v195
	v_add_f32_e32 v24, v28, v34
	v_add_f32_e32 v28, v36, v35
	v_lshlrev_b32_e32 v36, 16, v25
	v_and_b32_e32 v37, 0xffff0000, v25
	v_fmac_f32_e32 v53, v119, v119
	v_fmac_f32_e32 v165, v120, v120
	v_fmac_f32_e32 v164, v121, v121
	v_fmac_f32_e32 v163, v132, v132
	v_fmac_f32_e32 v161, v133, v133
	v_fmac_f32_e32 v160, v140, v140
	v_fmac_f32_e32 v159, v141, v141
	v_fmac_f32_e32 v158, v108, v108
	v_add_f32_e32 v41, v38, v33
	v_add_f32_e32 v42, v39, v245
	v_add_f32_e32 v25, v29, v36
	v_add_f32_e32 v29, v40, v37
	v_lshlrev_b32_e32 v38, 16, v26
	v_and_b32_e32 v39, 0xffff0000, v26
	v_lshlrev_b32_e32 v40, 16, v27
	v_fmac_f32_e32 v53, v113, v113
	v_fmac_f32_e32 v165, v116, v116
	v_fmac_f32_e32 v164, v117, v117
	v_fmac_f32_e32 v163, v128, v128
	v_fmac_f32_e32 v161, v129, v129
	v_fmac_f32_e32 v160, v96, v96
	v_fmac_f32_e32 v159, v97, v97
	v_fmac_f32_e32 v158, v104, v104
	v_add_f32_e32 v26, v30, v38
	v_add_f32_e32 v30, v41, v39
	v_and_b32_e32 v41, 0xffff0000, v27
	v_add_f32_e32 v27, v31, v40
	s_waitcnt vmcnt(5)
	v_lshlrev_b32_e32 v48, 16, v23
	v_fmac_f32_e32 v53, v109, v109
	v_fmac_f32_e32 v165, v110, v110
	v_fmac_f32_e32 v164, v111, v111
	v_fmac_f32_e32 v163, v86, v86
	v_fmac_f32_e32 v161, v87, v87
	v_fmac_f32_e32 v160, v92, v92
	v_fmac_f32_e32 v159, v93, v93
	v_fmac_f32_e32 v158, v244, v244
	v_add_f32_e32 v31, v42, v41
	v_lshlrev_b32_e32 v42, 16, v20
	v_and_b32_e32 v43, 0xffff0000, v20
	v_lshlrev_b32_e32 v44, 16, v21
	v_and_b32_e32 v45, 0xffff0000, v21
	v_lshlrev_b32_e32 v46, 16, v22
	v_and_b32_e32 v47, 0xffff0000, v22
	v_and_b32_e32 v49, 0xffff0000, v23
	v_add_f32_e32 v23, v27, v48
	s_waitcnt vmcnt(4)
; __device__ __forceinline__ float bflo(unsigned w) { return __uint_as_float(w << 16); }
; __device__ __forceinline__ float bfhi(unsigned w) { return __uint_as_float(w & 0xffff0000u); }
; __device__ __forceinline__ void a_unit(Frame& F, int L, int u, bool dry) {
;     ...
;         for (int i = 0; i < 16; ++i)
; #pragma unroll
;             for (int jj = 0; jj < 4; ++jj) { const float lo = bflo(raw[i][jj]), hi = bfhi(raw[i][jj]); s[2 * jj] += lo; q[2 * jj] = fmaf(lo, lo, q[2 * jj]); s[2 * jj + 1] += hi; q[2 * jj + 1] = fmaf(hi, hi, q[2 * jj + 1]); }
	v_lshlrev_b32_e32 v76, 16, v19
	v_fmac_f32_e32 v53, v105, v105
	v_fmac_f32_e32 v165, v102, v102
	v_fmac_f32_e32 v164, v103, v103
	v_fmac_f32_e32 v163, v194, v194
	v_fmac_f32_e32 v161, v195, v195
	v_fmac_f32_e32 v160, v32, v32
	v_fmac_f32_e32 v159, v33, v33
	v_fmac_f32_e32 v158, v40, v40
	v_add_f32_e32 v20, v24, v42
	v_add_f32_e32 v24, v28, v43
	v_add_f32_e32 v21, v25, v44
	v_add_f32_e32 v25, v29, v45
	v_add_f32_e32 v22, v26, v46
	v_add_f32_e32 v26, v30, v47
	v_lshlrev_b32_e32 v50, 16, v16
	v_and_b32_e32 v51, 0xffff0000, v16
	v_lshlrev_b32_e32 v62, 16, v17
	v_and_b32_e32 v63, 0xffff0000, v17
	v_lshlrev_b32_e32 v70, 16, v18
	v_and_b32_e32 v71, 0xffff0000, v18
	v_and_b32_e32 v77, 0xffff0000, v19
	v_add_f32_e32 v19, v23, v76
	s_waitcnt vmcnt(3)
	v_lshlrev_b32_e32 v84, 16, v15
	v_fmac_f32_e32 v53, v245, v245
	v_fmac_f32_e32 v165, v34, v34
	v_fmac_f32_e32 v164, v35, v35
	v_fmac_f32_e32 v163, v36, v36
	v_fmac_f32_e32 v161, v37, v37
	v_fmac_f32_e32 v160, v38, v38
	v_fmac_f32_e32 v159, v39, v39
	v_fmac_f32_e32 v158, v48, v48
	v_add_f32_e32 v27, v31, v49
	v_add_f32_e32 v16, v20, v50
	v_add_f32_e32 v20, v24, v51
	v_add_f32_e32 v17, v21, v62
	v_add_f32_e32 v21, v25, v63
	v_add_f32_e32 v18, v22, v70
	v_add_f32_e32 v22, v26, v71
	v_lshlrev_b32_e32 v66, 16, v12
	v_and_b32_e32 v67, 0xffff0000, v12
	v_lshlrev_b32_e32 v72, 16, v13
	v_and_b32_e32 v73, 0xffff0000, v13
	v_lshlrev_b32_e32 v80, 16, v14
	v_and_b32_e32 v81, 0xffff0000, v14
	v_and_b32_e32 v85, 0xffff0000, v15
	v_add_f32_e32 v15, v19, v84
	s_waitcnt vmcnt(2)
	v_lshlrev_b32_e32 v122, 16, v11
	v_fmac_f32_e32 v53, v41, v41
	v_fmac_f32_e32 v165, v42, v42
	v_fmac_f32_e32 v164, v43, v43
	v_fmac_f32_e32 v163, v44, v44
	v_fmac_f32_e32 v161, v45, v45
	v_fmac_f32_e32 v160, v46, v46
	v_fmac_f32_e32 v159, v47, v47
	v_fmac_f32_e32 v158, v76, v76
	v_add_f32_e32 v23, v27, v77
	v_add_f32_e32 v12, v16, v66
	v_add_f32_e32 v16, v20, v67
	v_add_f32_e32 v13, v17, v72
	v_add_f32_e32 v17, v21, v73
	v_add_f32_e32 v14, v18, v80
	v_add_f32_e32 v18, v22, v81
	v_lshlrev_b32_e32 v88, 16, v8
	v_and_b32_e32 v89, 0xffff0000, v8
	v_lshlrev_b32_e32 v94, 16, v9
	v_and_b32_e32 v95, 0xffff0000, v9
	v_lshlrev_b32_e32 v106, 16, v10
	v_and_b32_e32 v107, 0xffff0000, v10
	v_and_b32_e32 v123, 0xffff0000, v11
	v_add_f32_e32 v11, v15, v122
	s_waitcnt vmcnt(1)
	v_lshlrev_b32_e32 v146, 16, v7
	v_fmac_f32_e32 v53, v49, v49
	v_fmac_f32_e32 v165, v50, v50
	v_fmac_f32_e32 v164, v51, v51
	v_fmac_f32_e32 v163, v62, v62
	v_fmac_f32_e32 v161, v63, v63
	v_fmac_f32_e32 v160, v70, v70
	v_fmac_f32_e32 v159, v71, v71
	v_fmac_f32_e32 v158, v84, v84
	v_add_f32_e32 v19, v23, v85
	v_add_f32_e32 v8, v12, v88
	v_add_f32_e32 v12, v16, v89
	v_add_f32_e32 v9, v13, v94
	v_add_f32_e32 v13, v17, v95
	v_add_f32_e32 v10, v14, v106
	v_add_f32_e32 v14, v18, v107
	v_lshlrev_b32_e32 v124, 16, v4
	v_and_b32_e32 v125, 0xffff0000, v4
	v_lshlrev_b32_e32 v134, 16, v5
	v_and_b32_e32 v135, 0xffff0000, v5
	v_lshlrev_b32_e32 v142, 16, v6
	v_and_b32_e32 v143, 0xffff0000, v6
	v_and_b32_e32 v147, 0xffff0000, v7
	v_add_f32_e32 v7, v11, v146
	s_waitcnt vmcnt(0)
; #define LAS __attribute__((address_space(3)))
; __device__ __forceinline__ float xsum16(float v) { float a = v, b = v; asm("s_nop 1\n\tv_permlane16_swap_b32 %0, %1" : "+v"(a), "+v"(b)); return a + b; }
; __device__ __forceinline__ float xsum32(float v) { float a = v, b = v; asm("s_nop 1\n\tv_permlane32_swap_b32 %0, %1" : "+v"(a), "+v"(b)); return a + b; }
; __device__ __forceinline__ float bflo(unsigned w) { return __uint_as_float(w << 16); }
; __device__ __forceinline__ float bfhi(unsigned w) { return __uint_as_float(w & 0xffff0000u); }
; __device__ __forceinline__ void a_unit(Frame& F, int L, int u, bool dry) {
;     ...
;             for (int jj = 0; jj < 4; ++jj) { const float lo = bflo(raw[i][jj]), hi = bfhi(raw[i][jj]); s[2 * jj] += lo; q[2 * jj] = fmaf(lo, lo, q[2 * jj]); s[2 * jj + 1] += hi; q[2 * jj + 1] = fmaf(hi, hi, q[2 * jj + 1]); }
;     }
; #pragma unroll
;     for (int j = 0; j < 8; ++j) { s[j] = xsum32(xsum16(s[j])); q[j] = xsum32(xsum16(q[j])); }
;     if (cr == 0) {
; #pragma unroll
;         for (int j = 0; j < 8; ++j) *(LAS f32x2*)(part + (w * 128 + 8 * tg + j) * 2) = (f32x2){s[j], q[j]};
;     }
	v_lshlrev_b32_e32 v154, 16, v3
	v_fmac_f32_e32 v53, v77, v77
	v_fmac_f32_e32 v165, v66, v66
	v_fmac_f32_e32 v164, v67, v67
	v_fmac_f32_e32 v163, v72, v72
	v_fmac_f32_e32 v161, v73, v73
	v_fmac_f32_e32 v160, v80, v80
	v_fmac_f32_e32 v159, v81, v81
	v_fmac_f32_e32 v158, v122, v122
	v_add_f32_e32 v15, v19, v123
	v_add_f32_e32 v4, v8, v124
	v_add_f32_e32 v8, v12, v125
	v_add_f32_e32 v5, v9, v134
	v_add_f32_e32 v9, v13, v135
	v_add_f32_e32 v6, v10, v142
	v_add_f32_e32 v10, v14, v143
	v_lshlrev_b32_e32 v148, 16, v0
	v_and_b32_e32 v149, 0xffff0000, v0
	v_lshlrev_b32_e32 v150, 16, v1
	v_and_b32_e32 v151, 0xffff0000, v1
	v_lshlrev_b32_e32 v152, 16, v2
	v_and_b32_e32 v153, 0xffff0000, v2
	v_add_f32_e32 v24, v7, v154
	v_fmac_f32_e32 v53, v85, v85
	v_fmac_f32_e32 v165, v88, v88
	v_fmac_f32_e32 v164, v89, v89
	v_fmac_f32_e32 v163, v94, v94
	v_fmac_f32_e32 v161, v95, v95
	v_fmac_f32_e32 v160, v106, v106
	v_fmac_f32_e32 v159, v107, v107
	v_fmac_f32_e32 v158, v146, v146
	v_add_f32_e32 v11, v15, v147
	v_add_f32_e32 v0, v4, v148
	v_add_f32_e32 v4, v8, v149
	v_add_f32_e32 v8, v5, v150
	v_add_f32_e32 v12, v9, v151
	v_add_f32_e32 v16, v6, v152
	v_add_f32_e32 v20, v10, v153
	v_and_b32_e32 v155, 0xffff0000, v3
	v_mov_b32_e32 v25, v24
	v_fmac_f32_e32 v53, v123, v123
	v_fmac_f32_e32 v165, v124, v124
	v_fmac_f32_e32 v164, v125, v125
	v_fmac_f32_e32 v163, v134, v134
	v_fmac_f32_e32 v161, v135, v135
	v_fmac_f32_e32 v160, v142, v142
	v_fmac_f32_e32 v159, v143, v143
	v_fmac_f32_e32 v158, v154, v154
	v_add_f32_e32 v28, v11, v155
	v_mov_b32_e32 v1, v0
	v_mov_b32_e32 v5, v4
	v_mov_b32_e32 v9, v8
	v_mov_b32_e32 v13, v12
	v_mov_b32_e32 v17, v16
	v_mov_b32_e32 v21, v20
	s_nop 1
	v_permlane16_swap_b32 v24, v25
	v_fmac_f32_e32 v53, v147, v147
	v_fmac_f32_e32 v165, v148, v148
	v_fmac_f32_e32 v164, v149, v149
	v_fmac_f32_e32 v163, v150, v150
	v_fmac_f32_e32 v161, v151, v151
	v_fmac_f32_e32 v160, v152, v152
	v_fmac_f32_e32 v159, v153, v153
	s_nop 1
	v_permlane16_swap_b32 v0, v1
	s_nop 1
	v_permlane16_swap_b32 v4, v5
	s_nop 1
	v_permlane16_swap_b32 v8, v9
	s_nop 1
	v_permlane16_swap_b32 v12, v13
	s_nop 1
	v_permlane16_swap_b32 v16, v17
	s_nop 1
	v_permlane16_swap_b32 v20, v21
	v_add_f32_e32 v24, v24, v25
	v_mov_b32_e32 v25, v158
	v_mov_b32_e32 v29, v28
	v_fmac_f32_e32 v53, v155, v155
	v_add_f32_e32 v0, v0, v1
	v_mov_b32_e32 v1, v165
	v_add_f32_e32 v4, v4, v5
	v_mov_b32_e32 v5, v164
	v_add_f32_e32 v8, v8, v9
	v_mov_b32_e32 v9, v163
	v_add_f32_e32 v12, v12, v13
	v_mov_b32_e32 v13, v161
	v_add_f32_e32 v16, v16, v17
	v_mov_b32_e32 v17, v160
	v_add_f32_e32 v20, v20, v21
	v_mov_b32_e32 v21, v159
	s_nop 1
	v_permlane16_swap_b32 v158, v25
	s_nop 1
	v_permlane16_swap_b32 v28, v29
	s_nop 1
	v_permlane16_swap_b32 v165, v1
	s_nop 1
	v_permlane16_swap_b32 v164, v5
	s_nop 1
	v_permlane16_swap_b32 v163, v9
	s_nop 1
	v_permlane16_swap_b32 v161, v13
	s_nop 1
	v_permlane16_swap_b32 v160, v17
	s_nop 1
	v_permlane16_swap_b32 v159, v21
	s_nop 0
	v_add_f32_e32 v25, v158, v25
	v_add_f32_e32 v158, v28, v29
	v_mov_b32_e32 v28, v53
	v_add_f32_e32 v1, v165, v1
	v_add_f32_e32 v5, v164, v5
	v_add_f32_e32 v9, v163, v9
	v_add_f32_e32 v13, v161, v13
	v_add_f32_e32 v17, v160, v17
	v_add_f32_e32 v21, v159, v21
	s_nop 1
	v_permlane16_swap_b32 v53, v28
	v_mov_b32_e32 v2, v0
	v_add_f32_e32 v159, v53, v28
	v_mov_b32_e32 v3, v1
	v_mov_b32_e32 v6, v4
	v_mov_b32_e32 v7, v5
	v_mov_b32_e32 v10, v8
	v_mov_b32_e32 v11, v9
	v_mov_b32_e32 v14, v12
	v_mov_b32_e32 v15, v13
	v_mov_b32_e32 v18, v16
	v_mov_b32_e32 v19, v17
	v_mov_b32_e32 v22, v20
	v_mov_b32_e32 v23, v21
	v_mov_b32_e32 v26, v24
	v_mov_b32_e32 v27, v25
	v_mov_b32_e32 v160, v158
	v_mov_b32_e32 v161, v159
	s_nop 1
	v_permlane32_swap_b32 v0, v2
	s_nop 1
	v_permlane32_swap_b32 v1, v3
	s_nop 1
	v_permlane32_swap_b32 v4, v6
	s_nop 1
	v_permlane32_swap_b32 v5, v7
	s_nop 1
	v_permlane32_swap_b32 v8, v10
	s_nop 1
	v_permlane32_swap_b32 v9, v11
	s_nop 1
	v_permlane32_swap_b32 v12, v14
	s_nop 1
	v_permlane32_swap_b32 v13, v15
	s_nop 1
	v_permlane32_swap_b32 v16, v18
	s_nop 1
	v_permlane32_swap_b32 v17, v19
	s_nop 1
	v_permlane32_swap_b32 v20, v22
	s_nop 1
	v_permlane32_swap_b32 v21, v23
	s_nop 1
	v_permlane32_swap_b32 v24, v26
	s_nop 1
	v_permlane32_swap_b32 v25, v27
	s_nop 1
	v_permlane32_swap_b32 v158, v160
	s_nop 1
	v_permlane32_swap_b32 v159, v161
	s_and_saveexec_b64 s[0:1], vcc
	s_cbranch_execz .LBB0_471
	v_lshlrev_b32_e32 v28, 3, v190
	v_readlane_b32 s2, v253, 59
	v_pk_add_f32 v[2:3], v[0:1], v[2:3]
	v_pk_add_f32 v[4:5], v[4:5], v[6:7]
	v_or_b32_e32 v0, s2, v28
	v_lshl_add_u32 v0, v0, 3, 0
	v_add_u32_e32 v0, 0x22000, v0
	v_pk_add_f32 v[160:161], v[158:159], v[160:161]
	v_pk_add_f32 v[158:159], v[24:25], v[26:27]
	v_pk_add_f32 v[20:21], v[20:21], v[22:23]
	v_pk_add_f32 v[18:19], v[16:17], v[18:19]
	v_pk_add_f32 v[12:13], v[12:13], v[14:15]
	v_pk_add_f32 v[10:11], v[8:9], v[10:11]
	ds_write_b128 v0, v[2:5]
	ds_write_b128 v0, v[10:13] offset:16
	ds_write_b128 v0, v[18:21] offset:32
	ds_write_b128 v0, v[158:161] offset:48
